# k18 + attention causal-mask block skipped per wave when the key tile is fully visible + K-loop DMA address sums (SGPR base + SGPR step) done on the SALU instead of two 64-bit VALU adds per DMA
# speedup vs baseline: 1.0024x; 1.0024x over previous
.LBB0_444:
	s_add_u32 s48, s46, 0x20080
	s_addc_u32 s49, s47, 0
	s_add_u32 s25, s50, 0x100
	s_addc_u32 s64, s51, 0
	s_mov_b32 s65, -2
	s_add_u32 s46, s48, 0xfffe0080
	s_addc_u32 s47, s49, -1
	s_add_i32 s84, 0, 0x10000
	s_cmp_eq_u32 s65, 4
	s_cselect_b32 s47, s15, s47
	s_cselect_b32 s46, s14, s46
	v_add_u32_e32 v0, s84, v147
	s_cselect_b32 s51, s17, s64
	s_cselect_b32 s50, s16, s25
	s_add_i32 s86, 0, 0x14000
	ds_read_b128 v[150:153], v0
	ds_read_b128 v[154:157], v0 offset:1024
	ds_read_b128 v[158:161], v0 offset:2048
	ds_read_b128 v[162:165], v0 offset:3072
	v_add_u32_e32 v0, s86, v147
	ds_read_b128 v[166:169], v0
	ds_read_b128 v[170:173], v0 offset:1024
	ds_read_b128 v[174:177], v0 offset:2048
	ds_read_b128 v[178:181], v0 offset:3072
	v_mov_b32_e32 v0, v132
	ds_read_b128 v[182:185], v148
	ds_read_b128 v[186:189], v148 offset:1024
	ds_read_b128 v[190:193], v148 offset:2048
	ds_read_b128 v[194:197], v148 offset:3072
	ds_read_b128 v[198:201], v148 offset:4096
	ds_read_b128 v[202:205], v148 offset:5120
	ds_read_b128 v[206:209], v148 offset:6144
	ds_read_b128 v[210:213], v148 offset:7168
	s_add_i32 m0, s59, 0xc000
	s_nop 0
	global_load_lds_dwordx4 v0, s[48:49]
	v_mov_b32_e32 v0, v133
	s_add_i32 m0, s59, 0xe000
	s_nop 0
	global_load_lds_dwordx4 v0, s[48:49]
	s_waitcnt vmcnt(8)
	s_waitcnt lgkmcnt(0)
	s_barrier
	s_setprio 1
	s_waitcnt lgkmcnt(0)
	v_mfma_i32_16x16x64_i8 v[126:129], v[150:153], v[182:185], 0
	v_mfma_i32_16x16x64_i8 v[122:125], v[158:161], v[182:185], 0
	v_mfma_i32_16x16x64_i8 v[110:113], v[150:153], v[190:193], 0
	v_mfma_i32_16x16x64_i8 v[106:109], v[158:161], v[190:193], 0
	v_mfma_i32_16x16x64_i8 v[94:97], v[150:153], v[198:201], 0
	v_mfma_i32_16x16x64_i8 v[90:93], v[158:161], v[198:201], 0
	v_mfma_i32_16x16x64_i8 v[78:81], v[150:153], v[206:209], 0
	v_mfma_i32_16x16x64_i8 v[74:77], v[158:161], v[206:209], 0
	v_mfma_i32_16x16x64_i8 v[126:129], v[154:157], v[186:189], v[126:129]
	v_mfma_i32_16x16x64_i8 v[122:125], v[162:165], v[186:189], v[122:125]
	v_mfma_i32_16x16x64_i8 v[110:113], v[154:157], v[194:197], v[110:113]
	v_mfma_i32_16x16x64_i8 v[106:109], v[162:165], v[194:197], v[106:109]
	v_mfma_i32_16x16x64_i8 v[94:97], v[154:157], v[202:205], v[94:97]
	v_mfma_i32_16x16x64_i8 v[90:93], v[162:165], v[202:205], v[90:93]
	v_mfma_i32_16x16x64_i8 v[78:81], v[154:157], v[210:213], v[78:81]
	v_mfma_i32_16x16x64_i8 v[74:77], v[162:165], v[210:213], v[74:77]
	s_setprio 0
	s_setprio 1
	v_mfma_i32_16x16x64_i8 v[118:121], v[166:169], v[182:185], 0
	v_mfma_i32_16x16x64_i8 v[114:117], v[174:177], v[182:185], 0
	v_mfma_i32_16x16x64_i8 v[102:105], v[166:169], v[190:193], 0
	v_mfma_i32_16x16x64_i8 v[98:101], v[174:177], v[190:193], 0
	v_mfma_i32_16x16x64_i8 v[86:89], v[166:169], v[198:201], 0
	v_mfma_i32_16x16x64_i8 v[82:85], v[174:177], v[198:201], 0
	v_mfma_i32_16x16x64_i8 v[70:73], v[166:169], v[206:209], 0
	v_mfma_i32_16x16x64_i8 v[66:69], v[174:177], v[206:209], 0
	v_mfma_i32_16x16x64_i8 v[118:121], v[170:173], v[186:189], v[118:121]
	v_mfma_i32_16x16x64_i8 v[114:117], v[178:181], v[186:189], v[114:117]
	v_mfma_i32_16x16x64_i8 v[102:105], v[170:173], v[194:197], v[102:105]
	v_mfma_i32_16x16x64_i8 v[98:101], v[178:181], v[194:197], v[98:101]
	v_mfma_i32_16x16x64_i8 v[86:89], v[170:173], v[202:205], v[86:89]
	v_mfma_i32_16x16x64_i8 v[82:85], v[178:181], v[202:205], v[82:85]
	v_mfma_i32_16x16x64_i8 v[70:73], v[170:173], v[210:213], v[70:73]
	v_mfma_i32_16x16x64_i8 v[66:69], v[178:181], v[210:213], v[66:69]
	s_setprio 0
	s_barrier
	v_mov_b32_e32 v0, v143
	s_add_i32 s84, s84, s40
	ds_read_b128 v[182:185], v148 offset:16384
	ds_read_b128 v[186:189], v148 offset:17408
	ds_read_b128 v[190:193], v148 offset:18432
	ds_read_b128 v[194:197], v148 offset:19456
	ds_read_b128 v[198:201], v148 offset:20480
	ds_read_b128 v[202:205], v148 offset:21504
	ds_read_b128 v[206:209], v148 offset:22528
	ds_read_b128 v[210:213], v148 offset:23552
	s_mov_b32 m0, s84
	s_nop 0
	global_load_lds_dwordx4 v0, s[50:51]
	v_mov_b32_e32 v0, v144
	s_add_i32 m0, s84, 0x2000
	s_add_u32 s84, s50, 0x20000
	global_load_lds_dwordx4 v0, s[50:51]
	s_addc_u32 s85, s51, 0
	v_mov_b32_e32 v0, v143
	s_add_i32 s86, s86, s40
	s_mov_b32 m0, s86
	s_nop 0
	global_load_lds_dwordx4 v0, s[84:85]
	v_mov_b32_e32 v0, v144
	s_add_i32 m0, s86, 0x2000
	s_nop 0
	global_load_lds_dwordx4 v0, s[84:85]
	v_mov_b32_e32 v0, v132
	s_mov_b32 m0, s59
	s_nop 0
	global_load_lds_dwordx4 v0, s[46:47]
	v_mov_b32_e32 v0, v133
	s_mov_b32 m0, s60
	s_nop 0
	global_load_lds_dwordx4 v0, s[46:47]
	s_waitcnt vmcnt(8)
	s_waitcnt lgkmcnt(0)
	s_barrier
	s_setprio 1
	s_waitcnt lgkmcnt(0)
	v_mfma_i32_16x16x64_i8 v[62:65], v[150:153], v[182:185], 0
	v_mfma_i32_16x16x64_i8 v[58:61], v[158:161], v[182:185], 0
	v_mfma_i32_16x16x64_i8 v[46:49], v[150:153], v[190:193], 0
	v_mfma_i32_16x16x64_i8 v[42:45], v[158:161], v[190:193], 0
	v_mfma_i32_16x16x64_i8 v[30:33], v[150:153], v[198:201], 0
	v_mfma_i32_16x16x64_i8 v[26:29], v[158:161], v[198:201], 0
	v_mfma_i32_16x16x64_i8 v[14:17], v[150:153], v[206:209], 0
	v_mfma_i32_16x16x64_i8 v[10:13], v[158:161], v[206:209], 0
	v_mfma_i32_16x16x64_i8 v[62:65], v[154:157], v[186:189], v[62:65]
	v_mfma_i32_16x16x64_i8 v[58:61], v[162:165], v[186:189], v[58:61]
	v_mfma_i32_16x16x64_i8 v[46:49], v[154:157], v[194:197], v[46:49]
	v_mfma_i32_16x16x64_i8 v[42:45], v[162:165], v[194:197], v[42:45]
	v_mfma_i32_16x16x64_i8 v[30:33], v[154:157], v[202:205], v[30:33]
	v_mfma_i32_16x16x64_i8 v[26:29], v[162:165], v[202:205], v[26:29]
	v_mfma_i32_16x16x64_i8 v[14:17], v[154:157], v[210:213], v[14:17]
	v_mfma_i32_16x16x64_i8 v[10:13], v[162:165], v[210:213], v[10:13]
	s_setprio 0
	s_setprio 1
	v_mfma_i32_16x16x64_i8 v[54:57], v[166:169], v[182:185], 0
	v_mfma_i32_16x16x64_i8 v[50:53], v[174:177], v[182:185], 0
	v_mfma_i32_16x16x64_i8 v[38:41], v[166:169], v[190:193], 0
	v_mfma_i32_16x16x64_i8 v[34:37], v[174:177], v[190:193], 0
	v_mfma_i32_16x16x64_i8 v[22:25], v[166:169], v[198:201], 0
	v_mfma_i32_16x16x64_i8 v[18:21], v[174:177], v[198:201], 0
	v_mfma_i32_16x16x64_i8 v[6:9], v[166:169], v[206:209], 0
	v_mfma_i32_16x16x64_i8 v[2:5], v[174:177], v[206:209], 0
	v_mfma_i32_16x16x64_i8 v[54:57], v[170:173], v[186:189], v[54:57]
	v_mfma_i32_16x16x64_i8 v[50:53], v[178:181], v[186:189], v[50:53]
	v_mfma_i32_16x16x64_i8 v[38:41], v[170:173], v[194:197], v[38:41]
	v_mfma_i32_16x16x64_i8 v[34:37], v[178:181], v[194:197], v[34:37]
	v_mfma_i32_16x16x64_i8 v[22:25], v[170:173], v[202:205], v[22:25]
	v_mfma_i32_16x16x64_i8 v[18:21], v[178:181], v[202:205], v[18:21]
	v_mfma_i32_16x16x64_i8 v[6:9], v[170:173], v[210:213], v[6:9]
	v_mfma_i32_16x16x64_i8 v[2:5], v[178:181], v[210:213], v[2:5]
	s_setprio 0
	s_barrier
	s_add_i32 s86, 0, 0x18000
	v_add_u32_e32 v0, s86, v147
	s_add_i32 s87, 0, 0x1c000
	ds_read_b128 v[150:153], v0
	ds_read_b128 v[154:157], v0 offset:1024
	ds_read_b128 v[158:161], v0 offset:2048
	ds_read_b128 v[162:165], v0 offset:3072
	v_add_u32_e32 v0, s87, v147
	ds_read_b128 v[166:169], v0
	ds_read_b128 v[170:173], v0 offset:1024
	ds_read_b128 v[174:177], v0 offset:2048
	ds_read_b128 v[178:181], v0 offset:3072
	s_add_u32 s84, s46, 0x20000
	v_mov_b32_e32 v0, v132
	s_mov_b32 m0, s61
	ds_read_b128 v[182:185], v148 offset:32768
	ds_read_b128 v[186:189], v148 offset:33792
	ds_read_b128 v[190:193], v148 offset:34816
	ds_read_b128 v[194:197], v148 offset:35840
	ds_read_b128 v[198:201], v148 offset:36864
	ds_read_b128 v[202:205], v148 offset:37888
	ds_read_b128 v[206:209], v148 offset:38912
	ds_read_b128 v[210:213], v148 offset:39936
	s_addc_u32 s85, s47, 0
	s_nop 0
	global_load_lds_dwordx4 v0, s[84:85]
	v_mov_b32_e32 v0, v133
	s_mov_b32 m0, s66
	s_nop 0
	global_load_lds_dwordx4 v0, s[84:85]
	s_waitcnt vmcnt(8)
	s_waitcnt lgkmcnt(0)
	s_barrier
	s_setprio 1
	s_waitcnt lgkmcnt(0)
	v_mfma_i32_16x16x64_i8 v[126:129], v[150:153], v[182:185], v[126:129]
	v_mfma_i32_16x16x64_i8 v[122:125], v[158:161], v[182:185], v[122:125]
	v_mfma_i32_16x16x64_i8 v[110:113], v[150:153], v[190:193], v[110:113]
	v_mfma_i32_16x16x64_i8 v[106:109], v[158:161], v[190:193], v[106:109]
	v_mfma_i32_16x16x64_i8 v[94:97], v[150:153], v[198:201], v[94:97]
	v_mfma_i32_16x16x64_i8 v[90:93], v[158:161], v[198:201], v[90:93]
	v_mfma_i32_16x16x64_i8 v[78:81], v[150:153], v[206:209], v[78:81]
	v_mfma_i32_16x16x64_i8 v[74:77], v[158:161], v[206:209], v[74:77]
	v_mfma_i32_16x16x64_i8 v[126:129], v[154:157], v[186:189], v[126:129]
	v_mfma_i32_16x16x64_i8 v[122:125], v[162:165], v[186:189], v[122:125]
	v_mfma_i32_16x16x64_i8 v[110:113], v[154:157], v[194:197], v[110:113]
	v_mfma_i32_16x16x64_i8 v[106:109], v[162:165], v[194:197], v[106:109]
	v_mfma_i32_16x16x64_i8 v[94:97], v[154:157], v[202:205], v[94:97]
	v_mfma_i32_16x16x64_i8 v[90:93], v[162:165], v[202:205], v[90:93]
	v_mfma_i32_16x16x64_i8 v[78:81], v[154:157], v[210:213], v[78:81]
	v_mfma_i32_16x16x64_i8 v[74:77], v[162:165], v[210:213], v[74:77]
	s_setprio 0
	s_setprio 1
	v_mfma_i32_16x16x64_i8 v[118:121], v[166:169], v[182:185], v[118:121]
	v_mfma_i32_16x16x64_i8 v[114:117], v[174:177], v[182:185], v[114:117]
	v_mfma_i32_16x16x64_i8 v[102:105], v[166:169], v[190:193], v[102:105]
	v_mfma_i32_16x16x64_i8 v[98:101], v[174:177], v[190:193], v[98:101]
	v_mfma_i32_16x16x64_i8 v[86:89], v[166:169], v[198:201], v[86:89]
	v_mfma_i32_16x16x64_i8 v[82:85], v[174:177], v[198:201], v[82:85]
	v_mfma_i32_16x16x64_i8 v[70:73], v[166:169], v[206:209], v[70:73]
	v_mfma_i32_16x16x64_i8 v[66:69], v[174:177], v[206:209], v[66:69]
	v_mfma_i32_16x16x64_i8 v[118:121], v[170:173], v[186:189], v[118:121]
	v_mfma_i32_16x16x64_i8 v[114:117], v[178:181], v[186:189], v[114:117]
	v_mfma_i32_16x16x64_i8 v[102:105], v[170:173], v[194:197], v[102:105]
	v_mfma_i32_16x16x64_i8 v[98:101], v[178:181], v[194:197], v[98:101]
	v_mfma_i32_16x16x64_i8 v[86:89], v[170:173], v[202:205], v[86:89]
	v_mfma_i32_16x16x64_i8 v[82:85], v[178:181], v[202:205], v[82:85]
	v_mfma_i32_16x16x64_i8 v[70:73], v[170:173], v[210:213], v[70:73]
	v_mfma_i32_16x16x64_i8 v[66:69], v[178:181], v[210:213], v[66:69]
	s_setprio 0
	s_barrier
	v_mov_b32_e32 v0, v143
	ds_read_b128 v[182:185], v148 offset:49152
	ds_read_b128 v[186:189], v148 offset:50176
	ds_read_b128 v[190:193], v148 offset:51200
	ds_read_b128 v[194:197], v148 offset:52224
	ds_read_b128 v[198:201], v148 offset:53248
	ds_read_b128 v[202:205], v148 offset:54272
	ds_read_b128 v[206:209], v148 offset:55296
	ds_read_b128 v[210:213], v148 offset:56320
	s_add_i32 s84, s86, s40
	s_add_u32 s100, s50, s38
	s_addc_u32 s101, s51, s39
	s_mov_b32 m0, s84
	v_mov_b32_e32 v0, v144
	global_load_lds_dwordx4 v143, s[100:101]
	s_add_i32 m0, s84, 0x2000
	s_nop 0
	s_add_u32 s50, s50, 0x20080
	s_addc_u32 s51, s51, 0
	v_mov_b32_e32 v0, v143
	s_add_i32 s84, s87, s40
	global_load_lds_dwordx4 v144, s[100:101]
	s_mov_b32 m0, s84
	s_nop 0
	global_load_lds_dwordx4 v0, s[50:51]
	v_mov_b32_e32 v0, v144
	s_add_i32 m0, s84, 0x2000
	s_nop 0
	global_load_lds_dwordx4 v0, s[50:51]
	v_mov_b32_e32 v0, v132
	s_mov_b32 m0, s75
	s_add_u32 s100, s46, s38
	s_addc_u32 s101, s47, s39
	v_mov_b32_e32 v0, v133
	global_load_lds_dwordx4 v132, s[100:101]
	s_mov_b32 m0, s78
	s_nop 0
	global_load_lds_dwordx4 v133, s[100:101]
	s_waitcnt vmcnt(8)
	s_waitcnt lgkmcnt(0)
	s_barrier
	s_setprio 1
	s_waitcnt lgkmcnt(0)
	v_mfma_i32_16x16x64_i8 v[62:65], v[150:153], v[182:185], v[62:65]
	v_mfma_i32_16x16x64_i8 v[58:61], v[158:161], v[182:185], v[58:61]
	v_mfma_i32_16x16x64_i8 v[46:49], v[150:153], v[190:193], v[46:49]
	v_mfma_i32_16x16x64_i8 v[42:45], v[158:161], v[190:193], v[42:45]
	v_mfma_i32_16x16x64_i8 v[30:33], v[150:153], v[198:201], v[30:33]
	v_mfma_i32_16x16x64_i8 v[26:29], v[158:161], v[198:201], v[26:29]
	v_mfma_i32_16x16x64_i8 v[14:17], v[150:153], v[206:209], v[14:17]
	v_mfma_i32_16x16x64_i8 v[10:13], v[158:161], v[206:209], v[10:13]
	v_mfma_i32_16x16x64_i8 v[62:65], v[154:157], v[186:189], v[62:65]
	v_mfma_i32_16x16x64_i8 v[58:61], v[162:165], v[186:189], v[58:61]
	v_mfma_i32_16x16x64_i8 v[46:49], v[154:157], v[194:197], v[46:49]
	v_mfma_i32_16x16x64_i8 v[42:45], v[162:165], v[194:197], v[42:45]
	v_mfma_i32_16x16x64_i8 v[30:33], v[154:157], v[202:205], v[30:33]
	v_mfma_i32_16x16x64_i8 v[26:29], v[162:165], v[202:205], v[26:29]
	v_mfma_i32_16x16x64_i8 v[14:17], v[154:157], v[210:213], v[14:17]
	v_mfma_i32_16x16x64_i8 v[10:13], v[162:165], v[210:213], v[10:13]
	s_setprio 0
	s_setprio 1
	v_mfma_i32_16x16x64_i8 v[54:57], v[166:169], v[182:185], v[54:57]
	v_mfma_i32_16x16x64_i8 v[50:53], v[174:177], v[182:185], v[50:53]
	v_mfma_i32_16x16x64_i8 v[38:41], v[166:169], v[190:193], v[38:41]
	v_mfma_i32_16x16x64_i8 v[34:37], v[174:177], v[190:193], v[34:37]
	v_mfma_i32_16x16x64_i8 v[22:25], v[166:169], v[198:201], v[22:25]
	v_mfma_i32_16x16x64_i8 v[18:21], v[174:177], v[198:201], v[18:21]
	v_mfma_i32_16x16x64_i8 v[6:9], v[166:169], v[206:209], v[6:9]
	v_mfma_i32_16x16x64_i8 v[2:5], v[174:177], v[206:209], v[2:5]
	v_mfma_i32_16x16x64_i8 v[54:57], v[170:173], v[186:189], v[54:57]
	v_mfma_i32_16x16x64_i8 v[50:53], v[178:181], v[186:189], v[50:53]
	v_mfma_i32_16x16x64_i8 v[38:41], v[170:173], v[194:197], v[38:41]
	v_mfma_i32_16x16x64_i8 v[34:37], v[178:181], v[194:197], v[34:37]
	v_mfma_i32_16x16x64_i8 v[22:25], v[170:173], v[202:205], v[22:25]
	v_mfma_i32_16x16x64_i8 v[18:21], v[178:181], v[202:205], v[18:21]
	v_mfma_i32_16x16x64_i8 v[6:9], v[170:173], v[210:213], v[6:9]
	v_mfma_i32_16x16x64_i8 v[2:5], v[178:181], v[210:213], v[2:5]
	s_setprio 0
	s_barrier
	s_add_i32 s65, s65, 2
	s_add_u32 s48, s48, 0x100
	s_addc_u32 s49, s49, 0
	s_add_u32 s25, s25, 0x100
	s_addc_u32 s64, s64, 0
	s_cmp_gt_u32 s65, 5
	s_cbranch_scc0 .LBB0_445
	s_branch .Lpeel_exit_445
.LBB0_445:
	s_add_u32 s46, s48, 0xfffe0080
	s_addc_u32 s47, s49, -1
	s_add_i32 s84, 0, 0x10000
	s_cmp_eq_u32 s65, 4
	s_cselect_b32 s47, s15, s47
	s_cselect_b32 s46, s14, s46
	v_add_u32_e32 v0, s84, v147
	s_cselect_b32 s51, s17, s64
	s_cselect_b32 s50, s16, s25
	s_add_i32 s86, 0, 0x14000
	ds_read_b128 v[150:153], v0
	ds_read_b128 v[154:157], v0 offset:1024
	ds_read_b128 v[158:161], v0 offset:2048
	ds_read_b128 v[162:165], v0 offset:3072
	v_add_u32_e32 v0, s86, v147
	ds_read_b128 v[166:169], v0
	ds_read_b128 v[170:173], v0 offset:1024
	ds_read_b128 v[174:177], v0 offset:2048
	ds_read_b128 v[178:181], v0 offset:3072
	v_mov_b32_e32 v0, v132
	ds_read_b128 v[182:185], v148
	ds_read_b128 v[186:189], v148 offset:1024
	ds_read_b128 v[190:193], v148 offset:2048
	ds_read_b128 v[194:197], v148 offset:3072
	ds_read_b128 v[198:201], v148 offset:4096
	ds_read_b128 v[202:205], v148 offset:5120
	ds_read_b128 v[206:209], v148 offset:6144
	ds_read_b128 v[210:213], v148 offset:7168
	s_add_i32 m0, s59, 0xc000
	s_nop 0
	global_load_lds_dwordx4 v0, s[48:49]
	v_mov_b32_e32 v0, v133
	s_add_i32 m0, s59, 0xe000
	s_nop 0
	global_load_lds_dwordx4 v0, s[48:49]
	s_waitcnt vmcnt(8)
	s_waitcnt lgkmcnt(0)
	s_barrier
	s_setprio 1
	s_waitcnt lgkmcnt(0)
	v_mfma_i32_16x16x64_i8 v[126:129], v[150:153], v[182:185], v[126:129]
	v_mfma_i32_16x16x64_i8 v[122:125], v[158:161], v[182:185], v[122:125]
	v_mfma_i32_16x16x64_i8 v[110:113], v[150:153], v[190:193], v[110:113]
	v_mfma_i32_16x16x64_i8 v[106:109], v[158:161], v[190:193], v[106:109]
	v_mfma_i32_16x16x64_i8 v[94:97], v[150:153], v[198:201], v[94:97]
	v_mfma_i32_16x16x64_i8 v[90:93], v[158:161], v[198:201], v[90:93]
	v_mfma_i32_16x16x64_i8 v[78:81], v[150:153], v[206:209], v[78:81]
	v_mfma_i32_16x16x64_i8 v[74:77], v[158:161], v[206:209], v[74:77]
	v_mfma_i32_16x16x64_i8 v[126:129], v[154:157], v[186:189], v[126:129]
	v_mfma_i32_16x16x64_i8 v[122:125], v[162:165], v[186:189], v[122:125]
	v_mfma_i32_16x16x64_i8 v[110:113], v[154:157], v[194:197], v[110:113]
	v_mfma_i32_16x16x64_i8 v[106:109], v[162:165], v[194:197], v[106:109]
	v_mfma_i32_16x16x64_i8 v[94:97], v[154:157], v[202:205], v[94:97]
	v_mfma_i32_16x16x64_i8 v[90:93], v[162:165], v[202:205], v[90:93]
	v_mfma_i32_16x16x64_i8 v[78:81], v[154:157], v[210:213], v[78:81]
	v_mfma_i32_16x16x64_i8 v[74:77], v[162:165], v[210:213], v[74:77]
	s_setprio 0
	s_setprio 1
	v_mfma_i32_16x16x64_i8 v[118:121], v[166:169], v[182:185], v[118:121]
	v_mfma_i32_16x16x64_i8 v[114:117], v[174:177], v[182:185], v[114:117]
	v_mfma_i32_16x16x64_i8 v[102:105], v[166:169], v[190:193], v[102:105]
	v_mfma_i32_16x16x64_i8 v[98:101], v[174:177], v[190:193], v[98:101]
	v_mfma_i32_16x16x64_i8 v[86:89], v[166:169], v[198:201], v[86:89]
	v_mfma_i32_16x16x64_i8 v[82:85], v[174:177], v[198:201], v[82:85]
	v_mfma_i32_16x16x64_i8 v[70:73], v[166:169], v[206:209], v[70:73]
	v_mfma_i32_16x16x64_i8 v[66:69], v[174:177], v[206:209], v[66:69]
	v_mfma_i32_16x16x64_i8 v[118:121], v[170:173], v[186:189], v[118:121]
	v_mfma_i32_16x16x64_i8 v[114:117], v[178:181], v[186:189], v[114:117]
	v_mfma_i32_16x16x64_i8 v[102:105], v[170:173], v[194:197], v[102:105]
	v_mfma_i32_16x16x64_i8 v[98:101], v[178:181], v[194:197], v[98:101]
	v_mfma_i32_16x16x64_i8 v[86:89], v[170:173], v[202:205], v[86:89]
	v_mfma_i32_16x16x64_i8 v[82:85], v[178:181], v[202:205], v[82:85]
	v_mfma_i32_16x16x64_i8 v[70:73], v[170:173], v[210:213], v[70:73]
	v_mfma_i32_16x16x64_i8 v[66:69], v[178:181], v[210:213], v[66:69]
	s_setprio 0
	s_barrier
	v_mov_b32_e32 v0, v143
	s_add_i32 s84, s84, s40
	ds_read_b128 v[182:185], v148 offset:16384
	ds_read_b128 v[186:189], v148 offset:17408
	ds_read_b128 v[190:193], v148 offset:18432
	ds_read_b128 v[194:197], v148 offset:19456
	ds_read_b128 v[198:201], v148 offset:20480
	ds_read_b128 v[202:205], v148 offset:21504
	ds_read_b128 v[206:209], v148 offset:22528
	ds_read_b128 v[210:213], v148 offset:23552
	s_mov_b32 m0, s84
	s_nop 0
	global_load_lds_dwordx4 v0, s[50:51]
	v_mov_b32_e32 v0, v144
	s_add_i32 m0, s84, 0x2000
	s_add_u32 s84, s50, 0x20000
	global_load_lds_dwordx4 v0, s[50:51]
	s_addc_u32 s85, s51, 0
	v_mov_b32_e32 v0, v143
	s_add_i32 s86, s86, s40
	s_mov_b32 m0, s86
	s_nop 0
	global_load_lds_dwordx4 v0, s[84:85]
	v_mov_b32_e32 v0, v144
	s_add_i32 m0, s86, 0x2000
	s_nop 0
	global_load_lds_dwordx4 v0, s[84:85]
	v_mov_b32_e32 v0, v132
	s_mov_b32 m0, s59
	s_nop 0
	global_load_lds_dwordx4 v0, s[46:47]
	v_mov_b32_e32 v0, v133
	s_mov_b32 m0, s60
	s_nop 0
	global_load_lds_dwordx4 v0, s[46:47]
	s_waitcnt vmcnt(8)
	s_waitcnt lgkmcnt(0)
	s_barrier
	s_setprio 1
	s_waitcnt lgkmcnt(0)
	v_mfma_i32_16x16x64_i8 v[62:65], v[150:153], v[182:185], v[62:65]
	v_mfma_i32_16x16x64_i8 v[58:61], v[158:161], v[182:185], v[58:61]
	v_mfma_i32_16x16x64_i8 v[46:49], v[150:153], v[190:193], v[46:49]
	v_mfma_i32_16x16x64_i8 v[42:45], v[158:161], v[190:193], v[42:45]
	v_mfma_i32_16x16x64_i8 v[30:33], v[150:153], v[198:201], v[30:33]
	v_mfma_i32_16x16x64_i8 v[26:29], v[158:161], v[198:201], v[26:29]
	v_mfma_i32_16x16x64_i8 v[14:17], v[150:153], v[206:209], v[14:17]
	v_mfma_i32_16x16x64_i8 v[10:13], v[158:161], v[206:209], v[10:13]
	v_mfma_i32_16x16x64_i8 v[62:65], v[154:157], v[186:189], v[62:65]
	v_mfma_i32_16x16x64_i8 v[58:61], v[162:165], v[186:189], v[58:61]
	v_mfma_i32_16x16x64_i8 v[46:49], v[154:157], v[194:197], v[46:49]
	v_mfma_i32_16x16x64_i8 v[42:45], v[162:165], v[194:197], v[42:45]
	v_mfma_i32_16x16x64_i8 v[30:33], v[154:157], v[202:205], v[30:33]
	v_mfma_i32_16x16x64_i8 v[26:29], v[162:165], v[202:205], v[26:29]
	v_mfma_i32_16x16x64_i8 v[14:17], v[154:157], v[210:213], v[14:17]
	v_mfma_i32_16x16x64_i8 v[10:13], v[162:165], v[210:213], v[10:13]
	s_setprio 0
	s_setprio 1
	v_mfma_i32_16x16x64_i8 v[54:57], v[166:169], v[182:185], v[54:57]
	v_mfma_i32_16x16x64_i8 v[50:53], v[174:177], v[182:185], v[50:53]
	v_mfma_i32_16x16x64_i8 v[38:41], v[166:169], v[190:193], v[38:41]
	v_mfma_i32_16x16x64_i8 v[34:37], v[174:177], v[190:193], v[34:37]
	v_mfma_i32_16x16x64_i8 v[22:25], v[166:169], v[198:201], v[22:25]
	v_mfma_i32_16x16x64_i8 v[18:21], v[174:177], v[198:201], v[18:21]
	v_mfma_i32_16x16x64_i8 v[6:9], v[166:169], v[206:209], v[6:9]
	v_mfma_i32_16x16x64_i8 v[2:5], v[174:177], v[206:209], v[2:5]
	v_mfma_i32_16x16x64_i8 v[54:57], v[170:173], v[186:189], v[54:57]
	v_mfma_i32_16x16x64_i8 v[50:53], v[178:181], v[186:189], v[50:53]
	v_mfma_i32_16x16x64_i8 v[38:41], v[170:173], v[194:197], v[38:41]
	v_mfma_i32_16x16x64_i8 v[34:37], v[178:181], v[194:197], v[34:37]
	v_mfma_i32_16x16x64_i8 v[22:25], v[170:173], v[202:205], v[22:25]
	v_mfma_i32_16x16x64_i8 v[18:21], v[178:181], v[202:205], v[18:21]
	v_mfma_i32_16x16x64_i8 v[6:9], v[170:173], v[210:213], v[6:9]
	v_mfma_i32_16x16x64_i8 v[2:5], v[178:181], v[210:213], v[2:5]
	s_setprio 0
	s_barrier
	s_add_i32 s86, 0, 0x18000
	v_add_u32_e32 v0, s86, v147
	s_add_i32 s87, 0, 0x1c000
	ds_read_b128 v[150:153], v0
	ds_read_b128 v[154:157], v0 offset:1024
	ds_read_b128 v[158:161], v0 offset:2048
	ds_read_b128 v[162:165], v0 offset:3072
	v_add_u32_e32 v0, s87, v147
	ds_read_b128 v[166:169], v0
	ds_read_b128 v[170:173], v0 offset:1024
	ds_read_b128 v[174:177], v0 offset:2048
	ds_read_b128 v[178:181], v0 offset:3072
	s_add_u32 s84, s46, 0x20000
	v_mov_b32_e32 v0, v132
	s_mov_b32 m0, s61
	ds_read_b128 v[182:185], v148 offset:32768
	ds_read_b128 v[186:189], v148 offset:33792
	ds_read_b128 v[190:193], v148 offset:34816
	ds_read_b128 v[194:197], v148 offset:35840
	ds_read_b128 v[198:201], v148 offset:36864
	ds_read_b128 v[202:205], v148 offset:37888
	ds_read_b128 v[206:209], v148 offset:38912
	ds_read_b128 v[210:213], v148 offset:39936
	s_addc_u32 s85, s47, 0
	s_nop 0
	global_load_lds_dwordx4 v0, s[84:85]
	v_mov_b32_e32 v0, v133
	s_mov_b32 m0, s66
	s_nop 0
	global_load_lds_dwordx4 v0, s[84:85]
	s_waitcnt vmcnt(8)
	s_waitcnt lgkmcnt(0)
	s_barrier
	s_setprio 1
	s_waitcnt lgkmcnt(0)
	v_mfma_i32_16x16x64_i8 v[126:129], v[150:153], v[182:185], v[126:129]
	v_mfma_i32_16x16x64_i8 v[122:125], v[158:161], v[182:185], v[122:125]
	v_mfma_i32_16x16x64_i8 v[110:113], v[150:153], v[190:193], v[110:113]
	v_mfma_i32_16x16x64_i8 v[106:109], v[158:161], v[190:193], v[106:109]
	v_mfma_i32_16x16x64_i8 v[94:97], v[150:153], v[198:201], v[94:97]
	v_mfma_i32_16x16x64_i8 v[90:93], v[158:161], v[198:201], v[90:93]
	v_mfma_i32_16x16x64_i8 v[78:81], v[150:153], v[206:209], v[78:81]
	v_mfma_i32_16x16x64_i8 v[74:77], v[158:161], v[206:209], v[74:77]
	v_mfma_i32_16x16x64_i8 v[126:129], v[154:157], v[186:189], v[126:129]
	v_mfma_i32_16x16x64_i8 v[122:125], v[162:165], v[186:189], v[122:125]
	v_mfma_i32_16x16x64_i8 v[110:113], v[154:157], v[194:197], v[110:113]
	v_mfma_i32_16x16x64_i8 v[106:109], v[162:165], v[194:197], v[106:109]
	v_mfma_i32_16x16x64_i8 v[94:97], v[154:157], v[202:205], v[94:97]
	v_mfma_i32_16x16x64_i8 v[90:93], v[162:165], v[202:205], v[90:93]
	v_mfma_i32_16x16x64_i8 v[78:81], v[154:157], v[210:213], v[78:81]
	v_mfma_i32_16x16x64_i8 v[74:77], v[162:165], v[210:213], v[74:77]
	s_setprio 0
	s_setprio 1
	v_mfma_i32_16x16x64_i8 v[118:121], v[166:169], v[182:185], v[118:121]
	v_mfma_i32_16x16x64_i8 v[114:117], v[174:177], v[182:185], v[114:117]
	v_mfma_i32_16x16x64_i8 v[102:105], v[166:169], v[190:193], v[102:105]
	v_mfma_i32_16x16x64_i8 v[98:101], v[174:177], v[190:193], v[98:101]
	v_mfma_i32_16x16x64_i8 v[86:89], v[166:169], v[198:201], v[86:89]
	v_mfma_i32_16x16x64_i8 v[82:85], v[174:177], v[198:201], v[82:85]
	v_mfma_i32_16x16x64_i8 v[70:73], v[166:169], v[206:209], v[70:73]
	v_mfma_i32_16x16x64_i8 v[66:69], v[174:177], v[206:209], v[66:69]
	v_mfma_i32_16x16x64_i8 v[118:121], v[170:173], v[186:189], v[118:121]
	v_mfma_i32_16x16x64_i8 v[114:117], v[178:181], v[186:189], v[114:117]
	v_mfma_i32_16x16x64_i8 v[102:105], v[170:173], v[194:197], v[102:105]
	v_mfma_i32_16x16x64_i8 v[98:101], v[178:181], v[194:197], v[98:101]
	v_mfma_i32_16x16x64_i8 v[86:89], v[170:173], v[202:205], v[86:89]
	v_mfma_i32_16x16x64_i8 v[82:85], v[178:181], v[202:205], v[82:85]
	v_mfma_i32_16x16x64_i8 v[70:73], v[170:173], v[210:213], v[70:73]
	v_mfma_i32_16x16x64_i8 v[66:69], v[178:181], v[210:213], v[66:69]
	s_setprio 0
	s_barrier
	v_mov_b32_e32 v0, v143
	ds_read_b128 v[182:185], v148 offset:49152
	ds_read_b128 v[186:189], v148 offset:50176
	ds_read_b128 v[190:193], v148 offset:51200
	ds_read_b128 v[194:197], v148 offset:52224
	ds_read_b128 v[198:201], v148 offset:53248
	ds_read_b128 v[202:205], v148 offset:54272
	ds_read_b128 v[206:209], v148 offset:55296
	ds_read_b128 v[210:213], v148 offset:56320
	s_add_i32 s84, s86, s40
	s_add_u32 s100, s50, s38
	s_addc_u32 s101, s51, s39
	s_mov_b32 m0, s84
	v_mov_b32_e32 v0, v144
	global_load_lds_dwordx4 v143, s[100:101]
	s_add_i32 m0, s84, 0x2000
	s_nop 0
	s_add_u32 s50, s50, 0x20080
	s_addc_u32 s51, s51, 0
	v_mov_b32_e32 v0, v143
	s_add_i32 s84, s87, s40
	global_load_lds_dwordx4 v144, s[100:101]
	s_mov_b32 m0, s84
	s_nop 0
	global_load_lds_dwordx4 v0, s[50:51]
	v_mov_b32_e32 v0, v144
	s_add_i32 m0, s84, 0x2000
	s_nop 0
	global_load_lds_dwordx4 v0, s[50:51]
	v_mov_b32_e32 v0, v132
	s_mov_b32 m0, s75
	s_add_u32 s100, s46, s38
	s_addc_u32 s101, s47, s39
	v_mov_b32_e32 v0, v133
	global_load_lds_dwordx4 v132, s[100:101]
	s_mov_b32 m0, s78
	s_nop 0
	global_load_lds_dwordx4 v133, s[100:101]
	s_waitcnt vmcnt(8)
	s_waitcnt lgkmcnt(0)
	s_barrier
	s_setprio 1
	s_waitcnt lgkmcnt(0)
	v_mfma_i32_16x16x64_i8 v[62:65], v[150:153], v[182:185], v[62:65]
	v_mfma_i32_16x16x64_i8 v[58:61], v[158:161], v[182:185], v[58:61]
	v_mfma_i32_16x16x64_i8 v[46:49], v[150:153], v[190:193], v[46:49]
	v_mfma_i32_16x16x64_i8 v[42:45], v[158:161], v[190:193], v[42:45]
	v_mfma_i32_16x16x64_i8 v[30:33], v[150:153], v[198:201], v[30:33]
	v_mfma_i32_16x16x64_i8 v[26:29], v[158:161], v[198:201], v[26:29]
	v_mfma_i32_16x16x64_i8 v[14:17], v[150:153], v[206:209], v[14:17]
	v_mfma_i32_16x16x64_i8 v[10:13], v[158:161], v[206:209], v[10:13]
	v_mfma_i32_16x16x64_i8 v[62:65], v[154:157], v[186:189], v[62:65]
	v_mfma_i32_16x16x64_i8 v[58:61], v[162:165], v[186:189], v[58:61]
	v_mfma_i32_16x16x64_i8 v[46:49], v[154:157], v[194:197], v[46:49]
	v_mfma_i32_16x16x64_i8 v[42:45], v[162:165], v[194:197], v[42:45]
	v_mfma_i32_16x16x64_i8 v[30:33], v[154:157], v[202:205], v[30:33]
	v_mfma_i32_16x16x64_i8 v[26:29], v[162:165], v[202:205], v[26:29]
	v_mfma_i32_16x16x64_i8 v[14:17], v[154:157], v[210:213], v[14:17]
	v_mfma_i32_16x16x64_i8 v[10:13], v[162:165], v[210:213], v[10:13]
	s_setprio 0
	s_setprio 1
	v_mfma_i32_16x16x64_i8 v[54:57], v[166:169], v[182:185], v[54:57]
	v_mfma_i32_16x16x64_i8 v[50:53], v[174:177], v[182:185], v[50:53]
	v_mfma_i32_16x16x64_i8 v[38:41], v[166:169], v[190:193], v[38:41]
	v_mfma_i32_16x16x64_i8 v[34:37], v[174:177], v[190:193], v[34:37]
	v_mfma_i32_16x16x64_i8 v[22:25], v[166:169], v[198:201], v[22:25]
	v_mfma_i32_16x16x64_i8 v[18:21], v[174:177], v[198:201], v[18:21]
	v_mfma_i32_16x16x64_i8 v[6:9], v[166:169], v[206:209], v[6:9]
	v_mfma_i32_16x16x64_i8 v[2:5], v[174:177], v[206:209], v[2:5]
	v_mfma_i32_16x16x64_i8 v[54:57], v[170:173], v[186:189], v[54:57]
	v_mfma_i32_16x16x64_i8 v[50:53], v[178:181], v[186:189], v[50:53]
	v_mfma_i32_16x16x64_i8 v[38:41], v[170:173], v[194:197], v[38:41]
	v_mfma_i32_16x16x64_i8 v[34:37], v[178:181], v[194:197], v[34:37]
	v_mfma_i32_16x16x64_i8 v[22:25], v[170:173], v[202:205], v[22:25]
	v_mfma_i32_16x16x64_i8 v[18:21], v[178:181], v[202:205], v[18:21]
	v_mfma_i32_16x16x64_i8 v[6:9], v[170:173], v[210:213], v[6:9]
	v_mfma_i32_16x16x64_i8 v[2:5], v[178:181], v[210:213], v[2:5]
	s_setprio 0
	s_barrier
	s_add_i32 s65, s65, 2
	s_add_u32 s48, s48, 0x100
	s_addc_u32 s49, s49, 0
	s_add_u32 s25, s25, 0x100
	s_addc_u32 s64, s64, 0
	s_cmp_gt_u32 s65, 5
	s_cbranch_scc0 .LBB0_445

.LBB0_626:
	s_add_u32 s58, s14, s50
	s_addc_u32 s59, s15, s51
	s_add_u32 s46, s58, 0x100
	s_addc_u32 s47, s59, 0
	s_and_b64 s[4:5], s[48:49], exec
	s_cselect_b32 s47, s15, s47
	s_cselect_b32 s46, s14, s46
	s_add_u32 s4, s16, s50
	s_addc_u32 s5, s17, s51
	s_add_u32 s50, s4, 0x100
	s_addc_u32 s51, s5, 0
	s_add_i32 s78, 0, 0x10000
	s_and_b64 s[4:5], s[48:49], exec
	s_cselect_b32 s49, s17, s51
	s_cselect_b32 s48, s16, s50
	s_add_i32 s4, 0, 0x14000
	s_add_u32 s96, s58, 0x80080
	s_addc_u32 s97, s59, 0
	s_add_i32 s82, s78, s42
	s_add_i32 m0, s43, 0xc000
	s_add_i32 s5, s43, 0xe000
	s_add_i32 s76, s82, 0x2000
	v_add_u32_e32 v0, s78, v136
	s_add_u32 s94, s48, 0x40000
	ds_read_b128 v[138:141], v0
	ds_read_b128 v[142:145], v0 offset:1024
	ds_read_b128 v[146:149], v0 offset:2048
	ds_read_b128 v[150:153], v0 offset:3072
	v_add_u32_e32 v0, s4, v136
	s_addc_u32 s95, s49, 0
	s_add_i32 s77, s4, s42
	ds_read_b128 v[154:157], v0
	ds_read_b128 v[158:161], v0 offset:1024
	ds_read_b128 v[162:165], v0 offset:2048
	ds_read_b128 v[166:169], v0 offset:3072
	s_add_i32 s75, s77, 0x2000
	s_add_i32 s74, 0, 0x18000
	s_add_i32 s71, 0, 0x1c000
	s_add_u32 s58, s46, 0x80000
	s_addc_u32 s59, s47, 0
	s_add_i32 s70, s74, s42
	s_add_i32 s69, s70, 0x2000
	s_add_u32 s50, s48, 0x40080
	s_addc_u32 s51, s49, 0
	s_add_i32 s79, s71, s42
	s_add_i32 s78, s79, 0x2000
	v_mov_b32_e32 v0, v130
	ds_read_b128 v[170:173], v137
	ds_read_b128 v[174:177], v137 offset:1024
	ds_read_b128 v[178:181], v137 offset:2048
	ds_read_b128 v[182:185], v137 offset:3072
	ds_read_b128 v[186:189], v137 offset:4096
	ds_read_b128 v[190:193], v137 offset:5120
	ds_read_b128 v[194:197], v137 offset:6144
	ds_read_b128 v[198:201], v137 offset:7168
	s_nop 0
	global_load_lds_dwordx4 v0, s[96:97]
	v_mov_b32_e32 v0, v132
	s_mov_b32 m0, s5
	s_nop 0
	global_load_lds_dwordx4 v0, s[96:97]
	s_waitcnt vmcnt(8)
	s_waitcnt lgkmcnt(0)
	s_barrier
	s_setprio 1
	s_waitcnt lgkmcnt(0)
	v_mfma_f32_16x16x32_bf16 v[126:129], v[138:141], v[170:173], v[126:129]
	v_mfma_f32_16x16x32_bf16 v[122:125], v[146:149], v[170:173], v[122:125]
	v_mfma_f32_16x16x32_bf16 v[118:121], v[138:141], v[178:181], v[118:121]
	v_mfma_f32_16x16x32_bf16 v[110:113], v[146:149], v[178:181], v[110:113]
	v_mfma_f32_16x16x32_bf16 v[102:105], v[138:141], v[186:189], v[102:105]
	v_mfma_f32_16x16x32_bf16 v[94:97], v[146:149], v[186:189], v[94:97]
	v_mfma_f32_16x16x32_bf16 v[86:89], v[138:141], v[194:197], v[86:89]
	v_mfma_f32_16x16x32_bf16 v[78:81], v[146:149], v[194:197], v[78:81]
	v_mfma_f32_16x16x32_bf16 v[126:129], v[142:145], v[174:177], v[126:129]
	v_mfma_f32_16x16x32_bf16 v[122:125], v[150:153], v[174:177], v[122:125]
	v_mfma_f32_16x16x32_bf16 v[118:121], v[142:145], v[182:185], v[118:121]
	v_mfma_f32_16x16x32_bf16 v[110:113], v[150:153], v[182:185], v[110:113]
	v_mfma_f32_16x16x32_bf16 v[102:105], v[142:145], v[190:193], v[102:105]
	v_mfma_f32_16x16x32_bf16 v[94:97], v[150:153], v[190:193], v[94:97]
	v_mfma_f32_16x16x32_bf16 v[86:89], v[142:145], v[198:201], v[86:89]
	v_mfma_f32_16x16x32_bf16 v[78:81], v[150:153], v[198:201], v[78:81]
	s_setprio 0
	s_setprio 1
	v_mfma_f32_16x16x32_bf16 v[114:117], v[154:157], v[170:173], v[114:117]
	v_mfma_f32_16x16x32_bf16 v[106:109], v[162:165], v[170:173], v[106:109]
	v_mfma_f32_16x16x32_bf16 v[98:101], v[154:157], v[178:181], v[98:101]
	v_mfma_f32_16x16x32_bf16 v[90:93], v[162:165], v[178:181], v[90:93]
	v_mfma_f32_16x16x32_bf16 v[82:85], v[154:157], v[186:189], v[82:85]
	v_mfma_f32_16x16x32_bf16 v[74:77], v[162:165], v[186:189], v[74:77]
	v_mfma_f32_16x16x32_bf16 v[70:73], v[154:157], v[194:197], v[70:73]
	v_mfma_f32_16x16x32_bf16 v[62:65], v[162:165], v[194:197], v[62:65]
	v_mfma_f32_16x16x32_bf16 v[114:117], v[158:161], v[174:177], v[114:117]
	v_mfma_f32_16x16x32_bf16 v[106:109], v[166:169], v[174:177], v[106:109]
	v_mfma_f32_16x16x32_bf16 v[98:101], v[158:161], v[182:185], v[98:101]
	v_mfma_f32_16x16x32_bf16 v[90:93], v[166:169], v[182:185], v[90:93]
	v_mfma_f32_16x16x32_bf16 v[82:85], v[158:161], v[190:193], v[82:85]
	v_mfma_f32_16x16x32_bf16 v[74:77], v[166:169], v[190:193], v[74:77]
	v_mfma_f32_16x16x32_bf16 v[70:73], v[158:161], v[198:201], v[70:73]
	v_mfma_f32_16x16x32_bf16 v[62:65], v[166:169], v[198:201], v[62:65]
	s_setprio 0
	s_barrier
	v_mov_b32_e32 v0, v131
	s_mov_b32 m0, s82
	ds_read_b128 v[170:173], v137 offset:16384
	ds_read_b128 v[174:177], v137 offset:17408
	ds_read_b128 v[178:181], v137 offset:18432
	ds_read_b128 v[182:185], v137 offset:19456
	ds_read_b128 v[186:189], v137 offset:20480
	ds_read_b128 v[190:193], v137 offset:21504
	ds_read_b128 v[194:197], v137 offset:22528
	ds_read_b128 v[198:201], v137 offset:23552
	s_nop 0
	global_load_lds_dwordx4 v0, s[48:49]
	v_mov_b32_e32 v0, v133
	s_mov_b32 m0, s76
	s_nop 0
	global_load_lds_dwordx4 v0, s[48:49]
	v_mov_b32_e32 v0, v131
	s_mov_b32 m0, s77
	s_nop 0
	global_load_lds_dwordx4 v0, s[94:95]
	v_mov_b32_e32 v0, v133
	s_mov_b32 m0, s75
	s_nop 0
	global_load_lds_dwordx4 v0, s[94:95]
	v_mov_b32_e32 v0, v130
	s_mov_b32 m0, s43
	s_nop 0
	global_load_lds_dwordx4 v0, s[46:47]
	v_mov_b32_e32 v0, v132
	s_mov_b32 m0, s60
	s_nop 0
	global_load_lds_dwordx4 v0, s[46:47]
	s_waitcnt vmcnt(8)
	s_waitcnt lgkmcnt(0)
	s_barrier
	s_setprio 1
	s_waitcnt lgkmcnt(0)
	v_mfma_f32_16x16x32_bf16 v[66:69], v[138:141], v[170:173], v[66:69]
	v_mfma_f32_16x16x32_bf16 v[58:61], v[146:149], v[170:173], v[58:61]
	v_mfma_f32_16x16x32_bf16 v[54:57], v[138:141], v[178:181], v[54:57]
	v_mfma_f32_16x16x32_bf16 v[46:49], v[146:149], v[178:181], v[46:49]
	v_mfma_f32_16x16x32_bf16 v[38:41], v[138:141], v[186:189], v[38:41]
	v_mfma_f32_16x16x32_bf16 v[30:33], v[146:149], v[186:189], v[30:33]
	v_mfma_f32_16x16x32_bf16 v[22:25], v[138:141], v[194:197], v[22:25]
	v_mfma_f32_16x16x32_bf16 v[14:17], v[146:149], v[194:197], v[14:17]
	v_mfma_f32_16x16x32_bf16 v[66:69], v[142:145], v[174:177], v[66:69]
	v_mfma_f32_16x16x32_bf16 v[58:61], v[150:153], v[174:177], v[58:61]
	v_mfma_f32_16x16x32_bf16 v[54:57], v[142:145], v[182:185], v[54:57]
	v_mfma_f32_16x16x32_bf16 v[46:49], v[150:153], v[182:185], v[46:49]
	v_mfma_f32_16x16x32_bf16 v[38:41], v[142:145], v[190:193], v[38:41]
	v_mfma_f32_16x16x32_bf16 v[30:33], v[150:153], v[190:193], v[30:33]
	v_mfma_f32_16x16x32_bf16 v[22:25], v[142:145], v[198:201], v[22:25]
	v_mfma_f32_16x16x32_bf16 v[14:17], v[150:153], v[198:201], v[14:17]
	s_setprio 0
	s_setprio 1
	v_mfma_f32_16x16x32_bf16 v[50:53], v[154:157], v[170:173], v[50:53]
	v_mfma_f32_16x16x32_bf16 v[42:45], v[162:165], v[170:173], v[42:45]
	v_mfma_f32_16x16x32_bf16 v[34:37], v[154:157], v[178:181], v[34:37]
	v_mfma_f32_16x16x32_bf16 v[26:29], v[162:165], v[178:181], v[26:29]
	v_mfma_f32_16x16x32_bf16 v[18:21], v[154:157], v[186:189], v[18:21]
	v_mfma_f32_16x16x32_bf16 v[10:13], v[162:165], v[186:189], v[10:13]
	v_mfma_f32_16x16x32_bf16 v[6:9], v[154:157], v[194:197], v[6:9]
	v_mfma_f32_16x16x32_bf16 v[2:5], v[162:165], v[194:197], v[2:5]
	v_mfma_f32_16x16x32_bf16 v[50:53], v[158:161], v[174:177], v[50:53]
	v_mfma_f32_16x16x32_bf16 v[42:45], v[166:169], v[174:177], v[42:45]
	v_mfma_f32_16x16x32_bf16 v[34:37], v[158:161], v[182:185], v[34:37]
	v_mfma_f32_16x16x32_bf16 v[26:29], v[166:169], v[182:185], v[26:29]
	v_mfma_f32_16x16x32_bf16 v[18:21], v[158:161], v[190:193], v[18:21]
	v_mfma_f32_16x16x32_bf16 v[10:13], v[166:169], v[190:193], v[10:13]
	v_mfma_f32_16x16x32_bf16 v[6:9], v[158:161], v[198:201], v[6:9]
	v_mfma_f32_16x16x32_bf16 v[2:5], v[166:169], v[198:201], v[2:5]
	s_setprio 0
	s_barrier
	v_add_u32_e32 v0, s74, v136
	ds_read_b128 v[138:141], v0
	ds_read_b128 v[142:145], v0 offset:1024
	ds_read_b128 v[146:149], v0 offset:2048
	ds_read_b128 v[150:153], v0 offset:3072
	v_add_u32_e32 v0, s71, v136
	ds_read_b128 v[154:157], v0
	ds_read_b128 v[158:161], v0 offset:1024
	ds_read_b128 v[162:165], v0 offset:2048
	ds_read_b128 v[166:169], v0 offset:3072
	v_mov_b32_e32 v0, v130
	s_mov_b32 m0, s65
	ds_read_b128 v[170:173], v137 offset:32768
	ds_read_b128 v[174:177], v137 offset:33792
	ds_read_b128 v[178:181], v137 offset:34816
	ds_read_b128 v[182:185], v137 offset:35840
	ds_read_b128 v[186:189], v137 offset:36864
	ds_read_b128 v[190:193], v137 offset:37888
	ds_read_b128 v[194:197], v137 offset:38912
	ds_read_b128 v[198:201], v137 offset:39936
	s_nop 0
	global_load_lds_dwordx4 v0, s[58:59]
	v_mov_b32_e32 v0, v132
	s_mov_b32 m0, s66
	s_nop 0
	global_load_lds_dwordx4 v0, s[58:59]
	s_waitcnt vmcnt(8)
	s_waitcnt lgkmcnt(0)
	s_barrier
	s_setprio 1
	s_waitcnt lgkmcnt(0)
	v_mfma_f32_16x16x32_bf16 v[126:129], v[138:141], v[170:173], v[126:129]
	v_mfma_f32_16x16x32_bf16 v[122:125], v[146:149], v[170:173], v[122:125]
	v_mfma_f32_16x16x32_bf16 v[118:121], v[138:141], v[178:181], v[118:121]
	v_mfma_f32_16x16x32_bf16 v[110:113], v[146:149], v[178:181], v[110:113]
	v_mfma_f32_16x16x32_bf16 v[102:105], v[138:141], v[186:189], v[102:105]
	v_mfma_f32_16x16x32_bf16 v[94:97], v[146:149], v[186:189], v[94:97]
	v_mfma_f32_16x16x32_bf16 v[86:89], v[138:141], v[194:197], v[86:89]
	v_mfma_f32_16x16x32_bf16 v[78:81], v[146:149], v[194:197], v[78:81]
	v_mfma_f32_16x16x32_bf16 v[126:129], v[142:145], v[174:177], v[126:129]
	v_mfma_f32_16x16x32_bf16 v[122:125], v[150:153], v[174:177], v[122:125]
	v_mfma_f32_16x16x32_bf16 v[118:121], v[142:145], v[182:185], v[118:121]
	v_mfma_f32_16x16x32_bf16 v[110:113], v[150:153], v[182:185], v[110:113]
	v_mfma_f32_16x16x32_bf16 v[102:105], v[142:145], v[190:193], v[102:105]
	v_mfma_f32_16x16x32_bf16 v[94:97], v[150:153], v[190:193], v[94:97]
	v_mfma_f32_16x16x32_bf16 v[86:89], v[142:145], v[198:201], v[86:89]
	v_mfma_f32_16x16x32_bf16 v[78:81], v[150:153], v[198:201], v[78:81]
	s_setprio 0
	s_setprio 1
	v_mfma_f32_16x16x32_bf16 v[114:117], v[154:157], v[170:173], v[114:117]
	v_mfma_f32_16x16x32_bf16 v[106:109], v[162:165], v[170:173], v[106:109]
	v_mfma_f32_16x16x32_bf16 v[98:101], v[154:157], v[178:181], v[98:101]
	v_mfma_f32_16x16x32_bf16 v[90:93], v[162:165], v[178:181], v[90:93]
	v_mfma_f32_16x16x32_bf16 v[82:85], v[154:157], v[186:189], v[82:85]
	v_mfma_f32_16x16x32_bf16 v[74:77], v[162:165], v[186:189], v[74:77]
	v_mfma_f32_16x16x32_bf16 v[70:73], v[154:157], v[194:197], v[70:73]
	v_mfma_f32_16x16x32_bf16 v[62:65], v[162:165], v[194:197], v[62:65]
	v_mfma_f32_16x16x32_bf16 v[114:117], v[158:161], v[174:177], v[114:117]
	v_mfma_f32_16x16x32_bf16 v[106:109], v[166:169], v[174:177], v[106:109]
	v_mfma_f32_16x16x32_bf16 v[98:101], v[158:161], v[182:185], v[98:101]
	v_mfma_f32_16x16x32_bf16 v[90:93], v[166:169], v[182:185], v[90:93]
	v_mfma_f32_16x16x32_bf16 v[82:85], v[158:161], v[190:193], v[82:85]
	v_mfma_f32_16x16x32_bf16 v[74:77], v[166:169], v[190:193], v[74:77]
	v_mfma_f32_16x16x32_bf16 v[70:73], v[158:161], v[198:201], v[70:73]
	v_mfma_f32_16x16x32_bf16 v[62:65], v[166:169], v[198:201], v[62:65]
	s_setprio 0
	s_barrier
	v_mov_b32_e32 v0, v131
	ds_read_b128 v[170:173], v137 offset:49152
	ds_read_b128 v[174:177], v137 offset:50176
	ds_read_b128 v[178:181], v137 offset:51200
	ds_read_b128 v[182:185], v137 offset:52224
	ds_read_b128 v[186:189], v137 offset:53248
	ds_read_b128 v[190:193], v137 offset:54272
	ds_read_b128 v[194:197], v137 offset:55296
	ds_read_b128 v[198:201], v137 offset:56320
	s_mov_b32 m0, s70
	s_add_u32 s100, s48, s38
	s_addc_u32 s101, s49, s39
	v_mov_b32_e32 v0, v133
	global_load_lds_dwordx4 v131, s[100:101]
	s_mov_b32 m0, s69
	v_mov_b32_e32 v0, v131
	global_load_lds_dwordx4 v133, s[100:101]
	s_mov_b32 m0, s79
	s_nop 0
	global_load_lds_dwordx4 v0, s[50:51]
	v_mov_b32_e32 v0, v133
	s_mov_b32 m0, s78
	s_nop 0
	global_load_lds_dwordx4 v0, s[50:51]
	v_mov_b32_e32 v0, v130
	s_mov_b32 m0, s67
	s_add_u32 s100, s46, s38
	s_addc_u32 s101, s47, s39
	v_mov_b32_e32 v0, v132
	global_load_lds_dwordx4 v130, s[100:101]
	s_mov_b32 m0, s68
	s_nop 0
	global_load_lds_dwordx4 v132, s[100:101]
	s_waitcnt vmcnt(8)
	s_waitcnt lgkmcnt(0)
	s_barrier
	s_setprio 1
	s_waitcnt lgkmcnt(0)
	v_mfma_f32_16x16x32_bf16 v[66:69], v[138:141], v[170:173], v[66:69]
	v_mfma_f32_16x16x32_bf16 v[58:61], v[146:149], v[170:173], v[58:61]
	v_mfma_f32_16x16x32_bf16 v[54:57], v[138:141], v[178:181], v[54:57]
	v_mfma_f32_16x16x32_bf16 v[46:49], v[146:149], v[178:181], v[46:49]
	v_mfma_f32_16x16x32_bf16 v[38:41], v[138:141], v[186:189], v[38:41]
	v_mfma_f32_16x16x32_bf16 v[30:33], v[146:149], v[186:189], v[30:33]
	v_mfma_f32_16x16x32_bf16 v[22:25], v[138:141], v[194:197], v[22:25]
	v_mfma_f32_16x16x32_bf16 v[14:17], v[146:149], v[194:197], v[14:17]
	v_mfma_f32_16x16x32_bf16 v[66:69], v[142:145], v[174:177], v[66:69]
	v_mfma_f32_16x16x32_bf16 v[58:61], v[150:153], v[174:177], v[58:61]
	v_mfma_f32_16x16x32_bf16 v[54:57], v[142:145], v[182:185], v[54:57]
	v_mfma_f32_16x16x32_bf16 v[46:49], v[150:153], v[182:185], v[46:49]
	v_mfma_f32_16x16x32_bf16 v[38:41], v[142:145], v[190:193], v[38:41]
	v_mfma_f32_16x16x32_bf16 v[30:33], v[150:153], v[190:193], v[30:33]
	v_mfma_f32_16x16x32_bf16 v[22:25], v[142:145], v[198:201], v[22:25]
	v_mfma_f32_16x16x32_bf16 v[14:17], v[150:153], v[198:201], v[14:17]
	s_setprio 0
	s_setprio 1
	v_mfma_f32_16x16x32_bf16 v[50:53], v[154:157], v[170:173], v[50:53]
	v_mfma_f32_16x16x32_bf16 v[42:45], v[162:165], v[170:173], v[42:45]
	v_mfma_f32_16x16x32_bf16 v[34:37], v[154:157], v[178:181], v[34:37]
	v_mfma_f32_16x16x32_bf16 v[26:29], v[162:165], v[178:181], v[26:29]
	v_mfma_f32_16x16x32_bf16 v[18:21], v[154:157], v[186:189], v[18:21]
	v_mfma_f32_16x16x32_bf16 v[10:13], v[162:165], v[186:189], v[10:13]
	v_mfma_f32_16x16x32_bf16 v[6:9], v[154:157], v[194:197], v[6:9]
	v_mfma_f32_16x16x32_bf16 v[2:5], v[162:165], v[194:197], v[2:5]
	v_mfma_f32_16x16x32_bf16 v[50:53], v[158:161], v[174:177], v[50:53]
	v_mfma_f32_16x16x32_bf16 v[42:45], v[166:169], v[174:177], v[42:45]
	v_mfma_f32_16x16x32_bf16 v[34:37], v[158:161], v[182:185], v[34:37]
	v_mfma_f32_16x16x32_bf16 v[26:29], v[166:169], v[182:185], v[26:29]
	v_mfma_f32_16x16x32_bf16 v[18:21], v[158:161], v[190:193], v[18:21]
	v_mfma_f32_16x16x32_bf16 v[10:13], v[166:169], v[190:193], v[10:13]
	v_mfma_f32_16x16x32_bf16 v[6:9], v[158:161], v[198:201], v[6:9]
	v_mfma_f32_16x16x32_bf16 v[2:5], v[166:169], v[198:201], v[2:5]
	s_setprio 0
	s_barrier
	s_andn2_b64 vcc, exec, s[22:23]
	s_mov_b64 s[48:49], -1
	s_mov_b64 s[22:23], 0
	s_mov_b64 s[50:51], 0x100
	s_cbranch_vccz .LBB0_626
	s_cmpk_lt_u32 s25, 0x100
	s_cbranch_scc0 .LBB0_629
	s_barrier

.LBB0_634:
	s_add_u32 s50, s2, s48
	s_addc_u32 s51, s3, s49
	s_add_u32 s22, s50, 0x100
	s_addc_u32 s23, s51, 0
	s_and_b64 s[4:5], s[46:47], exec
	s_cselect_b32 s23, s3, s23
	s_cselect_b32 s22, s2, s22
	s_add_u32 s4, s14, s48
	s_addc_u32 s5, s15, s49
	s_add_u32 s48, s4, 0x900
	s_addc_u32 s49, s5, 0
	s_add_i32 s78, 0, 0x10000
	s_and_b64 s[4:5], s[46:47], exec
	s_cselect_b32 s47, s66, s49
	s_cselect_b32 s46, s65, s48
	s_add_i32 s4, 0, 0x14000
	s_add_u32 s94, s50, 0x40080
	s_addc_u32 s95, s51, 0
	s_add_i32 s82, s78, s40
	s_add_i32 m0, s41, 0xc000
	s_add_i32 s5, s41, 0xe000
	s_add_i32 s76, s82, 0x2000
	v_add_u32_e32 v0, s78, v136
	s_add_u32 s58, s46, 0x80000
	ds_read_b128 v[138:141], v0
	ds_read_b128 v[142:145], v0 offset:1024
	ds_read_b128 v[146:149], v0 offset:2048
	ds_read_b128 v[150:153], v0 offset:3072
	v_add_u32_e32 v0, s4, v136
	s_addc_u32 s59, s47, 0
	s_add_i32 s77, s4, s40
	ds_read_b128 v[154:157], v0
	ds_read_b128 v[158:161], v0 offset:1024
	ds_read_b128 v[162:165], v0 offset:2048
	ds_read_b128 v[166:169], v0 offset:3072
	s_add_i32 s75, s77, 0x2000
	s_add_i32 s74, 0, 0x18000
	s_add_i32 s71, 0, 0x1c000
	s_add_u32 s50, s22, 0x40000
	s_addc_u32 s51, s23, 0
	s_add_i32 s70, s74, s40
	s_add_i32 s69, s70, 0x2000
	s_add_u32 s48, s46, 0x80080
	s_addc_u32 s49, s47, 0
	s_add_i32 s79, s71, s40
	s_add_i32 s78, s79, 0x2000
	v_mov_b32_e32 v0, v130
	ds_read_b128 v[170:173], v137
	ds_read_b128 v[174:177], v137 offset:1024
	ds_read_b128 v[178:181], v137 offset:2048
	ds_read_b128 v[182:185], v137 offset:3072
	ds_read_b128 v[186:189], v137 offset:4096
	ds_read_b128 v[190:193], v137 offset:5120
	ds_read_b128 v[194:197], v137 offset:6144
	ds_read_b128 v[198:201], v137 offset:7168
	s_nop 0
	global_load_lds_dwordx4 v0, s[94:95]
	v_mov_b32_e32 v0, v132
	s_mov_b32 m0, s5
	s_nop 0
	global_load_lds_dwordx4 v0, s[94:95]
	s_waitcnt vmcnt(8)
	s_waitcnt lgkmcnt(0)
	s_barrier
	s_setprio 1
	s_waitcnt lgkmcnt(0)
	v_mfma_f32_16x16x32_bf16 v[126:129], v[138:141], v[170:173], v[126:129]
	v_mfma_f32_16x16x32_bf16 v[122:125], v[146:149], v[170:173], v[122:125]
	v_mfma_f32_16x16x32_bf16 v[118:121], v[138:141], v[178:181], v[118:121]
	v_mfma_f32_16x16x32_bf16 v[110:113], v[146:149], v[178:181], v[110:113]
	v_mfma_f32_16x16x32_bf16 v[102:105], v[138:141], v[186:189], v[102:105]
	v_mfma_f32_16x16x32_bf16 v[94:97], v[146:149], v[186:189], v[94:97]
	v_mfma_f32_16x16x32_bf16 v[86:89], v[138:141], v[194:197], v[86:89]
	v_mfma_f32_16x16x32_bf16 v[78:81], v[146:149], v[194:197], v[78:81]
	v_mfma_f32_16x16x32_bf16 v[126:129], v[142:145], v[174:177], v[126:129]
	v_mfma_f32_16x16x32_bf16 v[122:125], v[150:153], v[174:177], v[122:125]
	v_mfma_f32_16x16x32_bf16 v[118:121], v[142:145], v[182:185], v[118:121]
	v_mfma_f32_16x16x32_bf16 v[110:113], v[150:153], v[182:185], v[110:113]
	v_mfma_f32_16x16x32_bf16 v[102:105], v[142:145], v[190:193], v[102:105]
	v_mfma_f32_16x16x32_bf16 v[94:97], v[150:153], v[190:193], v[94:97]
	v_mfma_f32_16x16x32_bf16 v[86:89], v[142:145], v[198:201], v[86:89]
	v_mfma_f32_16x16x32_bf16 v[78:81], v[150:153], v[198:201], v[78:81]
	s_setprio 0
	s_setprio 1
	v_mfma_f32_16x16x32_bf16 v[114:117], v[154:157], v[170:173], v[114:117]
	v_mfma_f32_16x16x32_bf16 v[106:109], v[162:165], v[170:173], v[106:109]
	v_mfma_f32_16x16x32_bf16 v[98:101], v[154:157], v[178:181], v[98:101]
	v_mfma_f32_16x16x32_bf16 v[90:93], v[162:165], v[178:181], v[90:93]
	v_mfma_f32_16x16x32_bf16 v[82:85], v[154:157], v[186:189], v[82:85]
	v_mfma_f32_16x16x32_bf16 v[74:77], v[162:165], v[186:189], v[74:77]
	v_mfma_f32_16x16x32_bf16 v[70:73], v[154:157], v[194:197], v[70:73]
	v_mfma_f32_16x16x32_bf16 v[62:65], v[162:165], v[194:197], v[62:65]
	v_mfma_f32_16x16x32_bf16 v[114:117], v[158:161], v[174:177], v[114:117]
	v_mfma_f32_16x16x32_bf16 v[106:109], v[166:169], v[174:177], v[106:109]
	v_mfma_f32_16x16x32_bf16 v[98:101], v[158:161], v[182:185], v[98:101]
	v_mfma_f32_16x16x32_bf16 v[90:93], v[166:169], v[182:185], v[90:93]
	v_mfma_f32_16x16x32_bf16 v[82:85], v[158:161], v[190:193], v[82:85]
	v_mfma_f32_16x16x32_bf16 v[74:77], v[166:169], v[190:193], v[74:77]
	v_mfma_f32_16x16x32_bf16 v[70:73], v[158:161], v[198:201], v[70:73]
	v_mfma_f32_16x16x32_bf16 v[62:65], v[166:169], v[198:201], v[62:65]
	s_setprio 0
	s_barrier
	v_mov_b32_e32 v0, v131
	s_mov_b32 m0, s82
	ds_read_b128 v[170:173], v137 offset:16384
	ds_read_b128 v[174:177], v137 offset:17408
	ds_read_b128 v[178:181], v137 offset:18432
	ds_read_b128 v[182:185], v137 offset:19456
	ds_read_b128 v[186:189], v137 offset:20480
	ds_read_b128 v[190:193], v137 offset:21504
	ds_read_b128 v[194:197], v137 offset:22528
	ds_read_b128 v[198:201], v137 offset:23552
	s_nop 0
	global_load_lds_dwordx4 v0, s[46:47]
	v_mov_b32_e32 v0, v133
	s_mov_b32 m0, s76
	s_nop 0
	global_load_lds_dwordx4 v0, s[46:47]
	v_mov_b32_e32 v0, v131
	s_mov_b32 m0, s77
	s_nop 0
	global_load_lds_dwordx4 v0, s[58:59]
	v_mov_b32_e32 v0, v133
	s_mov_b32 m0, s75
	s_nop 0
	global_load_lds_dwordx4 v0, s[58:59]
	v_mov_b32_e32 v0, v130
	s_mov_b32 m0, s41
	s_nop 0
	global_load_lds_dwordx4 v0, s[22:23]
	v_mov_b32_e32 v0, v132
	s_mov_b32 m0, s42
	s_nop 0
	global_load_lds_dwordx4 v0, s[22:23]
	s_waitcnt vmcnt(8)
	s_waitcnt lgkmcnt(0)
	s_barrier
	s_setprio 1
	s_waitcnt lgkmcnt(0)
	v_mfma_f32_16x16x32_bf16 v[66:69], v[138:141], v[170:173], v[66:69]
	v_mfma_f32_16x16x32_bf16 v[58:61], v[146:149], v[170:173], v[58:61]
	v_mfma_f32_16x16x32_bf16 v[54:57], v[138:141], v[178:181], v[54:57]
	v_mfma_f32_16x16x32_bf16 v[46:49], v[146:149], v[178:181], v[46:49]
	v_mfma_f32_16x16x32_bf16 v[38:41], v[138:141], v[186:189], v[38:41]
	v_mfma_f32_16x16x32_bf16 v[30:33], v[146:149], v[186:189], v[30:33]
	v_mfma_f32_16x16x32_bf16 v[22:25], v[138:141], v[194:197], v[22:25]
	v_mfma_f32_16x16x32_bf16 v[14:17], v[146:149], v[194:197], v[14:17]
	v_mfma_f32_16x16x32_bf16 v[66:69], v[142:145], v[174:177], v[66:69]
	v_mfma_f32_16x16x32_bf16 v[58:61], v[150:153], v[174:177], v[58:61]
	v_mfma_f32_16x16x32_bf16 v[54:57], v[142:145], v[182:185], v[54:57]
	v_mfma_f32_16x16x32_bf16 v[46:49], v[150:153], v[182:185], v[46:49]
	v_mfma_f32_16x16x32_bf16 v[38:41], v[142:145], v[190:193], v[38:41]
	v_mfma_f32_16x16x32_bf16 v[30:33], v[150:153], v[190:193], v[30:33]
	v_mfma_f32_16x16x32_bf16 v[22:25], v[142:145], v[198:201], v[22:25]
	v_mfma_f32_16x16x32_bf16 v[14:17], v[150:153], v[198:201], v[14:17]
	s_setprio 0
	s_setprio 1
	v_mfma_f32_16x16x32_bf16 v[50:53], v[154:157], v[170:173], v[50:53]
	v_mfma_f32_16x16x32_bf16 v[42:45], v[162:165], v[170:173], v[42:45]
	v_mfma_f32_16x16x32_bf16 v[34:37], v[154:157], v[178:181], v[34:37]
	v_mfma_f32_16x16x32_bf16 v[26:29], v[162:165], v[178:181], v[26:29]
	v_mfma_f32_16x16x32_bf16 v[18:21], v[154:157], v[186:189], v[18:21]
	v_mfma_f32_16x16x32_bf16 v[10:13], v[162:165], v[186:189], v[10:13]
	v_mfma_f32_16x16x32_bf16 v[6:9], v[154:157], v[194:197], v[6:9]
	v_mfma_f32_16x16x32_bf16 v[2:5], v[162:165], v[194:197], v[2:5]
	v_mfma_f32_16x16x32_bf16 v[50:53], v[158:161], v[174:177], v[50:53]
	v_mfma_f32_16x16x32_bf16 v[42:45], v[166:169], v[174:177], v[42:45]
	v_mfma_f32_16x16x32_bf16 v[34:37], v[158:161], v[182:185], v[34:37]
	v_mfma_f32_16x16x32_bf16 v[26:29], v[166:169], v[182:185], v[26:29]
	v_mfma_f32_16x16x32_bf16 v[18:21], v[158:161], v[190:193], v[18:21]
	v_mfma_f32_16x16x32_bf16 v[10:13], v[166:169], v[190:193], v[10:13]
	v_mfma_f32_16x16x32_bf16 v[6:9], v[158:161], v[198:201], v[6:9]
	v_mfma_f32_16x16x32_bf16 v[2:5], v[166:169], v[198:201], v[2:5]
	s_setprio 0
	s_barrier
	v_add_u32_e32 v0, s74, v136
	ds_read_b128 v[138:141], v0
	ds_read_b128 v[142:145], v0 offset:1024
	ds_read_b128 v[146:149], v0 offset:2048
	ds_read_b128 v[150:153], v0 offset:3072
	v_add_u32_e32 v0, s71, v136
	ds_read_b128 v[154:157], v0
	ds_read_b128 v[158:161], v0 offset:1024
	ds_read_b128 v[162:165], v0 offset:2048
	ds_read_b128 v[166:169], v0 offset:3072
	v_mov_b32_e32 v0, v130
	s_mov_b32 m0, s43
	ds_read_b128 v[170:173], v137 offset:32768
	ds_read_b128 v[174:177], v137 offset:33792
	ds_read_b128 v[178:181], v137 offset:34816
	ds_read_b128 v[182:185], v137 offset:35840
	ds_read_b128 v[186:189], v137 offset:36864
	ds_read_b128 v[190:193], v137 offset:37888
	ds_read_b128 v[194:197], v137 offset:38912
	ds_read_b128 v[198:201], v137 offset:39936
	s_nop 0
	global_load_lds_dwordx4 v0, s[50:51]
	v_mov_b32_e32 v0, v132
	s_mov_b32 m0, s64
	s_nop 0
	global_load_lds_dwordx4 v0, s[50:51]
	s_waitcnt vmcnt(8)
	s_waitcnt lgkmcnt(0)
	s_barrier
	s_setprio 1
	s_waitcnt lgkmcnt(0)
	v_mfma_f32_16x16x32_bf16 v[126:129], v[138:141], v[170:173], v[126:129]
	v_mfma_f32_16x16x32_bf16 v[122:125], v[146:149], v[170:173], v[122:125]
	v_mfma_f32_16x16x32_bf16 v[118:121], v[138:141], v[178:181], v[118:121]
	v_mfma_f32_16x16x32_bf16 v[110:113], v[146:149], v[178:181], v[110:113]
	v_mfma_f32_16x16x32_bf16 v[102:105], v[138:141], v[186:189], v[102:105]
	v_mfma_f32_16x16x32_bf16 v[94:97], v[146:149], v[186:189], v[94:97]
	v_mfma_f32_16x16x32_bf16 v[86:89], v[138:141], v[194:197], v[86:89]
	v_mfma_f32_16x16x32_bf16 v[78:81], v[146:149], v[194:197], v[78:81]
	v_mfma_f32_16x16x32_bf16 v[126:129], v[142:145], v[174:177], v[126:129]
	v_mfma_f32_16x16x32_bf16 v[122:125], v[150:153], v[174:177], v[122:125]
	v_mfma_f32_16x16x32_bf16 v[118:121], v[142:145], v[182:185], v[118:121]
	v_mfma_f32_16x16x32_bf16 v[110:113], v[150:153], v[182:185], v[110:113]
	v_mfma_f32_16x16x32_bf16 v[102:105], v[142:145], v[190:193], v[102:105]
	v_mfma_f32_16x16x32_bf16 v[94:97], v[150:153], v[190:193], v[94:97]
	v_mfma_f32_16x16x32_bf16 v[86:89], v[142:145], v[198:201], v[86:89]
	v_mfma_f32_16x16x32_bf16 v[78:81], v[150:153], v[198:201], v[78:81]
	s_setprio 0
	s_setprio 1
	v_mfma_f32_16x16x32_bf16 v[114:117], v[154:157], v[170:173], v[114:117]
	v_mfma_f32_16x16x32_bf16 v[106:109], v[162:165], v[170:173], v[106:109]
	v_mfma_f32_16x16x32_bf16 v[98:101], v[154:157], v[178:181], v[98:101]
	v_mfma_f32_16x16x32_bf16 v[90:93], v[162:165], v[178:181], v[90:93]
	v_mfma_f32_16x16x32_bf16 v[82:85], v[154:157], v[186:189], v[82:85]
	v_mfma_f32_16x16x32_bf16 v[74:77], v[162:165], v[186:189], v[74:77]
	v_mfma_f32_16x16x32_bf16 v[70:73], v[154:157], v[194:197], v[70:73]
	v_mfma_f32_16x16x32_bf16 v[62:65], v[162:165], v[194:197], v[62:65]
	v_mfma_f32_16x16x32_bf16 v[114:117], v[158:161], v[174:177], v[114:117]
	v_mfma_f32_16x16x32_bf16 v[106:109], v[166:169], v[174:177], v[106:109]
	v_mfma_f32_16x16x32_bf16 v[98:101], v[158:161], v[182:185], v[98:101]
	v_mfma_f32_16x16x32_bf16 v[90:93], v[166:169], v[182:185], v[90:93]
	v_mfma_f32_16x16x32_bf16 v[82:85], v[158:161], v[190:193], v[82:85]
	v_mfma_f32_16x16x32_bf16 v[74:77], v[166:169], v[190:193], v[74:77]
	v_mfma_f32_16x16x32_bf16 v[70:73], v[158:161], v[198:201], v[70:73]
	v_mfma_f32_16x16x32_bf16 v[62:65], v[166:169], v[198:201], v[62:65]
	s_setprio 0
	s_barrier
	v_mov_b32_e32 v0, v131
	ds_read_b128 v[170:173], v137 offset:49152
	ds_read_b128 v[174:177], v137 offset:50176
	ds_read_b128 v[178:181], v137 offset:51200
	ds_read_b128 v[182:185], v137 offset:52224
	ds_read_b128 v[186:189], v137 offset:53248
	ds_read_b128 v[190:193], v137 offset:54272
	ds_read_b128 v[194:197], v137 offset:55296
	ds_read_b128 v[198:201], v137 offset:56320
	s_mov_b32 m0, s70
	s_add_u32 s100, s46, s38
	s_addc_u32 s101, s47, s39
	v_mov_b32_e32 v0, v133
	global_load_lds_dwordx4 v131, s[100:101]
	s_mov_b32 m0, s69
	v_mov_b32_e32 v0, v131
	global_load_lds_dwordx4 v133, s[100:101]
	s_mov_b32 m0, s79
	s_nop 0
	global_load_lds_dwordx4 v0, s[48:49]
	v_mov_b32_e32 v0, v133
	s_mov_b32 m0, s78
	s_nop 0
	global_load_lds_dwordx4 v0, s[48:49]
	v_mov_b32_e32 v0, v130
	s_mov_b32 m0, s67
	s_add_u32 s100, s22, s38
	s_addc_u32 s101, s23, s39
	v_mov_b32_e32 v0, v132
	global_load_lds_dwordx4 v130, s[100:101]
	s_mov_b32 m0, s68
	s_nop 0
	global_load_lds_dwordx4 v132, s[100:101]
	s_waitcnt vmcnt(8)
	s_waitcnt lgkmcnt(0)
	s_barrier
	s_setprio 1
	s_waitcnt lgkmcnt(0)
	v_mfma_f32_16x16x32_bf16 v[66:69], v[138:141], v[170:173], v[66:69]
	v_mfma_f32_16x16x32_bf16 v[58:61], v[146:149], v[170:173], v[58:61]
	v_mfma_f32_16x16x32_bf16 v[54:57], v[138:141], v[178:181], v[54:57]
	v_mfma_f32_16x16x32_bf16 v[46:49], v[146:149], v[178:181], v[46:49]
	v_mfma_f32_16x16x32_bf16 v[38:41], v[138:141], v[186:189], v[38:41]
	v_mfma_f32_16x16x32_bf16 v[30:33], v[146:149], v[186:189], v[30:33]
	v_mfma_f32_16x16x32_bf16 v[22:25], v[138:141], v[194:197], v[22:25]
	v_mfma_f32_16x16x32_bf16 v[14:17], v[146:149], v[194:197], v[14:17]
	v_mfma_f32_16x16x32_bf16 v[66:69], v[142:145], v[174:177], v[66:69]
	v_mfma_f32_16x16x32_bf16 v[58:61], v[150:153], v[174:177], v[58:61]
	v_mfma_f32_16x16x32_bf16 v[54:57], v[142:145], v[182:185], v[54:57]
	v_mfma_f32_16x16x32_bf16 v[46:49], v[150:153], v[182:185], v[46:49]
	v_mfma_f32_16x16x32_bf16 v[38:41], v[142:145], v[190:193], v[38:41]
	v_mfma_f32_16x16x32_bf16 v[30:33], v[150:153], v[190:193], v[30:33]
	v_mfma_f32_16x16x32_bf16 v[22:25], v[142:145], v[198:201], v[22:25]
	v_mfma_f32_16x16x32_bf16 v[14:17], v[150:153], v[198:201], v[14:17]
	s_setprio 0
	s_setprio 1
	v_mfma_f32_16x16x32_bf16 v[50:53], v[154:157], v[170:173], v[50:53]
	v_mfma_f32_16x16x32_bf16 v[42:45], v[162:165], v[170:173], v[42:45]
	v_mfma_f32_16x16x32_bf16 v[34:37], v[154:157], v[178:181], v[34:37]
	v_mfma_f32_16x16x32_bf16 v[26:29], v[162:165], v[178:181], v[26:29]
	v_mfma_f32_16x16x32_bf16 v[18:21], v[154:157], v[186:189], v[18:21]
	v_mfma_f32_16x16x32_bf16 v[10:13], v[162:165], v[186:189], v[10:13]
	v_mfma_f32_16x16x32_bf16 v[6:9], v[154:157], v[194:197], v[6:9]
	v_mfma_f32_16x16x32_bf16 v[2:5], v[162:165], v[194:197], v[2:5]
	v_mfma_f32_16x16x32_bf16 v[50:53], v[158:161], v[174:177], v[50:53]
	v_mfma_f32_16x16x32_bf16 v[42:45], v[166:169], v[174:177], v[42:45]
	v_mfma_f32_16x16x32_bf16 v[34:37], v[158:161], v[182:185], v[34:37]
	v_mfma_f32_16x16x32_bf16 v[26:29], v[166:169], v[182:185], v[26:29]
	v_mfma_f32_16x16x32_bf16 v[18:21], v[158:161], v[190:193], v[18:21]
	v_mfma_f32_16x16x32_bf16 v[10:13], v[166:169], v[190:193], v[10:13]
	v_mfma_f32_16x16x32_bf16 v[6:9], v[158:161], v[198:201], v[6:9]
	v_mfma_f32_16x16x32_bf16 v[2:5], v[166:169], v[198:201], v[2:5]
	s_setprio 0
	s_barrier
	s_andn2_b64 vcc, exec, s[16:17]
	s_mov_b64 s[46:47], -1
	s_mov_b64 s[16:17], 0
	s_mov_b64 s[48:49], 0x100
	s_cbranch_vccz .LBB0_634
	s_cmpk_lt_u32 s25, 0x100
	s_cbranch_scc0 .LBB0_637
	s_barrier

.LBB0_667:
	s_add_u32 s4, s70, s50
	s_addc_u32 s5, s71, s51
	s_add_u32 s46, s4, 0x9400100
	s_addc_u32 s47, s5, 0
	s_add_u32 s58, s74, s50
	s_addc_u32 s59, s75, s51
	s_add_i32 s77, 0, 0x10000
	s_cmpk_eq_i32 s50, 0x300
	s_cselect_b32 s47, s23, s47
	s_cselect_b32 s46, s22, s46
	v_add_u32_e32 v0, s77, v144
	s_cselect_b32 s59, s49, s59
	s_cselect_b32 s58, s48, s58
	s_add_i32 s78, 0, 0x14000
	ds_read_b128 v[146:149], v0
	ds_read_b128 v[150:153], v0 offset:1024
	ds_read_b128 v[154:157], v0 offset:2048
	ds_read_b128 v[158:161], v0 offset:3072
	v_add_u32_e32 v0, s78, v144
	ds_read_b128 v[162:165], v0
	ds_read_b128 v[166:169], v0 offset:1024
	ds_read_b128 v[170:173], v0 offset:2048
	ds_read_b128 v[174:177], v0 offset:3072
	v_mov_b32_e32 v0, v130
	ds_read_b128 v[178:181], v145
	ds_read_b128 v[182:185], v145 offset:1024
	ds_read_b128 v[186:189], v145 offset:2048
	ds_read_b128 v[190:193], v145 offset:3072
	ds_read_b128 v[194:197], v145 offset:4096
	ds_read_b128 v[198:201], v145 offset:5120
	ds_read_b128 v[202:205], v145 offset:6144
	ds_read_b128 v[206:209], v145 offset:7168
	s_add_i32 m0, s61, 0xc000
	s_add_u32 s100, s4, s54
	s_addc_u32 s101, s5, s55
	v_mov_b32_e32 v0, v141
	global_load_lds_dwordx4 v130, s[100:101]
	s_add_i32 m0, s61, 0xe000
	s_nop 0
	global_load_lds_dwordx4 v141, s[100:101]
	s_waitcnt vmcnt(8)
	s_waitcnt lgkmcnt(0)
	s_barrier
	s_setprio 1
	s_waitcnt lgkmcnt(0)
	v_mfma_i32_16x16x64_i8 v[126:129], v[146:149], v[178:181], v[126:129]
	v_mfma_i32_16x16x64_i8 v[122:125], v[154:157], v[178:181], v[122:125]
	v_mfma_i32_16x16x64_i8 v[110:113], v[146:149], v[186:189], v[110:113]
	v_mfma_i32_16x16x64_i8 v[106:109], v[154:157], v[186:189], v[106:109]
	v_mfma_i32_16x16x64_i8 v[94:97], v[146:149], v[194:197], v[94:97]
	v_mfma_i32_16x16x64_i8 v[90:93], v[154:157], v[194:197], v[90:93]
	v_mfma_i32_16x16x64_i8 v[78:81], v[146:149], v[202:205], v[78:81]
	v_mfma_i32_16x16x64_i8 v[74:77], v[154:157], v[202:205], v[74:77]
	v_mfma_i32_16x16x64_i8 v[126:129], v[150:153], v[182:185], v[126:129]
	v_mfma_i32_16x16x64_i8 v[122:125], v[158:161], v[182:185], v[122:125]
	v_mfma_i32_16x16x64_i8 v[110:113], v[150:153], v[190:193], v[110:113]
	v_mfma_i32_16x16x64_i8 v[106:109], v[158:161], v[190:193], v[106:109]
	v_mfma_i32_16x16x64_i8 v[94:97], v[150:153], v[198:201], v[94:97]
	v_mfma_i32_16x16x64_i8 v[90:93], v[158:161], v[198:201], v[90:93]
	v_mfma_i32_16x16x64_i8 v[78:81], v[150:153], v[206:209], v[78:81]
	v_mfma_i32_16x16x64_i8 v[74:77], v[158:161], v[206:209], v[74:77]
	s_setprio 0
	s_setprio 1
	v_mfma_i32_16x16x64_i8 v[118:121], v[162:165], v[178:181], v[118:121]
	v_mfma_i32_16x16x64_i8 v[114:117], v[170:173], v[178:181], v[114:117]
	v_mfma_i32_16x16x64_i8 v[102:105], v[162:165], v[186:189], v[102:105]
	v_mfma_i32_16x16x64_i8 v[98:101], v[170:173], v[186:189], v[98:101]
	v_mfma_i32_16x16x64_i8 v[86:89], v[162:165], v[194:197], v[86:89]
	v_mfma_i32_16x16x64_i8 v[82:85], v[170:173], v[194:197], v[82:85]
	v_mfma_i32_16x16x64_i8 v[70:73], v[162:165], v[202:205], v[70:73]
	v_mfma_i32_16x16x64_i8 v[66:69], v[170:173], v[202:205], v[66:69]
	v_mfma_i32_16x16x64_i8 v[118:121], v[166:169], v[182:185], v[118:121]
	v_mfma_i32_16x16x64_i8 v[114:117], v[174:177], v[182:185], v[114:117]
	v_mfma_i32_16x16x64_i8 v[102:105], v[166:169], v[190:193], v[102:105]
	v_mfma_i32_16x16x64_i8 v[98:101], v[174:177], v[190:193], v[98:101]
	v_mfma_i32_16x16x64_i8 v[86:89], v[166:169], v[198:201], v[86:89]
	v_mfma_i32_16x16x64_i8 v[82:85], v[174:177], v[198:201], v[82:85]
	v_mfma_i32_16x16x64_i8 v[70:73], v[166:169], v[206:209], v[70:73]
	v_mfma_i32_16x16x64_i8 v[66:69], v[174:177], v[206:209], v[66:69]
	s_setprio 0
	s_barrier
	v_mov_b32_e32 v0, v131
	s_add_i32 s4, s77, s60
	ds_read_b128 v[178:181], v145 offset:16384
	ds_read_b128 v[182:185], v145 offset:17408
	ds_read_b128 v[186:189], v145 offset:18432
	ds_read_b128 v[190:193], v145 offset:19456
	ds_read_b128 v[194:197], v145 offset:20480
	ds_read_b128 v[198:201], v145 offset:21504
	ds_read_b128 v[202:205], v145 offset:22528
	ds_read_b128 v[206:209], v145 offset:23552
	s_mov_b32 m0, s4
	s_nop 0
	global_load_lds_dwordx4 v0, s[58:59]
	v_mov_b32_e32 v0, v142
	s_add_i32 m0, s4, 0x2000
	s_add_u32 s4, s58, 0x20000
	global_load_lds_dwordx4 v0, s[58:59]
	s_addc_u32 s5, s59, 0
	v_mov_b32_e32 v0, v131
	s_add_i32 s77, s78, s60
	s_mov_b32 m0, s77
	s_nop 0
	global_load_lds_dwordx4 v0, s[4:5]
	v_mov_b32_e32 v0, v142
	s_add_i32 m0, s77, 0x2000
	s_nop 0
	global_load_lds_dwordx4 v0, s[4:5]
	v_mov_b32_e32 v0, v130
	s_mov_b32 m0, s61
	s_nop 0
	global_load_lds_dwordx4 v0, s[46:47]
	v_mov_b32_e32 v0, v141
	s_mov_b32 m0, s65
	s_nop 0
	global_load_lds_dwordx4 v0, s[46:47]
	s_waitcnt vmcnt(8)
	s_waitcnt lgkmcnt(0)
	s_barrier
	s_setprio 1
	s_waitcnt lgkmcnt(0)
	v_mfma_i32_16x16x64_i8 v[62:65], v[146:149], v[178:181], v[62:65]
	v_mfma_i32_16x16x64_i8 v[58:61], v[154:157], v[178:181], v[58:61]
	v_mfma_i32_16x16x64_i8 v[46:49], v[146:149], v[186:189], v[46:49]
	v_mfma_i32_16x16x64_i8 v[42:45], v[154:157], v[186:189], v[42:45]
	v_mfma_i32_16x16x64_i8 v[30:33], v[146:149], v[194:197], v[30:33]
	v_mfma_i32_16x16x64_i8 v[26:29], v[154:157], v[194:197], v[26:29]
	v_mfma_i32_16x16x64_i8 v[14:17], v[146:149], v[202:205], v[14:17]
	v_mfma_i32_16x16x64_i8 v[10:13], v[154:157], v[202:205], v[10:13]
	v_mfma_i32_16x16x64_i8 v[62:65], v[150:153], v[182:185], v[62:65]
	v_mfma_i32_16x16x64_i8 v[58:61], v[158:161], v[182:185], v[58:61]
	v_mfma_i32_16x16x64_i8 v[46:49], v[150:153], v[190:193], v[46:49]
	v_mfma_i32_16x16x64_i8 v[42:45], v[158:161], v[190:193], v[42:45]
	v_mfma_i32_16x16x64_i8 v[30:33], v[150:153], v[198:201], v[30:33]
	v_mfma_i32_16x16x64_i8 v[26:29], v[158:161], v[198:201], v[26:29]
	v_mfma_i32_16x16x64_i8 v[14:17], v[150:153], v[206:209], v[14:17]
	v_mfma_i32_16x16x64_i8 v[10:13], v[158:161], v[206:209], v[10:13]
	s_setprio 0
	s_setprio 1
	v_mfma_i32_16x16x64_i8 v[54:57], v[162:165], v[178:181], v[54:57]
	v_mfma_i32_16x16x64_i8 v[50:53], v[170:173], v[178:181], v[50:53]
	v_mfma_i32_16x16x64_i8 v[38:41], v[162:165], v[186:189], v[38:41]
	v_mfma_i32_16x16x64_i8 v[34:37], v[170:173], v[186:189], v[34:37]
	v_mfma_i32_16x16x64_i8 v[22:25], v[162:165], v[194:197], v[22:25]
	v_mfma_i32_16x16x64_i8 v[18:21], v[170:173], v[194:197], v[18:21]
	v_mfma_i32_16x16x64_i8 v[6:9], v[162:165], v[202:205], v[6:9]
	v_mfma_i32_16x16x64_i8 v[2:5], v[170:173], v[202:205], v[2:5]
	v_mfma_i32_16x16x64_i8 v[54:57], v[166:169], v[182:185], v[54:57]
	v_mfma_i32_16x16x64_i8 v[50:53], v[174:177], v[182:185], v[50:53]
	v_mfma_i32_16x16x64_i8 v[38:41], v[166:169], v[190:193], v[38:41]
	v_mfma_i32_16x16x64_i8 v[34:37], v[174:177], v[190:193], v[34:37]
	v_mfma_i32_16x16x64_i8 v[22:25], v[166:169], v[198:201], v[22:25]
	v_mfma_i32_16x16x64_i8 v[18:21], v[174:177], v[198:201], v[18:21]
	v_mfma_i32_16x16x64_i8 v[6:9], v[166:169], v[206:209], v[6:9]
	v_mfma_i32_16x16x64_i8 v[2:5], v[174:177], v[206:209], v[2:5]
	s_setprio 0
	s_barrier
	s_add_i32 s77, 0, 0x18000
	v_add_u32_e32 v0, s77, v144
	s_add_i32 s78, 0, 0x1c000
	ds_read_b128 v[146:149], v0
	ds_read_b128 v[150:153], v0 offset:1024
	ds_read_b128 v[154:157], v0 offset:2048
	ds_read_b128 v[158:161], v0 offset:3072
	v_add_u32_e32 v0, s78, v144
	ds_read_b128 v[162:165], v0
	ds_read_b128 v[166:169], v0 offset:1024
	ds_read_b128 v[170:173], v0 offset:2048
	ds_read_b128 v[174:177], v0 offset:3072
	s_add_u32 s4, s46, 0x20000
	v_mov_b32_e32 v0, v130
	s_mov_b32 m0, s66
	ds_read_b128 v[178:181], v145 offset:32768
	ds_read_b128 v[182:185], v145 offset:33792
	ds_read_b128 v[186:189], v145 offset:34816
	ds_read_b128 v[190:193], v145 offset:35840
	ds_read_b128 v[194:197], v145 offset:36864
	ds_read_b128 v[198:201], v145 offset:37888
	ds_read_b128 v[202:205], v145 offset:38912
	ds_read_b128 v[206:209], v145 offset:39936
	s_addc_u32 s5, s47, 0
	s_nop 0
	global_load_lds_dwordx4 v0, s[4:5]
	v_mov_b32_e32 v0, v141
	s_mov_b32 m0, s67
	s_nop 0
	global_load_lds_dwordx4 v0, s[4:5]
	s_waitcnt vmcnt(8)
	s_waitcnt lgkmcnt(0)
	s_barrier
	s_setprio 1
	s_waitcnt lgkmcnt(0)
	v_mfma_i32_16x16x64_i8 v[126:129], v[146:149], v[178:181], v[126:129]
	v_mfma_i32_16x16x64_i8 v[122:125], v[154:157], v[178:181], v[122:125]
	v_mfma_i32_16x16x64_i8 v[110:113], v[146:149], v[186:189], v[110:113]
	v_mfma_i32_16x16x64_i8 v[106:109], v[154:157], v[186:189], v[106:109]
	v_mfma_i32_16x16x64_i8 v[94:97], v[146:149], v[194:197], v[94:97]
	v_mfma_i32_16x16x64_i8 v[90:93], v[154:157], v[194:197], v[90:93]
	v_mfma_i32_16x16x64_i8 v[78:81], v[146:149], v[202:205], v[78:81]
	v_mfma_i32_16x16x64_i8 v[74:77], v[154:157], v[202:205], v[74:77]
	v_mfma_i32_16x16x64_i8 v[126:129], v[150:153], v[182:185], v[126:129]
	v_mfma_i32_16x16x64_i8 v[122:125], v[158:161], v[182:185], v[122:125]
	v_mfma_i32_16x16x64_i8 v[110:113], v[150:153], v[190:193], v[110:113]
	v_mfma_i32_16x16x64_i8 v[106:109], v[158:161], v[190:193], v[106:109]
	v_mfma_i32_16x16x64_i8 v[94:97], v[150:153], v[198:201], v[94:97]
	v_mfma_i32_16x16x64_i8 v[90:93], v[158:161], v[198:201], v[90:93]
	v_mfma_i32_16x16x64_i8 v[78:81], v[150:153], v[206:209], v[78:81]
	v_mfma_i32_16x16x64_i8 v[74:77], v[158:161], v[206:209], v[74:77]
	s_setprio 0
	s_setprio 1
	v_mfma_i32_16x16x64_i8 v[118:121], v[162:165], v[178:181], v[118:121]
	v_mfma_i32_16x16x64_i8 v[114:117], v[170:173], v[178:181], v[114:117]
	v_mfma_i32_16x16x64_i8 v[102:105], v[162:165], v[186:189], v[102:105]
	v_mfma_i32_16x16x64_i8 v[98:101], v[170:173], v[186:189], v[98:101]
	v_mfma_i32_16x16x64_i8 v[86:89], v[162:165], v[194:197], v[86:89]
	v_mfma_i32_16x16x64_i8 v[82:85], v[170:173], v[194:197], v[82:85]
	v_mfma_i32_16x16x64_i8 v[70:73], v[162:165], v[202:205], v[70:73]
	v_mfma_i32_16x16x64_i8 v[66:69], v[170:173], v[202:205], v[66:69]
	v_mfma_i32_16x16x64_i8 v[118:121], v[166:169], v[182:185], v[118:121]
	v_mfma_i32_16x16x64_i8 v[114:117], v[174:177], v[182:185], v[114:117]
	v_mfma_i32_16x16x64_i8 v[102:105], v[166:169], v[190:193], v[102:105]
	v_mfma_i32_16x16x64_i8 v[98:101], v[174:177], v[190:193], v[98:101]
	v_mfma_i32_16x16x64_i8 v[86:89], v[166:169], v[198:201], v[86:89]
	v_mfma_i32_16x16x64_i8 v[82:85], v[174:177], v[198:201], v[82:85]
	v_mfma_i32_16x16x64_i8 v[70:73], v[166:169], v[206:209], v[70:73]
	v_mfma_i32_16x16x64_i8 v[66:69], v[174:177], v[206:209], v[66:69]
	s_setprio 0
	s_barrier
	v_mov_b32_e32 v0, v131
	ds_read_b128 v[178:181], v145 offset:49152
	ds_read_b128 v[182:185], v145 offset:50176
	ds_read_b128 v[186:189], v145 offset:51200
	ds_read_b128 v[190:193], v145 offset:52224
	ds_read_b128 v[194:197], v145 offset:53248
	ds_read_b128 v[198:201], v145 offset:54272
	ds_read_b128 v[202:205], v145 offset:55296
	ds_read_b128 v[206:209], v145 offset:56320
	s_add_i32 s4, s77, s60
	s_add_u32 s100, s58, s38
	s_addc_u32 s101, s59, s39
	s_mov_b32 m0, s4
	v_mov_b32_e32 v0, v142
	global_load_lds_dwordx4 v131, s[100:101]
	s_add_i32 m0, s4, 0x2000
	s_add_u32 s4, s58, 0x20080
	s_addc_u32 s5, s59, 0
	v_mov_b32_e32 v0, v131
	s_add_i32 s58, s78, s60
	global_load_lds_dwordx4 v142, s[100:101]
	s_mov_b32 m0, s58
	s_nop 0
	global_load_lds_dwordx4 v0, s[4:5]
	v_mov_b32_e32 v0, v142
	s_add_i32 m0, s58, 0x2000
	s_nop 0
	global_load_lds_dwordx4 v0, s[4:5]
	v_mov_b32_e32 v0, v130
	s_mov_b32 m0, s68
	s_add_u32 s100, s46, s38
	s_addc_u32 s101, s47, s39
	v_mov_b32_e32 v0, v141
	global_load_lds_dwordx4 v130, s[100:101]
	s_mov_b32 m0, s69
	s_nop 0
	global_load_lds_dwordx4 v141, s[100:101]
	s_waitcnt vmcnt(8)
	s_waitcnt lgkmcnt(0)
	s_barrier
	s_setprio 1
	s_waitcnt lgkmcnt(0)
	v_mfma_i32_16x16x64_i8 v[62:65], v[146:149], v[178:181], v[62:65]
	v_mfma_i32_16x16x64_i8 v[58:61], v[154:157], v[178:181], v[58:61]
	v_mfma_i32_16x16x64_i8 v[46:49], v[146:149], v[186:189], v[46:49]
	v_mfma_i32_16x16x64_i8 v[42:45], v[154:157], v[186:189], v[42:45]
	v_mfma_i32_16x16x64_i8 v[30:33], v[146:149], v[194:197], v[30:33]
	v_mfma_i32_16x16x64_i8 v[26:29], v[154:157], v[194:197], v[26:29]
	v_mfma_i32_16x16x64_i8 v[14:17], v[146:149], v[202:205], v[14:17]
	v_mfma_i32_16x16x64_i8 v[10:13], v[154:157], v[202:205], v[10:13]
	v_mfma_i32_16x16x64_i8 v[62:65], v[150:153], v[182:185], v[62:65]
	v_mfma_i32_16x16x64_i8 v[58:61], v[158:161], v[182:185], v[58:61]
	v_mfma_i32_16x16x64_i8 v[46:49], v[150:153], v[190:193], v[46:49]
	v_mfma_i32_16x16x64_i8 v[42:45], v[158:161], v[190:193], v[42:45]
	v_mfma_i32_16x16x64_i8 v[30:33], v[150:153], v[198:201], v[30:33]
	v_mfma_i32_16x16x64_i8 v[26:29], v[158:161], v[198:201], v[26:29]
	v_mfma_i32_16x16x64_i8 v[14:17], v[150:153], v[206:209], v[14:17]
	v_mfma_i32_16x16x64_i8 v[10:13], v[158:161], v[206:209], v[10:13]
	s_setprio 0
	s_setprio 1
	v_mfma_i32_16x16x64_i8 v[54:57], v[162:165], v[178:181], v[54:57]
	v_mfma_i32_16x16x64_i8 v[50:53], v[170:173], v[178:181], v[50:53]
	v_mfma_i32_16x16x64_i8 v[38:41], v[162:165], v[186:189], v[38:41]
	v_mfma_i32_16x16x64_i8 v[34:37], v[170:173], v[186:189], v[34:37]
	v_mfma_i32_16x16x64_i8 v[22:25], v[162:165], v[194:197], v[22:25]
	v_mfma_i32_16x16x64_i8 v[18:21], v[170:173], v[194:197], v[18:21]
	v_mfma_i32_16x16x64_i8 v[6:9], v[162:165], v[202:205], v[6:9]
	v_mfma_i32_16x16x64_i8 v[2:5], v[170:173], v[202:205], v[2:5]
	v_mfma_i32_16x16x64_i8 v[54:57], v[166:169], v[182:185], v[54:57]
	v_mfma_i32_16x16x64_i8 v[50:53], v[174:177], v[182:185], v[50:53]
	v_mfma_i32_16x16x64_i8 v[38:41], v[166:169], v[190:193], v[38:41]
	v_mfma_i32_16x16x64_i8 v[34:37], v[174:177], v[190:193], v[34:37]
	v_mfma_i32_16x16x64_i8 v[22:25], v[166:169], v[198:201], v[22:25]
	v_mfma_i32_16x16x64_i8 v[18:21], v[174:177], v[198:201], v[18:21]
	v_mfma_i32_16x16x64_i8 v[6:9], v[166:169], v[206:209], v[6:9]
	v_mfma_i32_16x16x64_i8 v[2:5], v[174:177], v[206:209], v[2:5]
	s_setprio 0
	s_barrier
	s_add_i32 s76, s76, 2
	s_add_u32 s50, s50, 0x100
	s_addc_u32 s51, s51, 0
	s_cmp_gt_u32 s76, 5
	s_cbranch_scc0 .LBB0_667
	s_cmpk_lt_u32 s17, 0x100
	s_cbranch_scc0 .LBB0_661
	s_barrier
	s_branch .LBB0_661

.LBB0_821:
	s_add_u32 s4, s79, s50
	s_addc_u32 s5, s82, s51
	s_add_u32 s46, s4, 0x9800100
	s_addc_u32 s47, s5, 0
	s_add_u32 s58, s64, s50
	s_addc_u32 s59, s83, s51
	s_add_i32 s85, 0, 0x10000
	s_cmpk_eq_i32 s50, 0x1500
	s_cselect_b32 s47, s49, s47
	s_cselect_b32 s46, s48, s46
	v_add_u32_e32 v0, s85, v134
	s_cselect_b32 s59, s71, s59
	s_cselect_b32 s58, s70, s58
	s_add_i32 s86, 0, 0x14000
	ds_read_b128 v[136:139], v0
	ds_read_b128 v[140:143], v0 offset:1024
	ds_read_b128 v[144:147], v0 offset:2048
	ds_read_b128 v[148:151], v0 offset:3072
	v_add_u32_e32 v0, s86, v134
	ds_read_b128 v[152:155], v0
	ds_read_b128 v[156:159], v0 offset:1024
	ds_read_b128 v[160:163], v0 offset:2048
	ds_read_b128 v[164:167], v0 offset:3072
	v_mov_b32_e32 v0, v130
	ds_read_b128 v[168:171], v135
	ds_read_b128 v[172:175], v135 offset:1024
	ds_read_b128 v[176:179], v135 offset:2048
	ds_read_b128 v[180:183], v135 offset:3072
	ds_read_b128 v[184:187], v135 offset:4096
	ds_read_b128 v[188:191], v135 offset:5120
	ds_read_b128 v[192:195], v135 offset:6144
	ds_read_b128 v[198:201], v135 offset:7168
	s_add_i32 m0, s60, 0xc000
	s_add_u32 s100, s4, s88
	s_addc_u32 s101, s5, s89
	v_mov_b32_e32 v0, v131
	global_load_lds_dwordx4 v130, s[100:101]
	s_add_i32 m0, s60, 0xe000
	s_nop 0
	global_load_lds_dwordx4 v131, s[100:101]
	s_waitcnt vmcnt(8)
	s_waitcnt lgkmcnt(0)
	s_barrier
	s_setprio 1
	s_waitcnt lgkmcnt(0)
	v_mfma_f32_16x16x32_bf16 v[126:129], v[136:139], v[168:171], v[126:129]
	v_mfma_f32_16x16x32_bf16 v[122:125], v[144:147], v[168:171], v[122:125]
	v_mfma_f32_16x16x32_bf16 v[110:113], v[136:139], v[176:179], v[110:113]
	v_mfma_f32_16x16x32_bf16 v[106:109], v[144:147], v[176:179], v[106:109]
	v_mfma_f32_16x16x32_bf16 v[94:97], v[136:139], v[184:187], v[94:97]
	v_mfma_f32_16x16x32_bf16 v[90:93], v[144:147], v[184:187], v[90:93]
	v_mfma_f32_16x16x32_bf16 v[78:81], v[136:139], v[192:195], v[78:81]
	v_mfma_f32_16x16x32_bf16 v[74:77], v[144:147], v[192:195], v[74:77]
	v_mfma_f32_16x16x32_bf16 v[126:129], v[140:143], v[172:175], v[126:129]
	v_mfma_f32_16x16x32_bf16 v[122:125], v[148:151], v[172:175], v[122:125]
	v_mfma_f32_16x16x32_bf16 v[110:113], v[140:143], v[180:183], v[110:113]
	v_mfma_f32_16x16x32_bf16 v[106:109], v[148:151], v[180:183], v[106:109]
	v_mfma_f32_16x16x32_bf16 v[94:97], v[140:143], v[188:191], v[94:97]
	v_mfma_f32_16x16x32_bf16 v[90:93], v[148:151], v[188:191], v[90:93]
	v_mfma_f32_16x16x32_bf16 v[78:81], v[140:143], v[198:201], v[78:81]
	v_mfma_f32_16x16x32_bf16 v[74:77], v[148:151], v[198:201], v[74:77]
	s_setprio 0
	s_setprio 1
	v_mfma_f32_16x16x32_bf16 v[118:121], v[152:155], v[168:171], v[118:121]
	v_mfma_f32_16x16x32_bf16 v[114:117], v[160:163], v[168:171], v[114:117]
	v_mfma_f32_16x16x32_bf16 v[102:105], v[152:155], v[176:179], v[102:105]
	v_mfma_f32_16x16x32_bf16 v[98:101], v[160:163], v[176:179], v[98:101]
	v_mfma_f32_16x16x32_bf16 v[86:89], v[152:155], v[184:187], v[86:89]
	v_mfma_f32_16x16x32_bf16 v[82:85], v[160:163], v[184:187], v[82:85]
	v_mfma_f32_16x16x32_bf16 v[70:73], v[152:155], v[192:195], v[70:73]
	v_mfma_f32_16x16x32_bf16 v[66:69], v[160:163], v[192:195], v[66:69]
	v_mfma_f32_16x16x32_bf16 v[118:121], v[156:159], v[172:175], v[118:121]
	v_mfma_f32_16x16x32_bf16 v[114:117], v[164:167], v[172:175], v[114:117]
	v_mfma_f32_16x16x32_bf16 v[102:105], v[156:159], v[180:183], v[102:105]
	v_mfma_f32_16x16x32_bf16 v[98:101], v[164:167], v[180:183], v[98:101]
	v_mfma_f32_16x16x32_bf16 v[86:89], v[156:159], v[188:191], v[86:89]
	v_mfma_f32_16x16x32_bf16 v[82:85], v[164:167], v[188:191], v[82:85]
	v_mfma_f32_16x16x32_bf16 v[70:73], v[156:159], v[198:201], v[70:73]
	v_mfma_f32_16x16x32_bf16 v[66:69], v[164:167], v[198:201], v[66:69]
	s_setprio 0
	s_barrier
	v_mov_b32_e32 v0, v132
	s_add_i32 s4, s85, s26
	ds_read_b128 v[168:171], v135 offset:16384
	ds_read_b128 v[172:175], v135 offset:17408
	ds_read_b128 v[176:179], v135 offset:18432
	ds_read_b128 v[180:183], v135 offset:19456
	ds_read_b128 v[184:187], v135 offset:20480
	ds_read_b128 v[188:191], v135 offset:21504
	ds_read_b128 v[192:195], v135 offset:22528
	ds_read_b128 v[198:201], v135 offset:23552
	s_mov_b32 m0, s4
	s_nop 0
	global_load_lds_dwordx4 v0, s[58:59]
	v_mov_b32_e32 v0, v133
	s_add_i32 m0, s4, 0x2000
	s_add_u32 s4, s58, 0xb0000
	global_load_lds_dwordx4 v0, s[58:59]
	s_addc_u32 s5, s59, 0
	v_mov_b32_e32 v0, v132
	s_add_i32 s85, s86, s26
	s_mov_b32 m0, s85
	s_nop 0
	global_load_lds_dwordx4 v0, s[4:5]
	v_mov_b32_e32 v0, v133
	s_add_i32 m0, s85, 0x2000
	s_nop 0
	global_load_lds_dwordx4 v0, s[4:5]
	v_mov_b32_e32 v0, v130
	s_mov_b32 m0, s60
	s_nop 0
	global_load_lds_dwordx4 v0, s[46:47]
	v_mov_b32_e32 v0, v131
	s_mov_b32 m0, s65
	s_nop 0
	global_load_lds_dwordx4 v0, s[46:47]
	s_waitcnt vmcnt(8)
	s_waitcnt lgkmcnt(0)
	s_barrier
	s_setprio 1
	s_waitcnt lgkmcnt(0)
	v_mfma_f32_16x16x32_bf16 v[62:65], v[136:139], v[168:171], v[62:65]
	v_mfma_f32_16x16x32_bf16 v[58:61], v[144:147], v[168:171], v[58:61]
	v_mfma_f32_16x16x32_bf16 v[46:49], v[136:139], v[176:179], v[46:49]
	v_mfma_f32_16x16x32_bf16 v[42:45], v[144:147], v[176:179], v[42:45]
	v_mfma_f32_16x16x32_bf16 v[30:33], v[136:139], v[184:187], v[30:33]
	v_mfma_f32_16x16x32_bf16 v[26:29], v[144:147], v[184:187], v[26:29]
	v_mfma_f32_16x16x32_bf16 v[14:17], v[136:139], v[192:195], v[14:17]
	v_mfma_f32_16x16x32_bf16 v[10:13], v[144:147], v[192:195], v[10:13]
	v_mfma_f32_16x16x32_bf16 v[62:65], v[140:143], v[172:175], v[62:65]
	v_mfma_f32_16x16x32_bf16 v[58:61], v[148:151], v[172:175], v[58:61]
	v_mfma_f32_16x16x32_bf16 v[46:49], v[140:143], v[180:183], v[46:49]
	v_mfma_f32_16x16x32_bf16 v[42:45], v[148:151], v[180:183], v[42:45]
	v_mfma_f32_16x16x32_bf16 v[30:33], v[140:143], v[188:191], v[30:33]
	v_mfma_f32_16x16x32_bf16 v[26:29], v[148:151], v[188:191], v[26:29]
	v_mfma_f32_16x16x32_bf16 v[14:17], v[140:143], v[198:201], v[14:17]
	v_mfma_f32_16x16x32_bf16 v[10:13], v[148:151], v[198:201], v[10:13]
	s_setprio 0
	s_setprio 1
	v_mfma_f32_16x16x32_bf16 v[54:57], v[152:155], v[168:171], v[54:57]
	v_mfma_f32_16x16x32_bf16 v[50:53], v[160:163], v[168:171], v[50:53]
	v_mfma_f32_16x16x32_bf16 v[38:41], v[152:155], v[176:179], v[38:41]
	v_mfma_f32_16x16x32_bf16 v[34:37], v[160:163], v[176:179], v[34:37]
	v_mfma_f32_16x16x32_bf16 v[22:25], v[152:155], v[184:187], v[22:25]
	v_mfma_f32_16x16x32_bf16 v[18:21], v[160:163], v[184:187], v[18:21]
	v_mfma_f32_16x16x32_bf16 v[6:9], v[152:155], v[192:195], v[6:9]
	v_mfma_f32_16x16x32_bf16 v[2:5], v[160:163], v[192:195], v[2:5]
	v_mfma_f32_16x16x32_bf16 v[54:57], v[156:159], v[172:175], v[54:57]
	v_mfma_f32_16x16x32_bf16 v[50:53], v[164:167], v[172:175], v[50:53]
	v_mfma_f32_16x16x32_bf16 v[38:41], v[156:159], v[180:183], v[38:41]
	v_mfma_f32_16x16x32_bf16 v[34:37], v[164:167], v[180:183], v[34:37]
	v_mfma_f32_16x16x32_bf16 v[22:25], v[156:159], v[188:191], v[22:25]
	v_mfma_f32_16x16x32_bf16 v[18:21], v[164:167], v[188:191], v[18:21]
	v_mfma_f32_16x16x32_bf16 v[6:9], v[156:159], v[198:201], v[6:9]
	v_mfma_f32_16x16x32_bf16 v[2:5], v[164:167], v[198:201], v[2:5]
	s_setprio 0
	s_barrier
	s_add_i32 s85, 0, 0x18000
	v_add_u32_e32 v0, s85, v134
	s_add_i32 s86, 0, 0x1c000
	ds_read_b128 v[136:139], v0
	ds_read_b128 v[140:143], v0 offset:1024
	ds_read_b128 v[144:147], v0 offset:2048
	ds_read_b128 v[148:151], v0 offset:3072
	v_add_u32_e32 v0, s86, v134
	ds_read_b128 v[152:155], v0
	ds_read_b128 v[156:159], v0 offset:1024
	ds_read_b128 v[160:163], v0 offset:2048
	ds_read_b128 v[164:167], v0 offset:3072
	s_add_u32 s4, s46, 0xb0000
	v_mov_b32_e32 v0, v130
	s_mov_b32 m0, s68
	ds_read_b128 v[168:171], v135 offset:32768
	ds_read_b128 v[172:175], v135 offset:33792
	ds_read_b128 v[176:179], v135 offset:34816
	ds_read_b128 v[180:183], v135 offset:35840
	ds_read_b128 v[184:187], v135 offset:36864
	ds_read_b128 v[188:191], v135 offset:37888
	ds_read_b128 v[192:195], v135 offset:38912
	ds_read_b128 v[198:201], v135 offset:39936
	s_addc_u32 s5, s47, 0
	s_nop 0
	global_load_lds_dwordx4 v0, s[4:5]
	v_mov_b32_e32 v0, v131
	s_mov_b32 m0, s69
	s_nop 0
	global_load_lds_dwordx4 v0, s[4:5]
	s_waitcnt vmcnt(8)
	s_waitcnt lgkmcnt(0)
	s_barrier
	s_setprio 1
	s_waitcnt lgkmcnt(0)
	v_mfma_f32_16x16x32_bf16 v[126:129], v[136:139], v[168:171], v[126:129]
	v_mfma_f32_16x16x32_bf16 v[122:125], v[144:147], v[168:171], v[122:125]
	v_mfma_f32_16x16x32_bf16 v[110:113], v[136:139], v[176:179], v[110:113]
	v_mfma_f32_16x16x32_bf16 v[106:109], v[144:147], v[176:179], v[106:109]
	v_mfma_f32_16x16x32_bf16 v[94:97], v[136:139], v[184:187], v[94:97]
	v_mfma_f32_16x16x32_bf16 v[90:93], v[144:147], v[184:187], v[90:93]
	v_mfma_f32_16x16x32_bf16 v[78:81], v[136:139], v[192:195], v[78:81]
	v_mfma_f32_16x16x32_bf16 v[74:77], v[144:147], v[192:195], v[74:77]
	v_mfma_f32_16x16x32_bf16 v[126:129], v[140:143], v[172:175], v[126:129]
	v_mfma_f32_16x16x32_bf16 v[122:125], v[148:151], v[172:175], v[122:125]
	v_mfma_f32_16x16x32_bf16 v[110:113], v[140:143], v[180:183], v[110:113]
	v_mfma_f32_16x16x32_bf16 v[106:109], v[148:151], v[180:183], v[106:109]
	v_mfma_f32_16x16x32_bf16 v[94:97], v[140:143], v[188:191], v[94:97]
	v_mfma_f32_16x16x32_bf16 v[90:93], v[148:151], v[188:191], v[90:93]
	v_mfma_f32_16x16x32_bf16 v[78:81], v[140:143], v[198:201], v[78:81]
	v_mfma_f32_16x16x32_bf16 v[74:77], v[148:151], v[198:201], v[74:77]
	s_setprio 0
	s_setprio 1
	v_mfma_f32_16x16x32_bf16 v[118:121], v[152:155], v[168:171], v[118:121]
	v_mfma_f32_16x16x32_bf16 v[114:117], v[160:163], v[168:171], v[114:117]
	v_mfma_f32_16x16x32_bf16 v[102:105], v[152:155], v[176:179], v[102:105]
	v_mfma_f32_16x16x32_bf16 v[98:101], v[160:163], v[176:179], v[98:101]
	v_mfma_f32_16x16x32_bf16 v[86:89], v[152:155], v[184:187], v[86:89]
	v_mfma_f32_16x16x32_bf16 v[82:85], v[160:163], v[184:187], v[82:85]
	v_mfma_f32_16x16x32_bf16 v[70:73], v[152:155], v[192:195], v[70:73]
	v_mfma_f32_16x16x32_bf16 v[66:69], v[160:163], v[192:195], v[66:69]
	v_mfma_f32_16x16x32_bf16 v[118:121], v[156:159], v[172:175], v[118:121]
	v_mfma_f32_16x16x32_bf16 v[114:117], v[164:167], v[172:175], v[114:117]
	v_mfma_f32_16x16x32_bf16 v[102:105], v[156:159], v[180:183], v[102:105]
	v_mfma_f32_16x16x32_bf16 v[98:101], v[164:167], v[180:183], v[98:101]
	v_mfma_f32_16x16x32_bf16 v[86:89], v[156:159], v[188:191], v[86:89]
	v_mfma_f32_16x16x32_bf16 v[82:85], v[164:167], v[188:191], v[82:85]
	v_mfma_f32_16x16x32_bf16 v[70:73], v[156:159], v[198:201], v[70:73]
	v_mfma_f32_16x16x32_bf16 v[66:69], v[164:167], v[198:201], v[66:69]
	s_setprio 0
	s_barrier
	v_mov_b32_e32 v0, v132
	ds_read_b128 v[168:171], v135 offset:49152
	ds_read_b128 v[172:175], v135 offset:50176
	ds_read_b128 v[176:179], v135 offset:51200
	ds_read_b128 v[180:183], v135 offset:52224
	ds_read_b128 v[184:187], v135 offset:53248
	ds_read_b128 v[188:191], v135 offset:54272
	ds_read_b128 v[192:195], v135 offset:55296
	ds_read_b128 v[198:201], v135 offset:56320
	s_add_i32 s4, s85, s26
	s_add_u32 s100, s58, s38
	s_addc_u32 s101, s59, s39
	s_mov_b32 m0, s4
	v_mov_b32_e32 v0, v133
	global_load_lds_dwordx4 v132, s[100:101]
	s_add_i32 m0, s4, 0x2000
	s_add_u32 s4, s58, 0xb0080
	s_addc_u32 s5, s59, 0
	v_mov_b32_e32 v0, v132
	s_add_i32 s58, s86, s26
	global_load_lds_dwordx4 v133, s[100:101]
	s_mov_b32 m0, s58
	s_nop 0
	global_load_lds_dwordx4 v0, s[4:5]
	v_mov_b32_e32 v0, v133
	s_add_i32 m0, s58, 0x2000
	s_nop 0
	global_load_lds_dwordx4 v0, s[4:5]
	v_mov_b32_e32 v0, v130
	s_mov_b32 m0, s75
	s_add_u32 s100, s46, s38
	s_addc_u32 s101, s47, s39
	v_mov_b32_e32 v0, v131
	global_load_lds_dwordx4 v130, s[100:101]
	s_mov_b32 m0, s78
	s_nop 0
	global_load_lds_dwordx4 v131, s[100:101]
	s_waitcnt vmcnt(8)
	s_waitcnt lgkmcnt(0)
	s_barrier
	s_setprio 1
	s_waitcnt lgkmcnt(0)
	v_mfma_f32_16x16x32_bf16 v[62:65], v[136:139], v[168:171], v[62:65]
	v_mfma_f32_16x16x32_bf16 v[58:61], v[144:147], v[168:171], v[58:61]
	v_mfma_f32_16x16x32_bf16 v[46:49], v[136:139], v[176:179], v[46:49]
	v_mfma_f32_16x16x32_bf16 v[42:45], v[144:147], v[176:179], v[42:45]
	v_mfma_f32_16x16x32_bf16 v[30:33], v[136:139], v[184:187], v[30:33]
	v_mfma_f32_16x16x32_bf16 v[26:29], v[144:147], v[184:187], v[26:29]
	v_mfma_f32_16x16x32_bf16 v[14:17], v[136:139], v[192:195], v[14:17]
	v_mfma_f32_16x16x32_bf16 v[10:13], v[144:147], v[192:195], v[10:13]
	v_mfma_f32_16x16x32_bf16 v[62:65], v[140:143], v[172:175], v[62:65]
	v_mfma_f32_16x16x32_bf16 v[58:61], v[148:151], v[172:175], v[58:61]
	v_mfma_f32_16x16x32_bf16 v[46:49], v[140:143], v[180:183], v[46:49]
	v_mfma_f32_16x16x32_bf16 v[42:45], v[148:151], v[180:183], v[42:45]
	v_mfma_f32_16x16x32_bf16 v[30:33], v[140:143], v[188:191], v[30:33]
	v_mfma_f32_16x16x32_bf16 v[26:29], v[148:151], v[188:191], v[26:29]
	v_mfma_f32_16x16x32_bf16 v[14:17], v[140:143], v[198:201], v[14:17]
	v_mfma_f32_16x16x32_bf16 v[10:13], v[148:151], v[198:201], v[10:13]
	s_setprio 0
	s_setprio 1
	v_mfma_f32_16x16x32_bf16 v[54:57], v[152:155], v[168:171], v[54:57]
	v_mfma_f32_16x16x32_bf16 v[50:53], v[160:163], v[168:171], v[50:53]
	v_mfma_f32_16x16x32_bf16 v[38:41], v[152:155], v[176:179], v[38:41]
	v_mfma_f32_16x16x32_bf16 v[34:37], v[160:163], v[176:179], v[34:37]
	v_mfma_f32_16x16x32_bf16 v[22:25], v[152:155], v[184:187], v[22:25]
	v_mfma_f32_16x16x32_bf16 v[18:21], v[160:163], v[184:187], v[18:21]
	v_mfma_f32_16x16x32_bf16 v[6:9], v[152:155], v[192:195], v[6:9]
	v_mfma_f32_16x16x32_bf16 v[2:5], v[160:163], v[192:195], v[2:5]
	v_mfma_f32_16x16x32_bf16 v[54:57], v[156:159], v[172:175], v[54:57]
	v_mfma_f32_16x16x32_bf16 v[50:53], v[164:167], v[172:175], v[50:53]
	v_mfma_f32_16x16x32_bf16 v[38:41], v[156:159], v[180:183], v[38:41]
	v_mfma_f32_16x16x32_bf16 v[34:37], v[164:167], v[180:183], v[34:37]
	v_mfma_f32_16x16x32_bf16 v[22:25], v[156:159], v[188:191], v[22:25]
	v_mfma_f32_16x16x32_bf16 v[18:21], v[164:167], v[188:191], v[18:21]
	v_mfma_f32_16x16x32_bf16 v[6:9], v[156:159], v[198:201], v[6:9]
	v_mfma_f32_16x16x32_bf16 v[2:5], v[164:167], v[198:201], v[2:5]
	s_setprio 0
	s_barrier
	s_add_i32 s84, s84, 2
	s_add_u32 s50, s50, 0x100
	s_addc_u32 s51, s51, 0
	s_cmp_gt_u32 s84, 41
	s_cbranch_scc0 .LBB0_821
	s_cmpk_lt_u32 s24, 0x100
	s_cbranch_scc0 .LBB0_824
	s_barrier

.LBB0_869:
	s_add_u32 s4, s10, s2
	s_addc_u32 s5, s11, s3
	s_add_u32 s22, s4, 0x100
	s_addc_u32 s23, s5, 0
	s_add_u32 s46, s58, s2
	s_addc_u32 s47, s59, s3
	s_add_i32 s69, 0, 0x10000
	s_cmp_eq_u32 s68, 40
	s_cselect_b32 s23, s11, s23
	s_cselect_b32 s22, s10, s22
	v_add_u32_e32 v0, s69, v126
	s_cselect_b32 s47, s17, s47
	s_cselect_b32 s46, s16, s46
	s_add_i32 s70, 0, 0x14000
	ds_read_b128 v[128:131], v0
	ds_read_b128 v[142:145], v0 offset:1024
	ds_read_b128 v[146:149], v0 offset:2048
	ds_read_b128 v[150:153], v0 offset:3072
	v_add_u32_e32 v0, s70, v126
	ds_read_b128 v[154:157], v0
	ds_read_b128 v[160:163], v0 offset:1024
	ds_read_b128 v[164:167], v0 offset:2048
	ds_read_b128 v[168:171], v0 offset:3072
	v_mov_b32_e32 v0, v122
	ds_read_b128 v[172:175], v127
	ds_read_b128 v[176:179], v127 offset:1024
	ds_read_b128 v[180:183], v127 offset:2048
	ds_read_b128 v[184:187], v127 offset:3072
	ds_read_b128 v[188:191], v127 offset:4096
	ds_read_b128 v[192:195], v127 offset:5120
	ds_read_b128 v[196:199], v127 offset:6144
	ds_read_b128 v[200:203], v127 offset:7168
	s_add_i32 m0, s41, 0xc000
	s_add_u32 s100, s4, s62
	s_addc_u32 s101, s5, s63
	v_mov_b32_e32 v0, v123
	global_load_lds_dwordx4 v122, s[100:101]
	s_add_i32 m0, s41, 0xe000
	s_nop 0
	global_load_lds_dwordx4 v123, s[100:101]
	s_waitcnt vmcnt(8)
	s_waitcnt lgkmcnt(0)
	s_barrier
	s_setprio 1
	s_waitcnt lgkmcnt(0)
	v_mfma_f32_16x16x32_bf16 v[138:141], v[128:131], v[172:175], v[138:141]
	v_mfma_f32_16x16x32_bf16 v[132:135], v[146:149], v[172:175], v[134:137]
	v_mfma_f32_16x16x32_bf16 v[110:113], v[128:131], v[180:183], v[110:113]
	v_mfma_f32_16x16x32_bf16 v[106:109], v[146:149], v[180:183], v[106:109]
	v_mfma_f32_16x16x32_bf16 v[94:97], v[128:131], v[188:191], v[94:97]
	v_mfma_f32_16x16x32_bf16 v[90:93], v[146:149], v[188:191], v[90:93]
	v_mfma_f32_16x16x32_bf16 v[78:81], v[128:131], v[196:199], v[78:81]
	v_mfma_f32_16x16x32_bf16 v[74:77], v[146:149], v[196:199], v[74:77]
	v_mfma_f32_16x16x32_bf16 v[138:141], v[142:145], v[176:179], v[138:141]
	v_mfma_f32_16x16x32_bf16 v[132:135], v[150:153], v[176:179], v[132:135]
	v_mfma_f32_16x16x32_bf16 v[110:113], v[142:145], v[184:187], v[110:113]
	v_mfma_f32_16x16x32_bf16 v[106:109], v[150:153], v[184:187], v[106:109]
	v_mfma_f32_16x16x32_bf16 v[94:97], v[142:145], v[192:195], v[94:97]
	v_mfma_f32_16x16x32_bf16 v[90:93], v[150:153], v[192:195], v[90:93]
	v_mfma_f32_16x16x32_bf16 v[78:81], v[142:145], v[200:203], v[78:81]
	v_mfma_f32_16x16x32_bf16 v[74:77], v[150:153], v[200:203], v[74:77]
	s_setprio 0
	s_setprio 1
	v_mfma_f32_16x16x32_bf16 v[118:121], v[154:157], v[172:175], v[118:121]
	v_mfma_f32_16x16x32_bf16 v[114:117], v[164:167], v[172:175], v[114:117]
	v_mfma_f32_16x16x32_bf16 v[102:105], v[154:157], v[180:183], v[102:105]
	v_mfma_f32_16x16x32_bf16 v[98:101], v[164:167], v[180:183], v[98:101]
	v_mfma_f32_16x16x32_bf16 v[86:89], v[154:157], v[188:191], v[86:89]
	v_mfma_f32_16x16x32_bf16 v[82:85], v[164:167], v[188:191], v[82:85]
	v_mfma_f32_16x16x32_bf16 v[70:73], v[154:157], v[196:199], v[70:73]
	v_mfma_f32_16x16x32_bf16 v[66:69], v[164:167], v[196:199], v[66:69]
	v_mfma_f32_16x16x32_bf16 v[118:121], v[160:163], v[176:179], v[118:121]
	v_mfma_f32_16x16x32_bf16 v[114:117], v[168:171], v[176:179], v[114:117]
	v_mfma_f32_16x16x32_bf16 v[102:105], v[160:163], v[184:187], v[102:105]
	v_mfma_f32_16x16x32_bf16 v[98:101], v[168:171], v[184:187], v[98:101]
	v_mfma_f32_16x16x32_bf16 v[86:89], v[160:163], v[192:195], v[86:89]
	v_mfma_f32_16x16x32_bf16 v[82:85], v[168:171], v[192:195], v[82:85]
	v_mfma_f32_16x16x32_bf16 v[70:73], v[160:163], v[200:203], v[70:73]
	v_mfma_f32_16x16x32_bf16 v[66:69], v[168:171], v[200:203], v[66:69]
	s_setprio 0
	s_barrier
	v_mov_b32_e32 v0, v124
	s_add_i32 s4, s69, s26
	ds_read_b128 v[172:175], v127 offset:16384
	ds_read_b128 v[176:179], v127 offset:17408
	ds_read_b128 v[180:183], v127 offset:18432
	ds_read_b128 v[184:187], v127 offset:19456
	ds_read_b128 v[188:191], v127 offset:20480
	ds_read_b128 v[192:195], v127 offset:21504
	ds_read_b128 v[196:199], v127 offset:22528
	ds_read_b128 v[200:203], v127 offset:23552
	s_mov_b32 m0, s4
	s_nop 0
	global_load_lds_dwordx4 v0, s[46:47]
	v_mov_b32_e32 v0, v125
	s_add_i32 m0, s4, 0x2000
	s_add_u32 s4, s46, 0xb0000
	global_load_lds_dwordx4 v0, s[46:47]
	s_addc_u32 s5, s47, 0
	v_mov_b32_e32 v0, v124
	s_add_i32 s69, s70, s26
	s_mov_b32 m0, s69
	s_nop 0
	global_load_lds_dwordx4 v0, s[4:5]
	v_mov_b32_e32 v0, v125
	s_add_i32 m0, s69, 0x2000
	s_nop 0
	global_load_lds_dwordx4 v0, s[4:5]
	v_mov_b32_e32 v0, v122
	s_mov_b32 m0, s41
	s_nop 0
	global_load_lds_dwordx4 v0, s[22:23]
	v_mov_b32_e32 v0, v123
	s_mov_b32 m0, s48
	s_nop 0
	global_load_lds_dwordx4 v0, s[22:23]
	s_waitcnt vmcnt(8)
	s_waitcnt lgkmcnt(0)
	s_barrier
	s_setprio 1
	s_waitcnt lgkmcnt(0)
	v_mfma_f32_16x16x32_bf16 v[62:65], v[128:131], v[172:175], v[62:65]
	v_mfma_f32_16x16x32_bf16 v[58:61], v[146:149], v[172:175], v[58:61]
	v_mfma_f32_16x16x32_bf16 v[46:49], v[128:131], v[180:183], v[46:49]
	v_mfma_f32_16x16x32_bf16 v[42:45], v[146:149], v[180:183], v[42:45]
	v_mfma_f32_16x16x32_bf16 v[30:33], v[128:131], v[188:191], v[30:33]
	v_mfma_f32_16x16x32_bf16 v[26:29], v[146:149], v[188:191], v[26:29]
	v_mfma_f32_16x16x32_bf16 v[14:17], v[128:131], v[196:199], v[14:17]
	v_mfma_f32_16x16x32_bf16 v[10:13], v[146:149], v[196:199], v[10:13]
	v_mfma_f32_16x16x32_bf16 v[62:65], v[142:145], v[176:179], v[62:65]
	v_mfma_f32_16x16x32_bf16 v[58:61], v[150:153], v[176:179], v[58:61]
	v_mfma_f32_16x16x32_bf16 v[46:49], v[142:145], v[184:187], v[46:49]
	v_mfma_f32_16x16x32_bf16 v[42:45], v[150:153], v[184:187], v[42:45]
	v_mfma_f32_16x16x32_bf16 v[30:33], v[142:145], v[192:195], v[30:33]
	v_mfma_f32_16x16x32_bf16 v[26:29], v[150:153], v[192:195], v[26:29]
	v_mfma_f32_16x16x32_bf16 v[14:17], v[142:145], v[200:203], v[14:17]
	v_mfma_f32_16x16x32_bf16 v[10:13], v[150:153], v[200:203], v[10:13]
	s_setprio 0
	s_setprio 1
	v_mfma_f32_16x16x32_bf16 v[54:57], v[154:157], v[172:175], v[54:57]
	v_mfma_f32_16x16x32_bf16 v[50:53], v[164:167], v[172:175], v[50:53]
	v_mfma_f32_16x16x32_bf16 v[38:41], v[154:157], v[180:183], v[38:41]
	v_mfma_f32_16x16x32_bf16 v[34:37], v[164:167], v[180:183], v[34:37]
	v_mfma_f32_16x16x32_bf16 v[22:25], v[154:157], v[188:191], v[22:25]
	v_mfma_f32_16x16x32_bf16 v[18:21], v[164:167], v[188:191], v[18:21]
	v_mfma_f32_16x16x32_bf16 v[6:9], v[154:157], v[196:199], v[6:9]
	v_mfma_f32_16x16x32_bf16 v[2:5], v[164:167], v[196:199], v[2:5]
	v_mfma_f32_16x16x32_bf16 v[54:57], v[160:163], v[176:179], v[54:57]
	v_mfma_f32_16x16x32_bf16 v[50:53], v[168:171], v[176:179], v[50:53]
	v_mfma_f32_16x16x32_bf16 v[38:41], v[160:163], v[184:187], v[38:41]
	v_mfma_f32_16x16x32_bf16 v[34:37], v[168:171], v[184:187], v[34:37]
	v_mfma_f32_16x16x32_bf16 v[22:25], v[160:163], v[192:195], v[22:25]
	v_mfma_f32_16x16x32_bf16 v[18:21], v[168:171], v[192:195], v[18:21]
	v_mfma_f32_16x16x32_bf16 v[6:9], v[160:163], v[200:203], v[6:9]
	v_mfma_f32_16x16x32_bf16 v[2:5], v[168:171], v[200:203], v[2:5]
	s_setprio 0
	s_barrier
	s_add_i32 s69, 0, 0x18000
	v_add_u32_e32 v0, s69, v126
	s_add_i32 s70, 0, 0x1c000
	ds_read_b128 v[128:131], v0
	ds_read_b128 v[142:145], v0 offset:1024
	ds_read_b128 v[146:149], v0 offset:2048
	ds_read_b128 v[150:153], v0 offset:3072
	v_add_u32_e32 v0, s70, v126
	ds_read_b128 v[154:157], v0
	ds_read_b128 v[160:163], v0 offset:1024
	ds_read_b128 v[164:167], v0 offset:2048
	ds_read_b128 v[168:171], v0 offset:3072
	s_add_u32 s4, s22, 0xb0000
	v_mov_b32_e32 v0, v122
	s_mov_b32 m0, s49
	ds_read_b128 v[172:175], v127 offset:32768
	ds_read_b128 v[176:179], v127 offset:33792
	ds_read_b128 v[180:183], v127 offset:34816
	ds_read_b128 v[184:187], v127 offset:35840
	ds_read_b128 v[188:191], v127 offset:36864
	ds_read_b128 v[192:195], v127 offset:37888
	ds_read_b128 v[196:199], v127 offset:38912
	ds_read_b128 v[200:203], v127 offset:39936
	s_addc_u32 s5, s23, 0
	s_nop 0
	global_load_lds_dwordx4 v0, s[4:5]
	v_mov_b32_e32 v0, v123
	s_mov_b32 m0, s50
	s_nop 0
	global_load_lds_dwordx4 v0, s[4:5]
	s_waitcnt vmcnt(8)
	s_waitcnt lgkmcnt(0)
	s_barrier
	s_setprio 1
	s_waitcnt lgkmcnt(0)
	v_mfma_f32_16x16x32_bf16 v[136:139], v[128:131], v[172:175], v[138:141]
	v_mfma_f32_16x16x32_bf16 v[132:135], v[146:149], v[172:175], v[132:135]
	v_mfma_f32_16x16x32_bf16 v[110:113], v[128:131], v[180:183], v[110:113]
	v_mfma_f32_16x16x32_bf16 v[106:109], v[146:149], v[180:183], v[106:109]
	v_mfma_f32_16x16x32_bf16 v[94:97], v[128:131], v[188:191], v[94:97]
	v_mfma_f32_16x16x32_bf16 v[90:93], v[146:149], v[188:191], v[90:93]
	v_mfma_f32_16x16x32_bf16 v[78:81], v[128:131], v[196:199], v[78:81]
	v_mfma_f32_16x16x32_bf16 v[74:77], v[146:149], v[196:199], v[74:77]
	v_mfma_f32_16x16x32_bf16 v[138:141], v[142:145], v[176:179], v[136:139]
	v_mfma_f32_16x16x32_bf16 v[134:137], v[150:153], v[176:179], v[132:135]
	v_mfma_f32_16x16x32_bf16 v[110:113], v[142:145], v[184:187], v[110:113]
	v_mfma_f32_16x16x32_bf16 v[106:109], v[150:153], v[184:187], v[106:109]
	v_mfma_f32_16x16x32_bf16 v[94:97], v[142:145], v[192:195], v[94:97]
	v_mfma_f32_16x16x32_bf16 v[90:93], v[150:153], v[192:195], v[90:93]
	v_mfma_f32_16x16x32_bf16 v[78:81], v[142:145], v[200:203], v[78:81]
	v_mfma_f32_16x16x32_bf16 v[74:77], v[150:153], v[200:203], v[74:77]
	s_setprio 0
	s_setprio 1
	v_mfma_f32_16x16x32_bf16 v[118:121], v[154:157], v[172:175], v[118:121]
	v_mfma_f32_16x16x32_bf16 v[114:117], v[164:167], v[172:175], v[114:117]
	v_mfma_f32_16x16x32_bf16 v[102:105], v[154:157], v[180:183], v[102:105]
	v_mfma_f32_16x16x32_bf16 v[98:101], v[164:167], v[180:183], v[98:101]
	v_mfma_f32_16x16x32_bf16 v[86:89], v[154:157], v[188:191], v[86:89]
	v_mfma_f32_16x16x32_bf16 v[82:85], v[164:167], v[188:191], v[82:85]
	v_mfma_f32_16x16x32_bf16 v[70:73], v[154:157], v[196:199], v[70:73]
	v_mfma_f32_16x16x32_bf16 v[66:69], v[164:167], v[196:199], v[66:69]
	v_mfma_f32_16x16x32_bf16 v[118:121], v[160:163], v[176:179], v[118:121]
	v_mfma_f32_16x16x32_bf16 v[114:117], v[168:171], v[176:179], v[114:117]
	v_mfma_f32_16x16x32_bf16 v[102:105], v[160:163], v[184:187], v[102:105]
	v_mfma_f32_16x16x32_bf16 v[98:101], v[168:171], v[184:187], v[98:101]
	v_mfma_f32_16x16x32_bf16 v[86:89], v[160:163], v[192:195], v[86:89]
	v_mfma_f32_16x16x32_bf16 v[82:85], v[168:171], v[192:195], v[82:85]
	v_mfma_f32_16x16x32_bf16 v[70:73], v[160:163], v[200:203], v[70:73]
	v_mfma_f32_16x16x32_bf16 v[66:69], v[168:171], v[200:203], v[66:69]
	s_setprio 0
	s_barrier
	v_mov_b32_e32 v0, v124
	ds_read_b128 v[172:175], v127 offset:49152
	ds_read_b128 v[176:179], v127 offset:50176
	ds_read_b128 v[180:183], v127 offset:51200
	ds_read_b128 v[184:187], v127 offset:52224
	ds_read_b128 v[188:191], v127 offset:53248
	ds_read_b128 v[192:195], v127 offset:54272
	ds_read_b128 v[196:199], v127 offset:55296
	ds_read_b128 v[200:203], v127 offset:56320
	s_add_i32 s4, s69, s26
	s_add_u32 s100, s46, s38
	s_addc_u32 s101, s47, s39
	s_mov_b32 m0, s4
	v_mov_b32_e32 v0, v125
	global_load_lds_dwordx4 v124, s[100:101]
	s_add_i32 m0, s4, 0x2000
	s_add_u32 s4, s46, 0xb0080
	s_addc_u32 s5, s47, 0
	v_mov_b32_e32 v0, v124
	s_add_i32 s46, s70, s26
	global_load_lds_dwordx4 v125, s[100:101]
	s_mov_b32 m0, s46
	s_nop 0
	global_load_lds_dwordx4 v0, s[4:5]
	v_mov_b32_e32 v0, v125
	s_add_i32 m0, s46, 0x2000
	s_nop 0
	global_load_lds_dwordx4 v0, s[4:5]
	v_mov_b32_e32 v0, v122
	s_mov_b32 m0, s64
	s_add_u32 s100, s22, s38
	s_addc_u32 s101, s23, s39
	v_mov_b32_e32 v0, v123
	global_load_lds_dwordx4 v122, s[100:101]
	s_mov_b32 m0, s65
	s_nop 0
	global_load_lds_dwordx4 v123, s[100:101]
	s_waitcnt vmcnt(8)
	s_waitcnt lgkmcnt(0)
	s_barrier
	s_setprio 1
	s_waitcnt lgkmcnt(0)
	v_mfma_f32_16x16x32_bf16 v[62:65], v[128:131], v[172:175], v[62:65]
	v_mfma_f32_16x16x32_bf16 v[58:61], v[146:149], v[172:175], v[58:61]
	v_mfma_f32_16x16x32_bf16 v[46:49], v[128:131], v[180:183], v[46:49]
	v_mfma_f32_16x16x32_bf16 v[42:45], v[146:149], v[180:183], v[42:45]
	v_mfma_f32_16x16x32_bf16 v[30:33], v[128:131], v[188:191], v[30:33]
	v_mfma_f32_16x16x32_bf16 v[26:29], v[146:149], v[188:191], v[26:29]
	v_mfma_f32_16x16x32_bf16 v[14:17], v[128:131], v[196:199], v[14:17]
	v_mfma_f32_16x16x32_bf16 v[10:13], v[146:149], v[196:199], v[10:13]
	v_mfma_f32_16x16x32_bf16 v[62:65], v[142:145], v[176:179], v[62:65]
	v_mfma_f32_16x16x32_bf16 v[58:61], v[150:153], v[176:179], v[58:61]
	v_mfma_f32_16x16x32_bf16 v[46:49], v[142:145], v[184:187], v[46:49]
	v_mfma_f32_16x16x32_bf16 v[42:45], v[150:153], v[184:187], v[42:45]
	v_mfma_f32_16x16x32_bf16 v[30:33], v[142:145], v[192:195], v[30:33]
	v_mfma_f32_16x16x32_bf16 v[26:29], v[150:153], v[192:195], v[26:29]
	v_mfma_f32_16x16x32_bf16 v[14:17], v[142:145], v[200:203], v[14:17]
	v_mfma_f32_16x16x32_bf16 v[10:13], v[150:153], v[200:203], v[10:13]
	s_setprio 0
	s_setprio 1
	v_mfma_f32_16x16x32_bf16 v[54:57], v[154:157], v[172:175], v[54:57]
	v_mfma_f32_16x16x32_bf16 v[50:53], v[164:167], v[172:175], v[50:53]
	v_mfma_f32_16x16x32_bf16 v[38:41], v[154:157], v[180:183], v[38:41]
	v_mfma_f32_16x16x32_bf16 v[34:37], v[164:167], v[180:183], v[34:37]
	v_mfma_f32_16x16x32_bf16 v[22:25], v[154:157], v[188:191], v[22:25]
	v_mfma_f32_16x16x32_bf16 v[18:21], v[164:167], v[188:191], v[18:21]
	v_mfma_f32_16x16x32_bf16 v[6:9], v[154:157], v[196:199], v[6:9]
	v_mfma_f32_16x16x32_bf16 v[2:5], v[164:167], v[196:199], v[2:5]
	v_mfma_f32_16x16x32_bf16 v[54:57], v[160:163], v[176:179], v[54:57]
	v_mfma_f32_16x16x32_bf16 v[50:53], v[168:171], v[176:179], v[50:53]
	v_mfma_f32_16x16x32_bf16 v[38:41], v[160:163], v[184:187], v[38:41]
	v_mfma_f32_16x16x32_bf16 v[34:37], v[168:171], v[184:187], v[34:37]
	v_mfma_f32_16x16x32_bf16 v[22:25], v[160:163], v[192:195], v[22:25]
	v_mfma_f32_16x16x32_bf16 v[18:21], v[168:171], v[192:195], v[18:21]
	v_mfma_f32_16x16x32_bf16 v[6:9], v[160:163], v[200:203], v[6:9]
	v_mfma_f32_16x16x32_bf16 v[2:5], v[168:171], v[200:203], v[2:5]
	s_setprio 0
	s_barrier
	s_add_i32 s68, s68, 2
	s_add_u32 s2, s2, 0x100
	s_addc_u32 s3, s3, 0
	s_cmp_gt_u32 s68, 41
	s_cbranch_scc0 .LBB0_869
	s_cmpk_lt_u32 s25, 0x100
	s_cbranch_scc0 .LBB0_872
	s_barrier

.LBB0_953:
	s_add_u32 s58, s4, s2
	s_addc_u32 s59, s5, s3
	s_add_u32 s14, s58, 0x100
	s_addc_u32 s15, s59, 0
	s_add_u32 s16, s43, s2
	s_addc_u32 s17, s46, s3
	s_add_i32 s51, 0, 0x10000
	s_cmp_eq_u32 s50, 40
	s_cselect_b32 s15, s5, s15
	s_cselect_b32 s14, s4, s14
	v_add_u32_e32 v0, s51, v135
	s_cselect_b32 s17, s7, s17
	s_cselect_b32 s16, s6, s16
	s_add_i32 s60, 0, 0x14000
	ds_read_b128 v[138:141], v0
	ds_read_b128 v[142:145], v0 offset:1024
	ds_read_b128 v[146:149], v0 offset:2048
	ds_read_b128 v[150:153], v0 offset:3072
	v_add_u32_e32 v0, s60, v135
	ds_read_b128 v[154:157], v0
	ds_read_b128 v[158:161], v0 offset:1024
	ds_read_b128 v[162:165], v0 offset:2048
	ds_read_b128 v[166:169], v0 offset:3072
	v_mov_b32_e32 v0, v130
	ds_read_b128 v[170:173], v136
	ds_read_b128 v[174:177], v136 offset:1024
	ds_read_b128 v[178:181], v136 offset:2048
	ds_read_b128 v[182:185], v136 offset:3072
	ds_read_b128 v[186:189], v136 offset:4096
	ds_read_b128 v[190:193], v136 offset:5120
	ds_read_b128 v[194:197], v136 offset:6144
	ds_read_b128 v[198:201], v136 offset:7168
	s_add_i32 m0, s37, 0xc000
	s_add_u32 s100, s58, s62
	s_addc_u32 s101, s59, s63
	v_mov_b32_e32 v0, v131
	global_load_lds_dwordx4 v130, s[100:101]
	s_add_i32 m0, s37, 0xe000
	s_nop 0
	global_load_lds_dwordx4 v131, s[100:101]
	s_waitcnt vmcnt(8)
	s_waitcnt lgkmcnt(0)
	s_barrier
	s_setprio 1
	s_waitcnt lgkmcnt(0)
	v_mfma_f32_16x16x32_bf16 v[126:129], v[138:141], v[170:173], v[126:129]
	v_mfma_f32_16x16x32_bf16 v[122:125], v[146:149], v[170:173], v[122:125]
	v_mfma_f32_16x16x32_bf16 v[110:113], v[138:141], v[178:181], v[110:113]
	v_mfma_f32_16x16x32_bf16 v[106:109], v[146:149], v[178:181], v[106:109]
	v_mfma_f32_16x16x32_bf16 v[94:97], v[138:141], v[186:189], v[94:97]
	v_mfma_f32_16x16x32_bf16 v[90:93], v[146:149], v[186:189], v[90:93]
	v_mfma_f32_16x16x32_bf16 v[78:81], v[138:141], v[194:197], v[78:81]
	v_mfma_f32_16x16x32_bf16 v[74:77], v[146:149], v[194:197], v[74:77]
	v_mfma_f32_16x16x32_bf16 v[126:129], v[142:145], v[174:177], v[126:129]
	v_mfma_f32_16x16x32_bf16 v[122:125], v[150:153], v[174:177], v[122:125]
	v_mfma_f32_16x16x32_bf16 v[110:113], v[142:145], v[182:185], v[110:113]
	v_mfma_f32_16x16x32_bf16 v[106:109], v[150:153], v[182:185], v[106:109]
	v_mfma_f32_16x16x32_bf16 v[94:97], v[142:145], v[190:193], v[94:97]
	v_mfma_f32_16x16x32_bf16 v[90:93], v[150:153], v[190:193], v[90:93]
	v_mfma_f32_16x16x32_bf16 v[78:81], v[142:145], v[198:201], v[78:81]
	v_mfma_f32_16x16x32_bf16 v[74:77], v[150:153], v[198:201], v[74:77]
	s_setprio 0
	s_setprio 1
	v_mfma_f32_16x16x32_bf16 v[118:121], v[154:157], v[170:173], v[118:121]
	v_mfma_f32_16x16x32_bf16 v[114:117], v[162:165], v[170:173], v[114:117]
	v_mfma_f32_16x16x32_bf16 v[102:105], v[154:157], v[178:181], v[102:105]
	v_mfma_f32_16x16x32_bf16 v[98:101], v[162:165], v[178:181], v[98:101]
	v_mfma_f32_16x16x32_bf16 v[86:89], v[154:157], v[186:189], v[86:89]
	v_mfma_f32_16x16x32_bf16 v[82:85], v[162:165], v[186:189], v[82:85]
	v_mfma_f32_16x16x32_bf16 v[70:73], v[154:157], v[194:197], v[70:73]
	v_mfma_f32_16x16x32_bf16 v[66:69], v[162:165], v[194:197], v[66:69]
	v_mfma_f32_16x16x32_bf16 v[118:121], v[158:161], v[174:177], v[118:121]
	v_mfma_f32_16x16x32_bf16 v[114:117], v[166:169], v[174:177], v[114:117]
	v_mfma_f32_16x16x32_bf16 v[102:105], v[158:161], v[182:185], v[102:105]
	v_mfma_f32_16x16x32_bf16 v[98:101], v[166:169], v[182:185], v[98:101]
	v_mfma_f32_16x16x32_bf16 v[86:89], v[158:161], v[190:193], v[86:89]
	v_mfma_f32_16x16x32_bf16 v[82:85], v[166:169], v[190:193], v[82:85]
	v_mfma_f32_16x16x32_bf16 v[70:73], v[158:161], v[198:201], v[70:73]
	v_mfma_f32_16x16x32_bf16 v[66:69], v[166:169], v[198:201], v[66:69]
	s_setprio 0
	s_barrier
	v_mov_b32_e32 v0, v133
	s_add_i32 s51, s51, s26
	ds_read_b128 v[170:173], v136 offset:16384
	ds_read_b128 v[174:177], v136 offset:17408
	ds_read_b128 v[178:181], v136 offset:18432
	ds_read_b128 v[182:185], v136 offset:19456
	ds_read_b128 v[186:189], v136 offset:20480
	ds_read_b128 v[190:193], v136 offset:21504
	ds_read_b128 v[194:197], v136 offset:22528
	ds_read_b128 v[198:201], v136 offset:23552
	s_mov_b32 m0, s51
	s_nop 0
	global_load_lds_dwordx4 v0, s[16:17]
	v_mov_b32_e32 v0, v134
	s_add_i32 m0, s51, 0x2000
	s_add_u32 s58, s16, 0xb0000
	global_load_lds_dwordx4 v0, s[16:17]
	s_addc_u32 s59, s17, 0
	v_mov_b32_e32 v0, v133
	s_add_i32 s51, s60, s26
	s_mov_b32 m0, s51
	s_nop 0
	global_load_lds_dwordx4 v0, s[58:59]
	v_mov_b32_e32 v0, v134
	s_add_i32 m0, s51, 0x2000
	s_nop 0
	global_load_lds_dwordx4 v0, s[58:59]
	v_mov_b32_e32 v0, v130
	s_mov_b32 m0, s37
	s_nop 0
	global_load_lds_dwordx4 v0, s[14:15]
	v_mov_b32_e32 v0, v131
	s_mov_b32 m0, s40
	s_nop 0
	global_load_lds_dwordx4 v0, s[14:15]
	s_waitcnt vmcnt(8)
	s_waitcnt lgkmcnt(0)
	s_barrier
	s_setprio 1
	s_waitcnt lgkmcnt(0)
	v_mfma_f32_16x16x32_bf16 v[62:65], v[138:141], v[170:173], v[62:65]
	v_mfma_f32_16x16x32_bf16 v[58:61], v[146:149], v[170:173], v[58:61]
	v_mfma_f32_16x16x32_bf16 v[46:49], v[138:141], v[178:181], v[46:49]
	v_mfma_f32_16x16x32_bf16 v[42:45], v[146:149], v[178:181], v[42:45]
	v_mfma_f32_16x16x32_bf16 v[30:33], v[138:141], v[186:189], v[30:33]
	v_mfma_f32_16x16x32_bf16 v[26:29], v[146:149], v[186:189], v[26:29]
	v_mfma_f32_16x16x32_bf16 v[14:17], v[138:141], v[194:197], v[14:17]
	v_mfma_f32_16x16x32_bf16 v[10:13], v[146:149], v[194:197], v[10:13]
	v_mfma_f32_16x16x32_bf16 v[62:65], v[142:145], v[174:177], v[62:65]
	v_mfma_f32_16x16x32_bf16 v[58:61], v[150:153], v[174:177], v[58:61]
	v_mfma_f32_16x16x32_bf16 v[46:49], v[142:145], v[182:185], v[46:49]
	v_mfma_f32_16x16x32_bf16 v[42:45], v[150:153], v[182:185], v[42:45]
	v_mfma_f32_16x16x32_bf16 v[30:33], v[142:145], v[190:193], v[30:33]
	v_mfma_f32_16x16x32_bf16 v[26:29], v[150:153], v[190:193], v[26:29]
	v_mfma_f32_16x16x32_bf16 v[14:17], v[142:145], v[198:201], v[14:17]
	v_mfma_f32_16x16x32_bf16 v[10:13], v[150:153], v[198:201], v[10:13]
	s_setprio 0
	s_setprio 1
	v_mfma_f32_16x16x32_bf16 v[54:57], v[154:157], v[170:173], v[54:57]
	v_mfma_f32_16x16x32_bf16 v[50:53], v[162:165], v[170:173], v[50:53]
	v_mfma_f32_16x16x32_bf16 v[38:41], v[154:157], v[178:181], v[38:41]
	v_mfma_f32_16x16x32_bf16 v[34:37], v[162:165], v[178:181], v[34:37]
	v_mfma_f32_16x16x32_bf16 v[22:25], v[154:157], v[186:189], v[22:25]
	v_mfma_f32_16x16x32_bf16 v[18:21], v[162:165], v[186:189], v[18:21]
	v_mfma_f32_16x16x32_bf16 v[6:9], v[154:157], v[194:197], v[6:9]
	v_mfma_f32_16x16x32_bf16 v[2:5], v[162:165], v[194:197], v[2:5]
	v_mfma_f32_16x16x32_bf16 v[54:57], v[158:161], v[174:177], v[54:57]
	v_mfma_f32_16x16x32_bf16 v[50:53], v[166:169], v[174:177], v[50:53]
	v_mfma_f32_16x16x32_bf16 v[38:41], v[158:161], v[182:185], v[38:41]
	v_mfma_f32_16x16x32_bf16 v[34:37], v[166:169], v[182:185], v[34:37]
	v_mfma_f32_16x16x32_bf16 v[22:25], v[158:161], v[190:193], v[22:25]
	v_mfma_f32_16x16x32_bf16 v[18:21], v[166:169], v[190:193], v[18:21]
	v_mfma_f32_16x16x32_bf16 v[6:9], v[158:161], v[198:201], v[6:9]
	v_mfma_f32_16x16x32_bf16 v[2:5], v[166:169], v[198:201], v[2:5]
	s_setprio 0
	s_barrier
	s_add_i32 s51, 0, 0x18000
	v_add_u32_e32 v0, s51, v135
	s_add_i32 s60, 0, 0x1c000
	ds_read_b128 v[138:141], v0
	ds_read_b128 v[142:145], v0 offset:1024
	ds_read_b128 v[146:149], v0 offset:2048
	ds_read_b128 v[150:153], v0 offset:3072
	v_add_u32_e32 v0, s60, v135
	ds_read_b128 v[154:157], v0
	ds_read_b128 v[158:161], v0 offset:1024
	ds_read_b128 v[162:165], v0 offset:2048
	ds_read_b128 v[166:169], v0 offset:3072
	s_add_u32 s58, s14, 0xb0000
	v_mov_b32_e32 v0, v130
	s_mov_b32 m0, s41
	ds_read_b128 v[170:173], v136 offset:32768
	ds_read_b128 v[174:177], v136 offset:33792
	ds_read_b128 v[178:181], v136 offset:34816
	ds_read_b128 v[182:185], v136 offset:35840
	ds_read_b128 v[186:189], v136 offset:36864
	ds_read_b128 v[190:193], v136 offset:37888
	ds_read_b128 v[194:197], v136 offset:38912
	ds_read_b128 v[198:201], v136 offset:39936
	s_addc_u32 s59, s15, 0
	s_nop 0
	global_load_lds_dwordx4 v0, s[58:59]
	v_mov_b32_e32 v0, v131
	s_mov_b32 m0, s42
	s_nop 0
	global_load_lds_dwordx4 v0, s[58:59]
	s_waitcnt vmcnt(8)
	s_waitcnt lgkmcnt(0)
	s_barrier
	s_setprio 1
	s_waitcnt lgkmcnt(0)
	v_mfma_f32_16x16x32_bf16 v[126:129], v[138:141], v[170:173], v[126:129]
	v_mfma_f32_16x16x32_bf16 v[122:125], v[146:149], v[170:173], v[122:125]
	v_mfma_f32_16x16x32_bf16 v[110:113], v[138:141], v[178:181], v[110:113]
	v_mfma_f32_16x16x32_bf16 v[106:109], v[146:149], v[178:181], v[106:109]
	v_mfma_f32_16x16x32_bf16 v[94:97], v[138:141], v[186:189], v[94:97]
	v_mfma_f32_16x16x32_bf16 v[90:93], v[146:149], v[186:189], v[90:93]
	v_mfma_f32_16x16x32_bf16 v[78:81], v[138:141], v[194:197], v[78:81]
	v_mfma_f32_16x16x32_bf16 v[74:77], v[146:149], v[194:197], v[74:77]
	v_mfma_f32_16x16x32_bf16 v[126:129], v[142:145], v[174:177], v[126:129]
	v_mfma_f32_16x16x32_bf16 v[122:125], v[150:153], v[174:177], v[122:125]
	v_mfma_f32_16x16x32_bf16 v[110:113], v[142:145], v[182:185], v[110:113]
	v_mfma_f32_16x16x32_bf16 v[106:109], v[150:153], v[182:185], v[106:109]
	v_mfma_f32_16x16x32_bf16 v[94:97], v[142:145], v[190:193], v[94:97]
	v_mfma_f32_16x16x32_bf16 v[90:93], v[150:153], v[190:193], v[90:93]
	v_mfma_f32_16x16x32_bf16 v[78:81], v[142:145], v[198:201], v[78:81]
	v_mfma_f32_16x16x32_bf16 v[74:77], v[150:153], v[198:201], v[74:77]
	s_setprio 0
	s_setprio 1
	v_mfma_f32_16x16x32_bf16 v[118:121], v[154:157], v[170:173], v[118:121]
	v_mfma_f32_16x16x32_bf16 v[114:117], v[162:165], v[170:173], v[114:117]
	v_mfma_f32_16x16x32_bf16 v[102:105], v[154:157], v[178:181], v[102:105]
	v_mfma_f32_16x16x32_bf16 v[98:101], v[162:165], v[178:181], v[98:101]
	v_mfma_f32_16x16x32_bf16 v[86:89], v[154:157], v[186:189], v[86:89]
	v_mfma_f32_16x16x32_bf16 v[82:85], v[162:165], v[186:189], v[82:85]
	v_mfma_f32_16x16x32_bf16 v[70:73], v[154:157], v[194:197], v[70:73]
	v_mfma_f32_16x16x32_bf16 v[66:69], v[162:165], v[194:197], v[66:69]
	v_mfma_f32_16x16x32_bf16 v[118:121], v[158:161], v[174:177], v[118:121]
	v_mfma_f32_16x16x32_bf16 v[114:117], v[166:169], v[174:177], v[114:117]
	v_mfma_f32_16x16x32_bf16 v[102:105], v[158:161], v[182:185], v[102:105]
	v_mfma_f32_16x16x32_bf16 v[98:101], v[166:169], v[182:185], v[98:101]
	v_mfma_f32_16x16x32_bf16 v[86:89], v[158:161], v[190:193], v[86:89]
	v_mfma_f32_16x16x32_bf16 v[82:85], v[166:169], v[190:193], v[82:85]
	v_mfma_f32_16x16x32_bf16 v[70:73], v[158:161], v[198:201], v[70:73]
	v_mfma_f32_16x16x32_bf16 v[66:69], v[166:169], v[198:201], v[66:69]
	s_setprio 0
	s_barrier
	v_mov_b32_e32 v0, v133
	ds_read_b128 v[170:173], v136 offset:49152
	ds_read_b128 v[174:177], v136 offset:50176
	ds_read_b128 v[178:181], v136 offset:51200
	ds_read_b128 v[182:185], v136 offset:52224
	ds_read_b128 v[186:189], v136 offset:53248
	ds_read_b128 v[190:193], v136 offset:54272
	ds_read_b128 v[194:197], v136 offset:55296
	ds_read_b128 v[198:201], v136 offset:56320
	s_add_i32 s51, s51, s26
	s_add_u32 s100, s16, s38
	s_addc_u32 s101, s17, s39
	s_mov_b32 m0, s51
	v_mov_b32_e32 v0, v134
	global_load_lds_dwordx4 v133, s[100:101]
	s_add_i32 m0, s51, 0x2000
	s_nop 0
	s_add_u32 s16, s16, 0xb0080
	s_addc_u32 s17, s17, 0
	v_mov_b32_e32 v0, v133
	s_add_i32 s51, s60, s26
	global_load_lds_dwordx4 v134, s[100:101]
	s_mov_b32 m0, s51
	s_nop 0
	global_load_lds_dwordx4 v0, s[16:17]
	v_mov_b32_e32 v0, v134
	s_add_i32 m0, s51, 0x2000
	s_nop 0
	global_load_lds_dwordx4 v0, s[16:17]
	v_mov_b32_e32 v0, v130
	s_mov_b32 m0, s48
	s_add_u32 s100, s14, s38
	s_addc_u32 s101, s15, s39
	v_mov_b32_e32 v0, v131
	global_load_lds_dwordx4 v130, s[100:101]
	s_mov_b32 m0, s49
	s_nop 0
	global_load_lds_dwordx4 v131, s[100:101]
	s_waitcnt vmcnt(8)
	s_waitcnt lgkmcnt(0)
	s_barrier
	s_setprio 1
	s_waitcnt lgkmcnt(0)
	v_mfma_f32_16x16x32_bf16 v[62:65], v[138:141], v[170:173], v[62:65]
	v_mfma_f32_16x16x32_bf16 v[58:61], v[146:149], v[170:173], v[58:61]
	v_mfma_f32_16x16x32_bf16 v[46:49], v[138:141], v[178:181], v[46:49]
	v_mfma_f32_16x16x32_bf16 v[42:45], v[146:149], v[178:181], v[42:45]
	v_mfma_f32_16x16x32_bf16 v[30:33], v[138:141], v[186:189], v[30:33]
	v_mfma_f32_16x16x32_bf16 v[26:29], v[146:149], v[186:189], v[26:29]
	v_mfma_f32_16x16x32_bf16 v[14:17], v[138:141], v[194:197], v[14:17]
	v_mfma_f32_16x16x32_bf16 v[10:13], v[146:149], v[194:197], v[10:13]
	v_mfma_f32_16x16x32_bf16 v[62:65], v[142:145], v[174:177], v[62:65]
	v_mfma_f32_16x16x32_bf16 v[58:61], v[150:153], v[174:177], v[58:61]
	v_mfma_f32_16x16x32_bf16 v[46:49], v[142:145], v[182:185], v[46:49]
	v_mfma_f32_16x16x32_bf16 v[42:45], v[150:153], v[182:185], v[42:45]
	v_mfma_f32_16x16x32_bf16 v[30:33], v[142:145], v[190:193], v[30:33]
	v_mfma_f32_16x16x32_bf16 v[26:29], v[150:153], v[190:193], v[26:29]
	v_mfma_f32_16x16x32_bf16 v[14:17], v[142:145], v[198:201], v[14:17]
	v_mfma_f32_16x16x32_bf16 v[10:13], v[150:153], v[198:201], v[10:13]
	s_setprio 0
	s_setprio 1
	v_mfma_f32_16x16x32_bf16 v[54:57], v[154:157], v[170:173], v[54:57]
	v_mfma_f32_16x16x32_bf16 v[50:53], v[162:165], v[170:173], v[50:53]
	v_mfma_f32_16x16x32_bf16 v[38:41], v[154:157], v[178:181], v[38:41]
	v_mfma_f32_16x16x32_bf16 v[34:37], v[162:165], v[178:181], v[34:37]
	v_mfma_f32_16x16x32_bf16 v[22:25], v[154:157], v[186:189], v[22:25]
	v_mfma_f32_16x16x32_bf16 v[18:21], v[162:165], v[186:189], v[18:21]
	v_mfma_f32_16x16x32_bf16 v[6:9], v[154:157], v[194:197], v[6:9]
	v_mfma_f32_16x16x32_bf16 v[2:5], v[162:165], v[194:197], v[2:5]
	v_mfma_f32_16x16x32_bf16 v[54:57], v[158:161], v[174:177], v[54:57]
	v_mfma_f32_16x16x32_bf16 v[50:53], v[166:169], v[174:177], v[50:53]
	v_mfma_f32_16x16x32_bf16 v[38:41], v[158:161], v[182:185], v[38:41]
	v_mfma_f32_16x16x32_bf16 v[34:37], v[166:169], v[182:185], v[34:37]
	v_mfma_f32_16x16x32_bf16 v[22:25], v[158:161], v[190:193], v[22:25]
	v_mfma_f32_16x16x32_bf16 v[18:21], v[166:169], v[190:193], v[18:21]
	v_mfma_f32_16x16x32_bf16 v[6:9], v[158:161], v[198:201], v[6:9]
	v_mfma_f32_16x16x32_bf16 v[2:5], v[166:169], v[198:201], v[2:5]
	s_setprio 0
	s_barrier
	s_add_i32 s50, s50, 2
	s_add_u32 s2, s2, 0x100
	s_addc_u32 s3, s3, 0
	s_cmp_gt_u32 s50, 41
	s_cbranch_scc0 .LBB0_953
	s_cmpk_lt_u32 s25, 0x100
	s_cbranch_scc0 .LBB0_956
	s_barrier

.LBB0_1087:
	s_add_u32 s2, s6, 0x40080
	s_addc_u32 s3, s7, 0
	s_add_u32 s8, s8, 0x100
	s_addc_u32 s9, s9, 0
	s_mov_b32 s22, -2
	s_add_u32 s4, s2, 0xfffc0080
	s_addc_u32 s5, s3, -1
	s_add_i32 s23, 0, 0x10000
	s_cmp_eq_u32 s22, 12
	s_cselect_b32 s5, s49, s5
	s_cselect_b32 s4, s48, s4
	s_waitcnt vmcnt(0)
	v_add_u32_e32 v0, s23, v145
	s_cselect_b32 s7, s97, s9
	s_cselect_b32 s6, s96, s8
	s_add_i32 s25, 0, 0x14000
	ds_read_b128 v[146:149], v0
	ds_read_b128 v[152:155], v0 offset:1024
	ds_read_b128 v[156:159], v0 offset:2048
	ds_read_b128 v[160:163], v0 offset:3072
	v_add_u32_e32 v0, s25, v145
	ds_read_b128 v[164:167], v0
	ds_read_b128 v[168:171], v0 offset:1024
	ds_read_b128 v[172:175], v0 offset:2048
	ds_read_b128 v[176:179], v0 offset:3072
	v_mov_b32_e32 v0, v131
	ds_read_b128 v[180:183], v150
	ds_read_b128 v[184:187], v150 offset:1024
	ds_read_b128 v[188:191], v150 offset:2048
	ds_read_b128 v[192:195], v150 offset:3072
	ds_read_b128 v[196:199], v150 offset:4096
	ds_read_b128 v[200:203], v150 offset:5120
	ds_read_b128 v[204:207], v150 offset:6144
	ds_read_b128 v[208:211], v150 offset:7168
	s_add_i32 m0, s60, 0xc000
	s_nop 0
	global_load_lds_dwordx4 v0, s[2:3]
	v_mov_b32_e32 v0, v133
	s_add_i32 m0, s60, 0xe000
	s_nop 0
	global_load_lds_dwordx4 v0, s[2:3]
	s_waitcnt vmcnt(8)
	s_waitcnt lgkmcnt(0)
	s_barrier
	s_setprio 1
	s_waitcnt lgkmcnt(0)
	v_mfma_f32_16x16x32_bf16 v[126:129], v[146:149], v[180:183], 0
	v_mfma_f32_16x16x32_bf16 v[122:125], v[156:159], v[180:183], 0
	v_mfma_f32_16x16x32_bf16 v[110:113], v[146:149], v[188:191], 0
	v_mfma_f32_16x16x32_bf16 v[106:109], v[156:159], v[188:191], 0
	v_mfma_f32_16x16x32_bf16 v[94:97], v[146:149], v[196:199], 0
	v_mfma_f32_16x16x32_bf16 v[90:93], v[156:159], v[196:199], 0
	v_mfma_f32_16x16x32_bf16 v[78:81], v[146:149], v[204:207], 0
	v_mfma_f32_16x16x32_bf16 v[74:77], v[156:159], v[204:207], 0
	v_mfma_f32_16x16x32_bf16 v[126:129], v[152:155], v[184:187], v[126:129]
	v_mfma_f32_16x16x32_bf16 v[122:125], v[160:163], v[184:187], v[122:125]
	v_mfma_f32_16x16x32_bf16 v[110:113], v[152:155], v[192:195], v[110:113]
	v_mfma_f32_16x16x32_bf16 v[106:109], v[160:163], v[192:195], v[106:109]
	v_mfma_f32_16x16x32_bf16 v[94:97], v[152:155], v[200:203], v[94:97]
	v_mfma_f32_16x16x32_bf16 v[90:93], v[160:163], v[200:203], v[90:93]
	v_mfma_f32_16x16x32_bf16 v[78:81], v[152:155], v[208:211], v[78:81]
	v_mfma_f32_16x16x32_bf16 v[74:77], v[160:163], v[208:211], v[74:77]
	s_setprio 0
	s_setprio 1
	v_mfma_f32_16x16x32_bf16 v[118:121], v[164:167], v[180:183], 0
	v_mfma_f32_16x16x32_bf16 v[114:117], v[172:175], v[180:183], 0
	v_mfma_f32_16x16x32_bf16 v[102:105], v[164:167], v[188:191], 0
	v_mfma_f32_16x16x32_bf16 v[98:101], v[172:175], v[188:191], 0
	v_mfma_f32_16x16x32_bf16 v[86:89], v[164:167], v[196:199], 0
	v_mfma_f32_16x16x32_bf16 v[82:85], v[172:175], v[196:199], 0
	v_mfma_f32_16x16x32_bf16 v[70:73], v[164:167], v[204:207], 0
	v_mfma_f32_16x16x32_bf16 v[66:69], v[172:175], v[204:207], 0
	v_mfma_f32_16x16x32_bf16 v[118:121], v[168:171], v[184:187], v[118:121]
	v_mfma_f32_16x16x32_bf16 v[114:117], v[176:179], v[184:187], v[114:117]
	v_mfma_f32_16x16x32_bf16 v[102:105], v[168:171], v[192:195], v[102:105]
	v_mfma_f32_16x16x32_bf16 v[98:101], v[176:179], v[192:195], v[98:101]
	v_mfma_f32_16x16x32_bf16 v[86:89], v[168:171], v[200:203], v[86:89]
	v_mfma_f32_16x16x32_bf16 v[82:85], v[176:179], v[200:203], v[82:85]
	v_mfma_f32_16x16x32_bf16 v[70:73], v[168:171], v[208:211], v[70:73]
	v_mfma_f32_16x16x32_bf16 v[66:69], v[176:179], v[208:211], v[66:69]
	s_setprio 0
	s_barrier
	v_mov_b32_e32 v0, v137
	s_add_i32 s23, s23, s42
	ds_read_b128 v[180:183], v150 offset:16384
	ds_read_b128 v[184:187], v150 offset:17408
	ds_read_b128 v[188:191], v150 offset:18432
	ds_read_b128 v[192:195], v150 offset:19456
	ds_read_b128 v[196:199], v150 offset:20480
	ds_read_b128 v[200:203], v150 offset:21504
	ds_read_b128 v[204:207], v150 offset:22528
	ds_read_b128 v[208:211], v150 offset:23552
	s_mov_b32 m0, s23
	s_nop 0
	global_load_lds_dwordx4 v0, s[6:7]
	v_mov_b32_e32 v0, v139
	s_add_i32 m0, s23, 0x2000
	s_add_u32 s46, s6, 0x40000
	global_load_lds_dwordx4 v0, s[6:7]
	s_addc_u32 s47, s7, 0
	v_mov_b32_e32 v0, v137
	s_add_i32 s23, s25, s42
	s_mov_b32 m0, s23
	s_nop 0
	global_load_lds_dwordx4 v0, s[46:47]
	v_mov_b32_e32 v0, v139
	s_add_i32 m0, s23, 0x2000
	s_nop 0
	global_load_lds_dwordx4 v0, s[46:47]
	v_mov_b32_e32 v0, v131
	s_mov_b32 m0, s60
	s_nop 0
	global_load_lds_dwordx4 v0, s[4:5]
	v_mov_b32_e32 v0, v133
	s_mov_b32 m0, s61
	s_nop 0
	global_load_lds_dwordx4 v0, s[4:5]
	s_waitcnt vmcnt(8)
	s_waitcnt lgkmcnt(0)
	s_barrier
	s_setprio 1
	s_waitcnt lgkmcnt(0)
	v_mfma_f32_16x16x32_bf16 v[62:65], v[146:149], v[180:183], 0
	v_mfma_f32_16x16x32_bf16 v[58:61], v[156:159], v[180:183], 0
	v_mfma_f32_16x16x32_bf16 v[46:49], v[146:149], v[188:191], 0
	v_mfma_f32_16x16x32_bf16 v[42:45], v[156:159], v[188:191], 0
	v_mfma_f32_16x16x32_bf16 v[30:33], v[146:149], v[196:199], 0
	v_mfma_f32_16x16x32_bf16 v[26:29], v[156:159], v[196:199], 0
	v_mfma_f32_16x16x32_bf16 v[14:17], v[146:149], v[204:207], 0
	v_mfma_f32_16x16x32_bf16 v[10:13], v[156:159], v[204:207], 0
	v_mfma_f32_16x16x32_bf16 v[62:65], v[152:155], v[184:187], v[62:65]
	v_mfma_f32_16x16x32_bf16 v[58:61], v[160:163], v[184:187], v[58:61]
	v_mfma_f32_16x16x32_bf16 v[46:49], v[152:155], v[192:195], v[46:49]
	v_mfma_f32_16x16x32_bf16 v[42:45], v[160:163], v[192:195], v[42:45]
	v_mfma_f32_16x16x32_bf16 v[30:33], v[152:155], v[200:203], v[30:33]
	v_mfma_f32_16x16x32_bf16 v[26:29], v[160:163], v[200:203], v[26:29]
	v_mfma_f32_16x16x32_bf16 v[14:17], v[152:155], v[208:211], v[14:17]
	v_mfma_f32_16x16x32_bf16 v[10:13], v[160:163], v[208:211], v[10:13]
	s_setprio 0
	s_setprio 1
	v_mfma_f32_16x16x32_bf16 v[54:57], v[164:167], v[180:183], 0
	v_mfma_f32_16x16x32_bf16 v[50:53], v[172:175], v[180:183], 0
	v_mfma_f32_16x16x32_bf16 v[38:41], v[164:167], v[188:191], 0
	v_mfma_f32_16x16x32_bf16 v[34:37], v[172:175], v[188:191], 0
	v_mfma_f32_16x16x32_bf16 v[22:25], v[164:167], v[196:199], 0
	v_mfma_f32_16x16x32_bf16 v[18:21], v[172:175], v[196:199], 0
	v_mfma_f32_16x16x32_bf16 v[6:9], v[164:167], v[204:207], 0
	v_mfma_f32_16x16x32_bf16 v[2:5], v[172:175], v[204:207], 0
	v_mfma_f32_16x16x32_bf16 v[54:57], v[168:171], v[184:187], v[54:57]
	v_mfma_f32_16x16x32_bf16 v[50:53], v[176:179], v[184:187], v[50:53]
	v_mfma_f32_16x16x32_bf16 v[38:41], v[168:171], v[192:195], v[38:41]
	v_mfma_f32_16x16x32_bf16 v[34:37], v[176:179], v[192:195], v[34:37]
	v_mfma_f32_16x16x32_bf16 v[22:25], v[168:171], v[200:203], v[22:25]
	v_mfma_f32_16x16x32_bf16 v[18:21], v[176:179], v[200:203], v[18:21]
	v_mfma_f32_16x16x32_bf16 v[6:9], v[168:171], v[208:211], v[6:9]
	v_mfma_f32_16x16x32_bf16 v[2:5], v[176:179], v[208:211], v[2:5]
	s_setprio 0
	s_barrier
	s_add_i32 s23, 0, 0x18000
	v_add_u32_e32 v0, s23, v145
	s_add_i32 s25, 0, 0x1c000
	ds_read_b128 v[146:149], v0
	ds_read_b128 v[152:155], v0 offset:1024
	ds_read_b128 v[156:159], v0 offset:2048
	ds_read_b128 v[160:163], v0 offset:3072
	v_add_u32_e32 v0, s25, v145
	ds_read_b128 v[164:167], v0
	ds_read_b128 v[168:171], v0 offset:1024
	ds_read_b128 v[172:175], v0 offset:2048
	ds_read_b128 v[176:179], v0 offset:3072
	s_add_u32 s46, s4, 0x40000
	v_mov_b32_e32 v0, v131
	s_mov_b32 m0, s66
	ds_read_b128 v[180:183], v150 offset:32768
	ds_read_b128 v[184:187], v150 offset:33792
	ds_read_b128 v[188:191], v150 offset:34816
	ds_read_b128 v[192:195], v150 offset:35840
	ds_read_b128 v[196:199], v150 offset:36864
	ds_read_b128 v[200:203], v150 offset:37888
	ds_read_b128 v[204:207], v150 offset:38912
	ds_read_b128 v[208:211], v150 offset:39936
	s_addc_u32 s47, s5, 0
	s_nop 0
	global_load_lds_dwordx4 v0, s[46:47]
	v_mov_b32_e32 v0, v133
	s_mov_b32 m0, s67
	s_nop 0
	global_load_lds_dwordx4 v0, s[46:47]
	s_waitcnt vmcnt(8)
	s_waitcnt lgkmcnt(0)
	s_barrier
	s_setprio 1
	s_waitcnt lgkmcnt(0)
	v_mfma_f32_16x16x32_bf16 v[126:129], v[146:149], v[180:183], v[126:129]
	v_mfma_f32_16x16x32_bf16 v[122:125], v[156:159], v[180:183], v[122:125]
	v_mfma_f32_16x16x32_bf16 v[110:113], v[146:149], v[188:191], v[110:113]
	v_mfma_f32_16x16x32_bf16 v[106:109], v[156:159], v[188:191], v[106:109]
	v_mfma_f32_16x16x32_bf16 v[94:97], v[146:149], v[196:199], v[94:97]
	v_mfma_f32_16x16x32_bf16 v[90:93], v[156:159], v[196:199], v[90:93]
	v_mfma_f32_16x16x32_bf16 v[78:81], v[146:149], v[204:207], v[78:81]
	v_mfma_f32_16x16x32_bf16 v[74:77], v[156:159], v[204:207], v[74:77]
	v_mfma_f32_16x16x32_bf16 v[126:129], v[152:155], v[184:187], v[126:129]
	v_mfma_f32_16x16x32_bf16 v[122:125], v[160:163], v[184:187], v[122:125]
	v_mfma_f32_16x16x32_bf16 v[110:113], v[152:155], v[192:195], v[110:113]
	v_mfma_f32_16x16x32_bf16 v[106:109], v[160:163], v[192:195], v[106:109]
	v_mfma_f32_16x16x32_bf16 v[94:97], v[152:155], v[200:203], v[94:97]
	v_mfma_f32_16x16x32_bf16 v[90:93], v[160:163], v[200:203], v[90:93]
	v_mfma_f32_16x16x32_bf16 v[78:81], v[152:155], v[208:211], v[78:81]
	v_mfma_f32_16x16x32_bf16 v[74:77], v[160:163], v[208:211], v[74:77]
	s_setprio 0
	s_setprio 1
	v_mfma_f32_16x16x32_bf16 v[118:121], v[164:167], v[180:183], v[118:121]
	v_mfma_f32_16x16x32_bf16 v[114:117], v[172:175], v[180:183], v[114:117]
	v_mfma_f32_16x16x32_bf16 v[102:105], v[164:167], v[188:191], v[102:105]
	v_mfma_f32_16x16x32_bf16 v[98:101], v[172:175], v[188:191], v[98:101]
	v_mfma_f32_16x16x32_bf16 v[86:89], v[164:167], v[196:199], v[86:89]
	v_mfma_f32_16x16x32_bf16 v[82:85], v[172:175], v[196:199], v[82:85]
	v_mfma_f32_16x16x32_bf16 v[70:73], v[164:167], v[204:207], v[70:73]
	v_mfma_f32_16x16x32_bf16 v[66:69], v[172:175], v[204:207], v[66:69]
	v_mfma_f32_16x16x32_bf16 v[118:121], v[168:171], v[184:187], v[118:121]
	v_mfma_f32_16x16x32_bf16 v[114:117], v[176:179], v[184:187], v[114:117]
	v_mfma_f32_16x16x32_bf16 v[102:105], v[168:171], v[192:195], v[102:105]
	v_mfma_f32_16x16x32_bf16 v[98:101], v[176:179], v[192:195], v[98:101]
	v_mfma_f32_16x16x32_bf16 v[86:89], v[168:171], v[200:203], v[86:89]
	v_mfma_f32_16x16x32_bf16 v[82:85], v[176:179], v[200:203], v[82:85]
	v_mfma_f32_16x16x32_bf16 v[70:73], v[168:171], v[208:211], v[70:73]
	v_mfma_f32_16x16x32_bf16 v[66:69], v[176:179], v[208:211], v[66:69]
	s_setprio 0
	s_barrier
	v_mov_b32_e32 v0, v137
	ds_read_b128 v[180:183], v150 offset:49152
	ds_read_b128 v[184:187], v150 offset:50176
	ds_read_b128 v[188:191], v150 offset:51200
	ds_read_b128 v[192:195], v150 offset:52224
	ds_read_b128 v[196:199], v150 offset:53248
	ds_read_b128 v[200:203], v150 offset:54272
	ds_read_b128 v[204:207], v150 offset:55296
	ds_read_b128 v[208:211], v150 offset:56320
	s_add_i32 s23, s23, s42
	s_add_u32 s100, s6, s38
	s_addc_u32 s101, s7, s39
	s_mov_b32 m0, s23
	v_mov_b32_e32 v0, v139
	global_load_lds_dwordx4 v137, s[100:101]
	s_add_i32 m0, s23, 0x2000
	s_nop 0
	s_add_u32 s6, s6, 0x40080
	s_addc_u32 s7, s7, 0
	v_mov_b32_e32 v0, v137
	s_add_i32 s23, s25, s42
	global_load_lds_dwordx4 v139, s[100:101]
	s_mov_b32 m0, s23
	s_nop 0
	global_load_lds_dwordx4 v0, s[6:7]
	v_mov_b32_e32 v0, v139
	s_add_i32 m0, s23, 0x2000
	s_nop 0
	global_load_lds_dwordx4 v0, s[6:7]
	v_mov_b32_e32 v0, v131
	s_mov_b32 m0, s70
	s_add_u32 s100, s4, s38
	s_addc_u32 s101, s5, s39
	v_mov_b32_e32 v0, v133
	global_load_lds_dwordx4 v131, s[100:101]
	s_mov_b32 m0, s71
	s_nop 0
	global_load_lds_dwordx4 v133, s[100:101]
	s_waitcnt vmcnt(8)
	s_waitcnt lgkmcnt(0)
	s_barrier
	s_setprio 1
	s_waitcnt lgkmcnt(0)
	v_mfma_f32_16x16x32_bf16 v[62:65], v[146:149], v[180:183], v[62:65]
	v_mfma_f32_16x16x32_bf16 v[58:61], v[156:159], v[180:183], v[58:61]
	v_mfma_f32_16x16x32_bf16 v[46:49], v[146:149], v[188:191], v[46:49]
	v_mfma_f32_16x16x32_bf16 v[42:45], v[156:159], v[188:191], v[42:45]
	v_mfma_f32_16x16x32_bf16 v[30:33], v[146:149], v[196:199], v[30:33]
	v_mfma_f32_16x16x32_bf16 v[26:29], v[156:159], v[196:199], v[26:29]
	v_mfma_f32_16x16x32_bf16 v[14:17], v[146:149], v[204:207], v[14:17]
	v_mfma_f32_16x16x32_bf16 v[10:13], v[156:159], v[204:207], v[10:13]
	v_mfma_f32_16x16x32_bf16 v[62:65], v[152:155], v[184:187], v[62:65]
	v_mfma_f32_16x16x32_bf16 v[58:61], v[160:163], v[184:187], v[58:61]
	v_mfma_f32_16x16x32_bf16 v[46:49], v[152:155], v[192:195], v[46:49]
	v_mfma_f32_16x16x32_bf16 v[42:45], v[160:163], v[192:195], v[42:45]
	v_mfma_f32_16x16x32_bf16 v[30:33], v[152:155], v[200:203], v[30:33]
	v_mfma_f32_16x16x32_bf16 v[26:29], v[160:163], v[200:203], v[26:29]
	v_mfma_f32_16x16x32_bf16 v[14:17], v[152:155], v[208:211], v[14:17]
	v_mfma_f32_16x16x32_bf16 v[10:13], v[160:163], v[208:211], v[10:13]
	s_setprio 0
	s_setprio 1
	v_mfma_f32_16x16x32_bf16 v[54:57], v[164:167], v[180:183], v[54:57]
	v_mfma_f32_16x16x32_bf16 v[50:53], v[172:175], v[180:183], v[50:53]
	v_mfma_f32_16x16x32_bf16 v[38:41], v[164:167], v[188:191], v[38:41]
	v_mfma_f32_16x16x32_bf16 v[34:37], v[172:175], v[188:191], v[34:37]
	v_mfma_f32_16x16x32_bf16 v[22:25], v[164:167], v[196:199], v[22:25]
	v_mfma_f32_16x16x32_bf16 v[18:21], v[172:175], v[196:199], v[18:21]
	v_mfma_f32_16x16x32_bf16 v[6:9], v[164:167], v[204:207], v[6:9]
	v_mfma_f32_16x16x32_bf16 v[2:5], v[172:175], v[204:207], v[2:5]
	v_mfma_f32_16x16x32_bf16 v[54:57], v[168:171], v[184:187], v[54:57]
	v_mfma_f32_16x16x32_bf16 v[50:53], v[176:179], v[184:187], v[50:53]
	v_mfma_f32_16x16x32_bf16 v[38:41], v[168:171], v[192:195], v[38:41]
	v_mfma_f32_16x16x32_bf16 v[34:37], v[176:179], v[192:195], v[34:37]
	v_mfma_f32_16x16x32_bf16 v[22:25], v[168:171], v[200:203], v[22:25]
	v_mfma_f32_16x16x32_bf16 v[18:21], v[176:179], v[200:203], v[18:21]
	v_mfma_f32_16x16x32_bf16 v[6:9], v[168:171], v[208:211], v[6:9]
	v_mfma_f32_16x16x32_bf16 v[2:5], v[176:179], v[208:211], v[2:5]
	s_setprio 0
	s_barrier
	s_add_i32 s22, s22, 2
	s_add_u32 s2, s2, 0x100
	s_addc_u32 s3, s3, 0
	s_add_u32 s8, s8, 0x100
	s_addc_u32 s9, s9, 0
	s_cmp_gt_u32 s22, 13
	s_cbranch_scc0 .LBB0_1088
	s_branch .Lpeel_exit_1088
.LBB0_1088:
	s_add_u32 s4, s2, 0xfffc0080
	s_addc_u32 s5, s3, -1
	s_add_i32 s23, 0, 0x10000
	s_cmp_eq_u32 s22, 12
	s_cselect_b32 s5, s49, s5
	s_cselect_b32 s4, s48, s4
	v_add_u32_e32 v0, s23, v145
	s_cselect_b32 s7, s97, s9
	s_cselect_b32 s6, s96, s8
	s_add_i32 s25, 0, 0x14000
	ds_read_b128 v[146:149], v0
	ds_read_b128 v[152:155], v0 offset:1024
	ds_read_b128 v[156:159], v0 offset:2048
	ds_read_b128 v[160:163], v0 offset:3072
	v_add_u32_e32 v0, s25, v145
	ds_read_b128 v[164:167], v0
	ds_read_b128 v[168:171], v0 offset:1024
	ds_read_b128 v[172:175], v0 offset:2048
	ds_read_b128 v[176:179], v0 offset:3072
	v_mov_b32_e32 v0, v131
	ds_read_b128 v[180:183], v150
	ds_read_b128 v[184:187], v150 offset:1024
	ds_read_b128 v[188:191], v150 offset:2048
	ds_read_b128 v[192:195], v150 offset:3072
	ds_read_b128 v[196:199], v150 offset:4096
	ds_read_b128 v[200:203], v150 offset:5120
	ds_read_b128 v[204:207], v150 offset:6144
	ds_read_b128 v[208:211], v150 offset:7168
	s_add_i32 m0, s60, 0xc000
	s_nop 0
	global_load_lds_dwordx4 v0, s[2:3]
	v_mov_b32_e32 v0, v133
	s_add_i32 m0, s60, 0xe000
	s_nop 0
	global_load_lds_dwordx4 v0, s[2:3]
	s_waitcnt vmcnt(8)
	s_waitcnt lgkmcnt(0)
	s_barrier
	s_setprio 1
	s_waitcnt lgkmcnt(0)
	v_mfma_f32_16x16x32_bf16 v[126:129], v[146:149], v[180:183], v[126:129]
	v_mfma_f32_16x16x32_bf16 v[122:125], v[156:159], v[180:183], v[122:125]
	v_mfma_f32_16x16x32_bf16 v[110:113], v[146:149], v[188:191], v[110:113]
	v_mfma_f32_16x16x32_bf16 v[106:109], v[156:159], v[188:191], v[106:109]
	v_mfma_f32_16x16x32_bf16 v[94:97], v[146:149], v[196:199], v[94:97]
	v_mfma_f32_16x16x32_bf16 v[90:93], v[156:159], v[196:199], v[90:93]
	v_mfma_f32_16x16x32_bf16 v[78:81], v[146:149], v[204:207], v[78:81]
	v_mfma_f32_16x16x32_bf16 v[74:77], v[156:159], v[204:207], v[74:77]
	v_mfma_f32_16x16x32_bf16 v[126:129], v[152:155], v[184:187], v[126:129]
	v_mfma_f32_16x16x32_bf16 v[122:125], v[160:163], v[184:187], v[122:125]
	v_mfma_f32_16x16x32_bf16 v[110:113], v[152:155], v[192:195], v[110:113]
	v_mfma_f32_16x16x32_bf16 v[106:109], v[160:163], v[192:195], v[106:109]
	v_mfma_f32_16x16x32_bf16 v[94:97], v[152:155], v[200:203], v[94:97]
	v_mfma_f32_16x16x32_bf16 v[90:93], v[160:163], v[200:203], v[90:93]
	v_mfma_f32_16x16x32_bf16 v[78:81], v[152:155], v[208:211], v[78:81]
	v_mfma_f32_16x16x32_bf16 v[74:77], v[160:163], v[208:211], v[74:77]
	s_setprio 0
	s_setprio 1
	v_mfma_f32_16x16x32_bf16 v[118:121], v[164:167], v[180:183], v[118:121]
	v_mfma_f32_16x16x32_bf16 v[114:117], v[172:175], v[180:183], v[114:117]
	v_mfma_f32_16x16x32_bf16 v[102:105], v[164:167], v[188:191], v[102:105]
	v_mfma_f32_16x16x32_bf16 v[98:101], v[172:175], v[188:191], v[98:101]
	v_mfma_f32_16x16x32_bf16 v[86:89], v[164:167], v[196:199], v[86:89]
	v_mfma_f32_16x16x32_bf16 v[82:85], v[172:175], v[196:199], v[82:85]
	v_mfma_f32_16x16x32_bf16 v[70:73], v[164:167], v[204:207], v[70:73]
	v_mfma_f32_16x16x32_bf16 v[66:69], v[172:175], v[204:207], v[66:69]
	v_mfma_f32_16x16x32_bf16 v[118:121], v[168:171], v[184:187], v[118:121]
	v_mfma_f32_16x16x32_bf16 v[114:117], v[176:179], v[184:187], v[114:117]
	v_mfma_f32_16x16x32_bf16 v[102:105], v[168:171], v[192:195], v[102:105]
	v_mfma_f32_16x16x32_bf16 v[98:101], v[176:179], v[192:195], v[98:101]
	v_mfma_f32_16x16x32_bf16 v[86:89], v[168:171], v[200:203], v[86:89]
	v_mfma_f32_16x16x32_bf16 v[82:85], v[176:179], v[200:203], v[82:85]
	v_mfma_f32_16x16x32_bf16 v[70:73], v[168:171], v[208:211], v[70:73]
	v_mfma_f32_16x16x32_bf16 v[66:69], v[176:179], v[208:211], v[66:69]
	s_setprio 0
	s_barrier
	v_mov_b32_e32 v0, v137
	s_add_i32 s23, s23, s42
	ds_read_b128 v[180:183], v150 offset:16384
	ds_read_b128 v[184:187], v150 offset:17408
	ds_read_b128 v[188:191], v150 offset:18432
	ds_read_b128 v[192:195], v150 offset:19456
	ds_read_b128 v[196:199], v150 offset:20480
	ds_read_b128 v[200:203], v150 offset:21504
	ds_read_b128 v[204:207], v150 offset:22528
	ds_read_b128 v[208:211], v150 offset:23552
	s_mov_b32 m0, s23
	s_nop 0
	global_load_lds_dwordx4 v0, s[6:7]
	v_mov_b32_e32 v0, v139
	s_add_i32 m0, s23, 0x2000
	s_add_u32 s46, s6, 0x40000
	global_load_lds_dwordx4 v0, s[6:7]
	s_addc_u32 s47, s7, 0
	v_mov_b32_e32 v0, v137
	s_add_i32 s23, s25, s42
	s_mov_b32 m0, s23
	s_nop 0
	global_load_lds_dwordx4 v0, s[46:47]
	v_mov_b32_e32 v0, v139
	s_add_i32 m0, s23, 0x2000
	s_nop 0
	global_load_lds_dwordx4 v0, s[46:47]
	v_mov_b32_e32 v0, v131
	s_mov_b32 m0, s60
	s_nop 0
	global_load_lds_dwordx4 v0, s[4:5]
	v_mov_b32_e32 v0, v133
	s_mov_b32 m0, s61
	s_nop 0
	global_load_lds_dwordx4 v0, s[4:5]
	s_waitcnt vmcnt(8)
	s_waitcnt lgkmcnt(0)
	s_barrier
	s_setprio 1
	s_waitcnt lgkmcnt(0)
	v_mfma_f32_16x16x32_bf16 v[62:65], v[146:149], v[180:183], v[62:65]
	v_mfma_f32_16x16x32_bf16 v[58:61], v[156:159], v[180:183], v[58:61]
	v_mfma_f32_16x16x32_bf16 v[46:49], v[146:149], v[188:191], v[46:49]
	v_mfma_f32_16x16x32_bf16 v[42:45], v[156:159], v[188:191], v[42:45]
	v_mfma_f32_16x16x32_bf16 v[30:33], v[146:149], v[196:199], v[30:33]
	v_mfma_f32_16x16x32_bf16 v[26:29], v[156:159], v[196:199], v[26:29]
	v_mfma_f32_16x16x32_bf16 v[14:17], v[146:149], v[204:207], v[14:17]
	v_mfma_f32_16x16x32_bf16 v[10:13], v[156:159], v[204:207], v[10:13]
	v_mfma_f32_16x16x32_bf16 v[62:65], v[152:155], v[184:187], v[62:65]
	v_mfma_f32_16x16x32_bf16 v[58:61], v[160:163], v[184:187], v[58:61]
	v_mfma_f32_16x16x32_bf16 v[46:49], v[152:155], v[192:195], v[46:49]
	v_mfma_f32_16x16x32_bf16 v[42:45], v[160:163], v[192:195], v[42:45]
	v_mfma_f32_16x16x32_bf16 v[30:33], v[152:155], v[200:203], v[30:33]
	v_mfma_f32_16x16x32_bf16 v[26:29], v[160:163], v[200:203], v[26:29]
	v_mfma_f32_16x16x32_bf16 v[14:17], v[152:155], v[208:211], v[14:17]
	v_mfma_f32_16x16x32_bf16 v[10:13], v[160:163], v[208:211], v[10:13]
	s_setprio 0
	s_setprio 1
	v_mfma_f32_16x16x32_bf16 v[54:57], v[164:167], v[180:183], v[54:57]
	v_mfma_f32_16x16x32_bf16 v[50:53], v[172:175], v[180:183], v[50:53]
	v_mfma_f32_16x16x32_bf16 v[38:41], v[164:167], v[188:191], v[38:41]
	v_mfma_f32_16x16x32_bf16 v[34:37], v[172:175], v[188:191], v[34:37]
	v_mfma_f32_16x16x32_bf16 v[22:25], v[164:167], v[196:199], v[22:25]
	v_mfma_f32_16x16x32_bf16 v[18:21], v[172:175], v[196:199], v[18:21]
	v_mfma_f32_16x16x32_bf16 v[6:9], v[164:167], v[204:207], v[6:9]
	v_mfma_f32_16x16x32_bf16 v[2:5], v[172:175], v[204:207], v[2:5]
	v_mfma_f32_16x16x32_bf16 v[54:57], v[168:171], v[184:187], v[54:57]
	v_mfma_f32_16x16x32_bf16 v[50:53], v[176:179], v[184:187], v[50:53]
	v_mfma_f32_16x16x32_bf16 v[38:41], v[168:171], v[192:195], v[38:41]
	v_mfma_f32_16x16x32_bf16 v[34:37], v[176:179], v[192:195], v[34:37]
	v_mfma_f32_16x16x32_bf16 v[22:25], v[168:171], v[200:203], v[22:25]
	v_mfma_f32_16x16x32_bf16 v[18:21], v[176:179], v[200:203], v[18:21]
	v_mfma_f32_16x16x32_bf16 v[6:9], v[168:171], v[208:211], v[6:9]
	v_mfma_f32_16x16x32_bf16 v[2:5], v[176:179], v[208:211], v[2:5]
	s_setprio 0
	s_barrier
	s_add_i32 s23, 0, 0x18000
	v_add_u32_e32 v0, s23, v145
	s_add_i32 s25, 0, 0x1c000
	ds_read_b128 v[146:149], v0
	ds_read_b128 v[152:155], v0 offset:1024
	ds_read_b128 v[156:159], v0 offset:2048
	ds_read_b128 v[160:163], v0 offset:3072
	v_add_u32_e32 v0, s25, v145
	ds_read_b128 v[164:167], v0
	ds_read_b128 v[168:171], v0 offset:1024
	ds_read_b128 v[172:175], v0 offset:2048
	ds_read_b128 v[176:179], v0 offset:3072
	s_add_u32 s46, s4, 0x40000
	v_mov_b32_e32 v0, v131
	s_mov_b32 m0, s66
	ds_read_b128 v[180:183], v150 offset:32768
	ds_read_b128 v[184:187], v150 offset:33792
	ds_read_b128 v[188:191], v150 offset:34816
	ds_read_b128 v[192:195], v150 offset:35840
	ds_read_b128 v[196:199], v150 offset:36864
	ds_read_b128 v[200:203], v150 offset:37888
	ds_read_b128 v[204:207], v150 offset:38912
	ds_read_b128 v[208:211], v150 offset:39936
	s_addc_u32 s47, s5, 0
	s_nop 0
	global_load_lds_dwordx4 v0, s[46:47]
	v_mov_b32_e32 v0, v133
	s_mov_b32 m0, s67
	s_nop 0
	global_load_lds_dwordx4 v0, s[46:47]
	s_waitcnt vmcnt(8)
	s_waitcnt lgkmcnt(0)
	s_barrier
	s_setprio 1
	s_waitcnt lgkmcnt(0)
	v_mfma_f32_16x16x32_bf16 v[126:129], v[146:149], v[180:183], v[126:129]
	v_mfma_f32_16x16x32_bf16 v[122:125], v[156:159], v[180:183], v[122:125]
	v_mfma_f32_16x16x32_bf16 v[110:113], v[146:149], v[188:191], v[110:113]
	v_mfma_f32_16x16x32_bf16 v[106:109], v[156:159], v[188:191], v[106:109]
	v_mfma_f32_16x16x32_bf16 v[94:97], v[146:149], v[196:199], v[94:97]
	v_mfma_f32_16x16x32_bf16 v[90:93], v[156:159], v[196:199], v[90:93]
	v_mfma_f32_16x16x32_bf16 v[78:81], v[146:149], v[204:207], v[78:81]
	v_mfma_f32_16x16x32_bf16 v[74:77], v[156:159], v[204:207], v[74:77]
	v_mfma_f32_16x16x32_bf16 v[126:129], v[152:155], v[184:187], v[126:129]
	v_mfma_f32_16x16x32_bf16 v[122:125], v[160:163], v[184:187], v[122:125]
	v_mfma_f32_16x16x32_bf16 v[110:113], v[152:155], v[192:195], v[110:113]
	v_mfma_f32_16x16x32_bf16 v[106:109], v[160:163], v[192:195], v[106:109]
	v_mfma_f32_16x16x32_bf16 v[94:97], v[152:155], v[200:203], v[94:97]
	v_mfma_f32_16x16x32_bf16 v[90:93], v[160:163], v[200:203], v[90:93]
	v_mfma_f32_16x16x32_bf16 v[78:81], v[152:155], v[208:211], v[78:81]
	v_mfma_f32_16x16x32_bf16 v[74:77], v[160:163], v[208:211], v[74:77]
	s_setprio 0
	s_setprio 1
	v_mfma_f32_16x16x32_bf16 v[118:121], v[164:167], v[180:183], v[118:121]
	v_mfma_f32_16x16x32_bf16 v[114:117], v[172:175], v[180:183], v[114:117]
	v_mfma_f32_16x16x32_bf16 v[102:105], v[164:167], v[188:191], v[102:105]
	v_mfma_f32_16x16x32_bf16 v[98:101], v[172:175], v[188:191], v[98:101]
	v_mfma_f32_16x16x32_bf16 v[86:89], v[164:167], v[196:199], v[86:89]
	v_mfma_f32_16x16x32_bf16 v[82:85], v[172:175], v[196:199], v[82:85]
	v_mfma_f32_16x16x32_bf16 v[70:73], v[164:167], v[204:207], v[70:73]
	v_mfma_f32_16x16x32_bf16 v[66:69], v[172:175], v[204:207], v[66:69]
	v_mfma_f32_16x16x32_bf16 v[118:121], v[168:171], v[184:187], v[118:121]
	v_mfma_f32_16x16x32_bf16 v[114:117], v[176:179], v[184:187], v[114:117]
	v_mfma_f32_16x16x32_bf16 v[102:105], v[168:171], v[192:195], v[102:105]
	v_mfma_f32_16x16x32_bf16 v[98:101], v[176:179], v[192:195], v[98:101]
	v_mfma_f32_16x16x32_bf16 v[86:89], v[168:171], v[200:203], v[86:89]
	v_mfma_f32_16x16x32_bf16 v[82:85], v[176:179], v[200:203], v[82:85]
	v_mfma_f32_16x16x32_bf16 v[70:73], v[168:171], v[208:211], v[70:73]
	v_mfma_f32_16x16x32_bf16 v[66:69], v[176:179], v[208:211], v[66:69]
	s_setprio 0
	s_barrier
	v_mov_b32_e32 v0, v137
	ds_read_b128 v[180:183], v150 offset:49152
	ds_read_b128 v[184:187], v150 offset:50176
	ds_read_b128 v[188:191], v150 offset:51200
	ds_read_b128 v[192:195], v150 offset:52224
	ds_read_b128 v[196:199], v150 offset:53248
	ds_read_b128 v[200:203], v150 offset:54272
	ds_read_b128 v[204:207], v150 offset:55296
	ds_read_b128 v[208:211], v150 offset:56320
	s_add_i32 s23, s23, s42
	s_add_u32 s100, s6, s38
	s_addc_u32 s101, s7, s39
	s_mov_b32 m0, s23
	v_mov_b32_e32 v0, v139
	global_load_lds_dwordx4 v137, s[100:101]
	s_add_i32 m0, s23, 0x2000
	s_nop 0
	s_add_u32 s6, s6, 0x40080
	s_addc_u32 s7, s7, 0
	v_mov_b32_e32 v0, v137
	s_add_i32 s23, s25, s42
	global_load_lds_dwordx4 v139, s[100:101]
	s_mov_b32 m0, s23
	s_nop 0
	global_load_lds_dwordx4 v0, s[6:7]
	v_mov_b32_e32 v0, v139
	s_add_i32 m0, s23, 0x2000
	s_nop 0
	global_load_lds_dwordx4 v0, s[6:7]
	v_mov_b32_e32 v0, v131
	s_mov_b32 m0, s70
	s_add_u32 s100, s4, s38
	s_addc_u32 s101, s5, s39
	v_mov_b32_e32 v0, v133
	global_load_lds_dwordx4 v131, s[100:101]
	s_mov_b32 m0, s71
	s_nop 0
	global_load_lds_dwordx4 v133, s[100:101]
	s_waitcnt vmcnt(8)
	s_waitcnt lgkmcnt(0)
	s_barrier
	s_setprio 1
	s_waitcnt lgkmcnt(0)
	v_mfma_f32_16x16x32_bf16 v[62:65], v[146:149], v[180:183], v[62:65]
	v_mfma_f32_16x16x32_bf16 v[58:61], v[156:159], v[180:183], v[58:61]
	v_mfma_f32_16x16x32_bf16 v[46:49], v[146:149], v[188:191], v[46:49]
	v_mfma_f32_16x16x32_bf16 v[42:45], v[156:159], v[188:191], v[42:45]
	v_mfma_f32_16x16x32_bf16 v[30:33], v[146:149], v[196:199], v[30:33]
	v_mfma_f32_16x16x32_bf16 v[26:29], v[156:159], v[196:199], v[26:29]
	v_mfma_f32_16x16x32_bf16 v[14:17], v[146:149], v[204:207], v[14:17]
	v_mfma_f32_16x16x32_bf16 v[10:13], v[156:159], v[204:207], v[10:13]
	v_mfma_f32_16x16x32_bf16 v[62:65], v[152:155], v[184:187], v[62:65]
	v_mfma_f32_16x16x32_bf16 v[58:61], v[160:163], v[184:187], v[58:61]
	v_mfma_f32_16x16x32_bf16 v[46:49], v[152:155], v[192:195], v[46:49]
	v_mfma_f32_16x16x32_bf16 v[42:45], v[160:163], v[192:195], v[42:45]
	v_mfma_f32_16x16x32_bf16 v[30:33], v[152:155], v[200:203], v[30:33]
	v_mfma_f32_16x16x32_bf16 v[26:29], v[160:163], v[200:203], v[26:29]
	v_mfma_f32_16x16x32_bf16 v[14:17], v[152:155], v[208:211], v[14:17]
	v_mfma_f32_16x16x32_bf16 v[10:13], v[160:163], v[208:211], v[10:13]
	s_setprio 0
	s_setprio 1
	v_mfma_f32_16x16x32_bf16 v[54:57], v[164:167], v[180:183], v[54:57]
	v_mfma_f32_16x16x32_bf16 v[50:53], v[172:175], v[180:183], v[50:53]
	v_mfma_f32_16x16x32_bf16 v[38:41], v[164:167], v[188:191], v[38:41]
	v_mfma_f32_16x16x32_bf16 v[34:37], v[172:175], v[188:191], v[34:37]
	v_mfma_f32_16x16x32_bf16 v[22:25], v[164:167], v[196:199], v[22:25]
	v_mfma_f32_16x16x32_bf16 v[18:21], v[172:175], v[196:199], v[18:21]
	v_mfma_f32_16x16x32_bf16 v[6:9], v[164:167], v[204:207], v[6:9]
	v_mfma_f32_16x16x32_bf16 v[2:5], v[172:175], v[204:207], v[2:5]
	v_mfma_f32_16x16x32_bf16 v[54:57], v[168:171], v[184:187], v[54:57]
	v_mfma_f32_16x16x32_bf16 v[50:53], v[176:179], v[184:187], v[50:53]
	v_mfma_f32_16x16x32_bf16 v[38:41], v[168:171], v[192:195], v[38:41]
	v_mfma_f32_16x16x32_bf16 v[34:37], v[176:179], v[192:195], v[34:37]
	v_mfma_f32_16x16x32_bf16 v[22:25], v[168:171], v[200:203], v[22:25]
	v_mfma_f32_16x16x32_bf16 v[18:21], v[176:179], v[200:203], v[18:21]
	v_mfma_f32_16x16x32_bf16 v[6:9], v[168:171], v[208:211], v[6:9]
	v_mfma_f32_16x16x32_bf16 v[2:5], v[176:179], v[208:211], v[2:5]
	s_setprio 0
	s_barrier
	s_add_i32 s22, s22, 2
	s_add_u32 s2, s2, 0x100
	s_addc_u32 s3, s3, 0
	s_add_u32 s8, s8, 0x100
	s_addc_u32 s9, s9, 0
	s_cmp_gt_u32 s22, 13
	s_cbranch_scc0 .LBB0_1088

.LBB0_1335:
	s_add_i32 s4, s58, -1
	s_add_i32 s5, s79, 0x8000
	s_lshr_b32 s4, s4, 2
	s_and_b32 s24, s5, 0x18000
	v_mad_u64_u32 v[64:65], s[4:5], s4, v239, v[214:215]
	s_lshl_b32 s26, s24, 1
	v_lshl_add_u64 v[64:65], v[64:65], 0, s[26:27]
	s_add_i32 s4, s64, s75
	s_mov_b32 s5, m0
	s_mov_b32 m0, s4
	s_nop 0
	global_load_lds_dwordx4 v[64:65], off
	s_mov_b32 m0, s5
	ds_read_b128 v[64:67], v14
	ds_read_b128 v[68:71], v14 offset:32
	ds_read_b128 v[72:75], v14 offset:64
	ds_read_b128 v[76:79], v14 offset:96
	ds_read_b128 v[160:163], v14 offset:128
	ds_read_b128 v[164:167], v14 offset:160
	ds_read_b128 v[168:171], v14 offset:192
	ds_read_b128 v[172:175], v14 offset:224
	s_add_i32 s59, s65, s58
	s_add_i32 s4, s59, -2
	s_waitcnt lgkmcnt(4)
	v_add_f32_e32 v94, v126, v78
	v_add_f32_e32 v95, v127, v79
	v_add_f32_e32 v90, v122, v74
	v_add_f32_e32 v91, v123, v75
	v_add_f32_e32 v86, v118, v70
	v_add_f32_e32 v87, v119, v71
	v_add_f32_e32 v82, v114, v66
	v_add_f32_e32 v83, v115, v67
	v_add_f32_e32 v92, v124, v76
	v_add_f32_e32 v93, v125, v77
	v_add_f32_e32 v88, v120, v72
	v_add_f32_e32 v89, v121, v73
	v_add_f32_e32 v84, v116, v68
	v_add_f32_e32 v85, v117, v69
	v_add_f32_e32 v80, v112, v64
	v_add_f32_e32 v81, v113, v65
	s_waitcnt lgkmcnt(0)
	v_add_f32_e32 v78, v110, v174
	v_add_f32_e32 v79, v111, v175
	v_add_f32_e32 v74, v106, v170
	v_add_f32_e32 v75, v107, v171
	v_add_f32_e32 v70, v102, v166
	v_add_f32_e32 v71, v103, v167
	v_add_f32_e32 v66, v98, v162
	v_add_f32_e32 v67, v99, v163
	v_add_f32_e32 v76, v108, v172
	v_add_f32_e32 v77, v109, v173
	v_add_f32_e32 v72, v104, v168
	v_add_f32_e32 v73, v105, v169
	v_add_f32_e32 v68, v100, v164
	v_add_f32_e32 v69, v101, v165
	s_cmp_lt_i32 s4, 0
	v_add_f32_e32 v64, v96, v160
	v_add_f32_e32 v65, v97, v161
	s_cbranch_scc1 .LBB0_1337
	s_lshl_b32 s100, s4, 6
	s_add_i32 s100, s100, 63
	s_lshl_b32 s101, s33, 5
	s_cmp_le_i32 s100, s101
	s_cbranch_scc1 .LBB0_1337
	v_add_u32_e32 v97, 0xffffffa5, v0
	v_add_u32_e32 v96, 0xffffff85, v0
	v_cmp_le_i32_e32 vcc, v97, v227
	s_nop 1
	v_cndmask_b32_e32 v64, v238, v64, vcc
	v_cmp_lt_i32_e32 vcc, v96, v227
	s_nop 1
	v_cndmask_b32_e32 v81, v238, v81, vcc
	v_cmp_le_i32_e32 vcc, v96, v227
	v_add_u32_e32 v96, 0xffffffa6, v0
	s_nop 0
	v_cndmask_b32_e32 v80, v238, v80, vcc
	v_cmp_le_i32_e32 vcc, v96, v227
	v_add_u32_e32 v96, 0xffffff87, v0
	s_nop 0
	v_cndmask_b32_e32 v65, v238, v65, vcc
	v_cmp_le_i32_e32 vcc, v96, v227
	v_add_u32_e32 v96, 0xffffffa7, v0
	s_nop 0
	v_cndmask_b32_e32 v82, v238, v82, vcc
	v_cmp_le_i32_e32 vcc, v96, v227
	v_add_u32_e32 v96, 0xffffff88, v0
	s_nop 0
	v_cndmask_b32_e32 v66, v238, v66, vcc
	v_cmp_le_i32_e32 vcc, v96, v227
	v_add_u32_e32 v96, 0xffffffa8, v0
	s_nop 0
	v_cndmask_b32_e32 v83, v238, v83, vcc
	v_cmp_le_i32_e32 vcc, v96, v227
	v_add_u32_e32 v96, 0xffffff8d, v0
	s_nop 0
	v_cndmask_b32_e32 v67, v238, v67, vcc
	v_cmp_le_i32_e32 vcc, v96, v227
	v_add_u32_e32 v96, 0xffffffad, v0
	s_nop 0
	v_cndmask_b32_e32 v84, v238, v84, vcc
	v_cmp_le_i32_e32 vcc, v96, v227
	v_add_u32_e32 v96, 0xffffff8e, v0
	s_nop 0
	v_cndmask_b32_e32 v68, v238, v68, vcc
	v_cmp_le_i32_e32 vcc, v96, v227
	v_add_u32_e32 v96, 0xffffffae, v0
	s_nop 0
	v_cndmask_b32_e32 v85, v238, v85, vcc
	v_cmp_le_i32_e32 vcc, v96, v227
	v_add_u32_e32 v96, 0xffffff8f, v0
	s_nop 0
	v_cndmask_b32_e32 v69, v238, v69, vcc
	v_cmp_le_i32_e32 vcc, v96, v227
	v_add_u32_e32 v96, 0xffffffaf, v0
	s_nop 0
	v_cndmask_b32_e32 v86, v238, v86, vcc
	v_cmp_le_i32_e32 vcc, v96, v227
	v_add_u32_e32 v96, 0xffffff90, v0
	s_nop 0
	v_cndmask_b32_e32 v70, v238, v70, vcc
	v_cmp_le_i32_e32 vcc, v96, v227
	v_add_u32_e32 v96, 0xffffffb0, v0
	s_nop 0
	v_cndmask_b32_e32 v87, v238, v87, vcc
	v_cmp_le_i32_e32 vcc, v96, v227
	v_add_u32_e32 v96, 0xffffff95, v0
	s_nop 0
	v_cndmask_b32_e32 v71, v238, v71, vcc
	v_cmp_le_i32_e32 vcc, v96, v227
	v_add_u32_e32 v96, 0xffffffb5, v0
	s_nop 0
	v_cndmask_b32_e32 v88, v238, v88, vcc
	v_cmp_le_i32_e32 vcc, v96, v227
	v_add_u32_e32 v96, 0xffffff96, v0
	s_nop 0
	v_cndmask_b32_e32 v72, v238, v72, vcc
	v_cmp_le_i32_e32 vcc, v96, v227
	v_add_u32_e32 v96, 0xffffffb6, v0
	s_nop 0
	v_cndmask_b32_e32 v89, v238, v89, vcc
	v_cmp_le_i32_e32 vcc, v96, v227
	v_add_u32_e32 v96, 0xffffff97, v0
	s_nop 0
	v_cndmask_b32_e32 v73, v238, v73, vcc
	v_cmp_le_i32_e32 vcc, v96, v227
	v_add_u32_e32 v96, 0xffffffb7, v0
	s_nop 0
	v_cndmask_b32_e32 v90, v238, v90, vcc
	v_cmp_le_i32_e32 vcc, v96, v227
	v_add_u32_e32 v96, 0xffffff98, v0
	s_nop 0
	v_cndmask_b32_e32 v74, v238, v74, vcc
	v_cmp_le_i32_e32 vcc, v96, v227
	v_add_u32_e32 v96, 0xffffffb8, v0
	s_nop 0
	v_cndmask_b32_e32 v91, v238, v91, vcc
	v_cmp_le_i32_e32 vcc, v96, v227
	v_add_u32_e32 v96, 0xffffff9d, v0
	s_nop 0
	v_cndmask_b32_e32 v75, v238, v75, vcc
	v_cmp_le_i32_e32 vcc, v96, v227
	v_add_u32_e32 v96, 0xffffffbd, v0
	s_nop 0
	v_cndmask_b32_e32 v92, v238, v92, vcc
	v_cmp_le_i32_e32 vcc, v96, v227
	v_add_u32_e32 v96, 0xffffff9e, v0
	s_nop 0
	v_cndmask_b32_e32 v76, v238, v76, vcc
	v_cmp_le_i32_e32 vcc, v96, v227
	v_add_u32_e32 v96, 0xffffffbe, v0
	s_nop 0
	v_cndmask_b32_e32 v93, v238, v93, vcc
	v_cmp_le_i32_e32 vcc, v96, v227
	v_add_u32_e32 v96, 0xffffff9f, v0
	s_nop 0
	v_cndmask_b32_e32 v77, v238, v77, vcc
	v_cmp_le_i32_e32 vcc, v96, v227
	v_add_u32_e32 v96, 0xffffffbf, v0
	s_nop 0
	v_cndmask_b32_e32 v94, v238, v94, vcc
	v_cmp_le_i32_e32 vcc, v96, v227
	v_add_u32_e32 v96, 0xffffffa0, v0
	s_nop 0
	v_cndmask_b32_e32 v78, v238, v78, vcc
	v_cmp_le_i32_e32 vcc, v96, v227
	v_subrev_u32_e32 v96, 64, v0
	s_nop 0
	v_cndmask_b32_e32 v95, v238, v95, vcc
	v_cmp_le_i32_e32 vcc, v96, v227
	s_nop 1
	v_cndmask_b32_e32 v79, v238, v79, vcc

.LBB0_1350:
	ds_read_b128 v[64:67], v14 offset:256
	ds_read_b128 v[68:71], v14 offset:288
	ds_read_b128 v[72:75], v14 offset:320
	ds_read_b128 v[76:79], v14 offset:352
	ds_read_b128 v[242:245], v14 offset:384
	ds_read_b128 v[246:249], v14 offset:416
	ds_read_b128 v[250:253], v14 offset:448
	ds_read_b128 v[232:235], v14 offset:480
	s_add_i32 s59, s59, -1
	s_waitcnt lgkmcnt(4)
	v_add_f32_e32 v94, v126, v78
	v_add_f32_e32 v95, v127, v79
	v_add_f32_e32 v90, v122, v74
	v_add_f32_e32 v91, v123, v75
	v_add_f32_e32 v86, v118, v70
	v_add_f32_e32 v87, v119, v71
	v_add_f32_e32 v82, v114, v66
	v_add_f32_e32 v83, v115, v67
	v_add_f32_e32 v92, v124, v76
	v_add_f32_e32 v93, v125, v77
	v_add_f32_e32 v88, v120, v72
	v_add_f32_e32 v89, v121, v73
	v_add_f32_e32 v84, v116, v68
	v_add_f32_e32 v85, v117, v69
	v_add_f32_e32 v80, v112, v64
	v_add_f32_e32 v81, v113, v65
	s_waitcnt lgkmcnt(0)
	v_add_f32_e32 v78, v110, v234
	v_add_f32_e32 v79, v111, v235
	v_add_f32_e32 v74, v106, v252
	v_add_f32_e32 v75, v107, v253
	v_add_f32_e32 v70, v102, v248
	v_add_f32_e32 v71, v103, v249
	v_add_f32_e32 v66, v98, v244
	v_add_f32_e32 v67, v99, v245
	v_add_f32_e32 v76, v108, v232
	v_add_f32_e32 v77, v109, v233
	v_add_f32_e32 v72, v104, v250
	v_add_f32_e32 v73, v105, v251
	v_add_f32_e32 v68, v100, v246
	v_add_f32_e32 v69, v101, v247
	s_cmp_lt_i32 s59, 0
	v_add_f32_e32 v64, v96, v242
	v_add_f32_e32 v65, v97, v243
	s_cbranch_scc1 .LBB0_1352
	s_lshl_b32 s100, s59, 6
	s_add_i32 s100, s100, 63
	s_lshl_b32 s101, s33, 5
	s_cmp_le_i32 s100, s101
	s_cbranch_scc1 .LBB0_1352
	v_subrev_u32_e32 v97, 27, v0
	v_subrev_u32_e32 v96, 59, v0
	v_cmp_le_i32_e32 vcc, v97, v227
	s_nop 1
	v_cndmask_b32_e32 v64, v238, v64, vcc
	v_cmp_lt_i32_e32 vcc, v96, v227
	s_nop 1
	v_cndmask_b32_e32 v81, v238, v81, vcc
	v_cmp_le_i32_e32 vcc, v96, v227
	v_subrev_u32_e32 v96, 26, v0
	s_nop 0
	v_cndmask_b32_e32 v80, v238, v80, vcc
	v_cmp_le_i32_e32 vcc, v96, v227
	v_subrev_u32_e32 v96, 57, v0
	s_nop 0
	v_cndmask_b32_e32 v65, v238, v65, vcc
	v_cmp_le_i32_e32 vcc, v96, v227
	v_subrev_u32_e32 v96, 25, v0
	s_nop 0
	v_cndmask_b32_e32 v82, v238, v82, vcc
	v_cmp_le_i32_e32 vcc, v96, v227
	v_subrev_u32_e32 v96, 56, v0
	s_nop 0
	v_cndmask_b32_e32 v66, v238, v66, vcc
	v_cmp_le_i32_e32 vcc, v96, v227
	v_subrev_u32_e32 v96, 24, v0
	s_nop 0
	v_cndmask_b32_e32 v83, v238, v83, vcc
	v_cmp_le_i32_e32 vcc, v96, v227
	v_subrev_u32_e32 v96, 51, v0
	s_nop 0
	v_cndmask_b32_e32 v67, v238, v67, vcc
	v_cmp_le_i32_e32 vcc, v96, v227
	v_subrev_u32_e32 v96, 19, v0
	s_nop 0
	v_cndmask_b32_e32 v84, v238, v84, vcc
	v_cmp_le_i32_e32 vcc, v96, v227
	v_subrev_u32_e32 v96, 50, v0
	s_nop 0
	v_cndmask_b32_e32 v68, v238, v68, vcc
	v_cmp_le_i32_e32 vcc, v96, v227
	v_subrev_u32_e32 v96, 18, v0
	s_nop 0
	v_cndmask_b32_e32 v85, v238, v85, vcc
	v_cmp_le_i32_e32 vcc, v96, v227
	v_subrev_u32_e32 v96, 49, v0
	s_nop 0
	v_cndmask_b32_e32 v69, v238, v69, vcc
	v_cmp_le_i32_e32 vcc, v96, v227
	v_subrev_u32_e32 v96, 17, v0
	s_nop 0
	v_cndmask_b32_e32 v86, v238, v86, vcc
	v_cmp_le_i32_e32 vcc, v96, v227
	v_subrev_u32_e32 v96, 48, v0
	s_nop 0
	v_cndmask_b32_e32 v70, v238, v70, vcc
	v_cmp_le_i32_e32 vcc, v96, v227
	v_add_u32_e32 v96, -16, v0
	s_nop 0
	v_cndmask_b32_e32 v87, v238, v87, vcc
	v_cmp_le_i32_e32 vcc, v96, v227
	v_subrev_u32_e32 v96, 43, v0
	s_nop 0
	v_cndmask_b32_e32 v71, v238, v71, vcc
	v_cmp_le_i32_e32 vcc, v96, v227
	v_add_u32_e32 v96, -11, v0
	s_nop 0
	v_cndmask_b32_e32 v88, v238, v88, vcc
	v_cmp_le_i32_e32 vcc, v96, v227
	v_subrev_u32_e32 v96, 42, v0
	s_nop 0
	v_cndmask_b32_e32 v72, v238, v72, vcc
	v_cmp_le_i32_e32 vcc, v96, v227
	v_add_u32_e32 v96, -10, v0
	s_nop 0
	v_cndmask_b32_e32 v89, v238, v89, vcc
	v_cmp_le_i32_e32 vcc, v96, v227
	v_subrev_u32_e32 v96, 41, v0
	s_nop 0
	v_cndmask_b32_e32 v73, v238, v73, vcc
	v_cmp_le_i32_e32 vcc, v96, v227
	v_add_u32_e32 v96, -9, v0
	s_nop 0
	v_cndmask_b32_e32 v90, v238, v90, vcc
	v_cmp_le_i32_e32 vcc, v96, v227
	v_subrev_u32_e32 v96, 40, v0
	s_nop 0
	v_cndmask_b32_e32 v74, v238, v74, vcc
	v_cmp_le_i32_e32 vcc, v96, v227
	v_add_u32_e32 v96, -8, v0
	s_nop 0
	v_cndmask_b32_e32 v91, v238, v91, vcc
	v_cmp_le_i32_e32 vcc, v96, v227
	v_subrev_u32_e32 v96, 35, v0
	s_nop 0
	v_cndmask_b32_e32 v75, v238, v75, vcc
	v_cmp_le_i32_e32 vcc, v96, v227
	v_add_u32_e32 v96, -3, v0
	s_nop 0
	v_cndmask_b32_e32 v92, v238, v92, vcc
	v_cmp_le_i32_e32 vcc, v96, v227
	v_subrev_u32_e32 v96, 34, v0
	s_nop 0
	v_cndmask_b32_e32 v76, v238, v76, vcc
	v_cmp_le_i32_e32 vcc, v96, v227
	v_add_u32_e32 v96, -2, v0
	s_nop 0
	v_cndmask_b32_e32 v93, v238, v93, vcc
	v_cmp_le_i32_e32 vcc, v96, v227
	v_subrev_u32_e32 v96, 33, v0
	s_nop 0
	v_cndmask_b32_e32 v77, v238, v77, vcc
	v_cmp_le_i32_e32 vcc, v96, v227
	v_add_u32_e32 v96, -1, v0
	s_nop 0
	v_cndmask_b32_e32 v94, v238, v94, vcc
	v_cmp_le_i32_e32 vcc, v96, v227
	v_subrev_u32_e32 v96, 32, v0
	s_nop 0
	v_cndmask_b32_e32 v78, v238, v78, vcc
	v_cmp_le_i32_e32 vcc, v96, v227
	s_nop 1
	v_cndmask_b32_e32 v95, v238, v95, vcc
	v_cmp_le_i32_e32 vcc, v0, v227
	s_nop 1
	v_cndmask_b32_e32 v79, v238, v79, vcc

.LBB0_1473:
	s_add_u32 s16, s4, s14
	s_addc_u32 s17, s5, s15
	s_add_u32 s22, s16, 0x100
	s_addc_u32 s23, s17, 0
	s_and_b64 s[10:11], s[12:13], exec
	s_cselect_b32 s11, s5, s23
	s_cselect_b32 s10, s4, s22
	s_add_u32 s14, s6, s14
	s_addc_u32 s15, s7, s15
	s_add_u32 s14, s14, 0x100
	s_addc_u32 s15, s15, 0
	s_add_i32 s69, 0, 0x10000
	s_and_b64 s[12:13], s[12:13], exec
	s_cselect_b32 s13, s7, s15
	s_cselect_b32 s12, s6, s14
	s_add_i32 s15, 0, 0x14000
	s_add_u32 s46, s16, 0x80080
	s_addc_u32 s47, s17, 0
	s_add_i32 s71, s69, s41
	s_add_i32 m0, s42, 0xc000
	s_add_i32 s74, s42, 0xe000
	s_add_i32 s67, s71, 0x2000
	v_add_u32_e32 v0, s69, v136
	s_add_u32 s22, s12, 0x40000
	ds_read_b128 v[138:141], v0
	ds_read_b128 v[142:145], v0 offset:1024
	ds_read_b128 v[146:149], v0 offset:2048
	ds_read_b128 v[150:153], v0 offset:3072
	v_add_u32_e32 v0, s15, v136
	s_addc_u32 s23, s13, 0
	s_add_i32 s68, s15, s41
	ds_read_b128 v[154:157], v0
	ds_read_b128 v[158:161], v0 offset:1024
	ds_read_b128 v[162:165], v0 offset:2048
	ds_read_b128 v[166:169], v0 offset:3072
	s_add_i32 s66, s68, 0x2000
	s_add_i32 s65, 0, 0x18000
	s_add_i32 s64, 0, 0x1c000
	s_add_u32 s16, s10, 0x80000
	s_addc_u32 s17, s11, 0
	s_add_i32 s61, s65, s41
	s_add_i32 s60, s61, 0x2000
	s_add_u32 s14, s12, 0x40080
	s_addc_u32 s15, s13, 0
	s_add_i32 s70, s64, s41
	s_add_i32 s69, s70, 0x2000
	v_mov_b32_e32 v0, v130
	ds_read_b128 v[170:173], v137
	ds_read_b128 v[174:177], v137 offset:1024
	ds_read_b128 v[178:181], v137 offset:2048
	ds_read_b128 v[182:185], v137 offset:3072
	ds_read_b128 v[186:189], v137 offset:4096
	ds_read_b128 v[190:193], v137 offset:5120
	ds_read_b128 v[194:197], v137 offset:6144
	ds_read_b128 v[198:201], v137 offset:7168
	s_nop 0
	global_load_lds_dwordx4 v0, s[46:47]
	v_mov_b32_e32 v0, v132
	s_mov_b32 m0, s74
	s_nop 0
	global_load_lds_dwordx4 v0, s[46:47]
	s_waitcnt vmcnt(8)
	s_waitcnt lgkmcnt(0)
	s_barrier
	s_setprio 1
	s_waitcnt lgkmcnt(0)
	v_mfma_f32_16x16x32_bf16 v[126:129], v[138:141], v[170:173], v[126:129]
	v_mfma_f32_16x16x32_bf16 v[122:125], v[146:149], v[170:173], v[122:125]
	v_mfma_f32_16x16x32_bf16 v[118:121], v[138:141], v[178:181], v[118:121]
	v_mfma_f32_16x16x32_bf16 v[110:113], v[146:149], v[178:181], v[110:113]
	v_mfma_f32_16x16x32_bf16 v[102:105], v[138:141], v[186:189], v[102:105]
	v_mfma_f32_16x16x32_bf16 v[94:97], v[146:149], v[186:189], v[94:97]
	v_mfma_f32_16x16x32_bf16 v[86:89], v[138:141], v[194:197], v[86:89]
	v_mfma_f32_16x16x32_bf16 v[78:81], v[146:149], v[194:197], v[78:81]
	v_mfma_f32_16x16x32_bf16 v[126:129], v[142:145], v[174:177], v[126:129]
	v_mfma_f32_16x16x32_bf16 v[122:125], v[150:153], v[174:177], v[122:125]
	v_mfma_f32_16x16x32_bf16 v[118:121], v[142:145], v[182:185], v[118:121]
	v_mfma_f32_16x16x32_bf16 v[110:113], v[150:153], v[182:185], v[110:113]
	v_mfma_f32_16x16x32_bf16 v[102:105], v[142:145], v[190:193], v[102:105]
	v_mfma_f32_16x16x32_bf16 v[94:97], v[150:153], v[190:193], v[94:97]
	v_mfma_f32_16x16x32_bf16 v[86:89], v[142:145], v[198:201], v[86:89]
	v_mfma_f32_16x16x32_bf16 v[78:81], v[150:153], v[198:201], v[78:81]
	s_setprio 0
	s_setprio 1
	v_mfma_f32_16x16x32_bf16 v[114:117], v[154:157], v[170:173], v[114:117]
	v_mfma_f32_16x16x32_bf16 v[106:109], v[162:165], v[170:173], v[106:109]
	v_mfma_f32_16x16x32_bf16 v[98:101], v[154:157], v[178:181], v[98:101]
	v_mfma_f32_16x16x32_bf16 v[90:93], v[162:165], v[178:181], v[90:93]
	v_mfma_f32_16x16x32_bf16 v[82:85], v[154:157], v[186:189], v[82:85]
	v_mfma_f32_16x16x32_bf16 v[74:77], v[162:165], v[186:189], v[74:77]
	v_mfma_f32_16x16x32_bf16 v[70:73], v[154:157], v[194:197], v[70:73]
	v_mfma_f32_16x16x32_bf16 v[62:65], v[162:165], v[194:197], v[62:65]
	v_mfma_f32_16x16x32_bf16 v[114:117], v[158:161], v[174:177], v[114:117]
	v_mfma_f32_16x16x32_bf16 v[106:109], v[166:169], v[174:177], v[106:109]
	v_mfma_f32_16x16x32_bf16 v[98:101], v[158:161], v[182:185], v[98:101]
	v_mfma_f32_16x16x32_bf16 v[90:93], v[166:169], v[182:185], v[90:93]
	v_mfma_f32_16x16x32_bf16 v[82:85], v[158:161], v[190:193], v[82:85]
	v_mfma_f32_16x16x32_bf16 v[74:77], v[166:169], v[190:193], v[74:77]
	v_mfma_f32_16x16x32_bf16 v[70:73], v[158:161], v[198:201], v[70:73]
	v_mfma_f32_16x16x32_bf16 v[62:65], v[166:169], v[198:201], v[62:65]
	s_setprio 0
	s_barrier
	v_mov_b32_e32 v0, v131
	s_mov_b32 m0, s71
	ds_read_b128 v[170:173], v137 offset:16384
	ds_read_b128 v[174:177], v137 offset:17408
	ds_read_b128 v[178:181], v137 offset:18432
	ds_read_b128 v[182:185], v137 offset:19456
	ds_read_b128 v[186:189], v137 offset:20480
	ds_read_b128 v[190:193], v137 offset:21504
	ds_read_b128 v[194:197], v137 offset:22528
	ds_read_b128 v[198:201], v137 offset:23552
	s_nop 0
	global_load_lds_dwordx4 v0, s[12:13]
	v_mov_b32_e32 v0, v133
	s_mov_b32 m0, s67
	s_nop 0
	global_load_lds_dwordx4 v0, s[12:13]
	v_mov_b32_e32 v0, v131
	s_mov_b32 m0, s68
	s_nop 0
	global_load_lds_dwordx4 v0, s[22:23]
	v_mov_b32_e32 v0, v133
	s_mov_b32 m0, s66
	s_nop 0
	global_load_lds_dwordx4 v0, s[22:23]
	v_mov_b32_e32 v0, v130
	s_mov_b32 m0, s42
	s_nop 0
	global_load_lds_dwordx4 v0, s[10:11]
	v_mov_b32_e32 v0, v132
	s_mov_b32 m0, s43
	s_nop 0
	global_load_lds_dwordx4 v0, s[10:11]
	s_waitcnt vmcnt(8)
	s_waitcnt lgkmcnt(0)
	s_barrier
	s_setprio 1
	s_waitcnt lgkmcnt(0)
	v_mfma_f32_16x16x32_bf16 v[66:69], v[138:141], v[170:173], v[66:69]
	v_mfma_f32_16x16x32_bf16 v[58:61], v[146:149], v[170:173], v[58:61]
	v_mfma_f32_16x16x32_bf16 v[54:57], v[138:141], v[178:181], v[54:57]
	v_mfma_f32_16x16x32_bf16 v[46:49], v[146:149], v[178:181], v[46:49]
	v_mfma_f32_16x16x32_bf16 v[38:41], v[138:141], v[186:189], v[38:41]
	v_mfma_f32_16x16x32_bf16 v[30:33], v[146:149], v[186:189], v[30:33]
	v_mfma_f32_16x16x32_bf16 v[22:25], v[138:141], v[194:197], v[22:25]
	v_mfma_f32_16x16x32_bf16 v[14:17], v[146:149], v[194:197], v[14:17]
	v_mfma_f32_16x16x32_bf16 v[66:69], v[142:145], v[174:177], v[66:69]
	v_mfma_f32_16x16x32_bf16 v[58:61], v[150:153], v[174:177], v[58:61]
	v_mfma_f32_16x16x32_bf16 v[54:57], v[142:145], v[182:185], v[54:57]
	v_mfma_f32_16x16x32_bf16 v[46:49], v[150:153], v[182:185], v[46:49]
	v_mfma_f32_16x16x32_bf16 v[38:41], v[142:145], v[190:193], v[38:41]
	v_mfma_f32_16x16x32_bf16 v[30:33], v[150:153], v[190:193], v[30:33]
	v_mfma_f32_16x16x32_bf16 v[22:25], v[142:145], v[198:201], v[22:25]
	v_mfma_f32_16x16x32_bf16 v[14:17], v[150:153], v[198:201], v[14:17]
	s_setprio 0
	s_setprio 1
	v_mfma_f32_16x16x32_bf16 v[50:53], v[154:157], v[170:173], v[50:53]
	v_mfma_f32_16x16x32_bf16 v[42:45], v[162:165], v[170:173], v[42:45]
	v_mfma_f32_16x16x32_bf16 v[34:37], v[154:157], v[178:181], v[34:37]
	v_mfma_f32_16x16x32_bf16 v[26:29], v[162:165], v[178:181], v[26:29]
	v_mfma_f32_16x16x32_bf16 v[18:21], v[154:157], v[186:189], v[18:21]
	v_mfma_f32_16x16x32_bf16 v[10:13], v[162:165], v[186:189], v[10:13]
	v_mfma_f32_16x16x32_bf16 v[6:9], v[154:157], v[194:197], v[6:9]
	v_mfma_f32_16x16x32_bf16 v[2:5], v[162:165], v[194:197], v[2:5]
	v_mfma_f32_16x16x32_bf16 v[50:53], v[158:161], v[174:177], v[50:53]
	v_mfma_f32_16x16x32_bf16 v[42:45], v[166:169], v[174:177], v[42:45]
	v_mfma_f32_16x16x32_bf16 v[34:37], v[158:161], v[182:185], v[34:37]
	v_mfma_f32_16x16x32_bf16 v[26:29], v[166:169], v[182:185], v[26:29]
	v_mfma_f32_16x16x32_bf16 v[18:21], v[158:161], v[190:193], v[18:21]
	v_mfma_f32_16x16x32_bf16 v[10:13], v[166:169], v[190:193], v[10:13]
	v_mfma_f32_16x16x32_bf16 v[6:9], v[158:161], v[198:201], v[6:9]
	v_mfma_f32_16x16x32_bf16 v[2:5], v[166:169], v[198:201], v[2:5]
	s_setprio 0
	s_barrier
	v_add_u32_e32 v0, s65, v136
	ds_read_b128 v[138:141], v0
	ds_read_b128 v[142:145], v0 offset:1024
	ds_read_b128 v[146:149], v0 offset:2048
	ds_read_b128 v[150:153], v0 offset:3072
	v_add_u32_e32 v0, s64, v136
	ds_read_b128 v[154:157], v0
	ds_read_b128 v[158:161], v0 offset:1024
	ds_read_b128 v[162:165], v0 offset:2048
	ds_read_b128 v[166:169], v0 offset:3072
	v_mov_b32_e32 v0, v130
	s_mov_b32 m0, s50
	ds_read_b128 v[170:173], v137 offset:32768
	ds_read_b128 v[174:177], v137 offset:33792
	ds_read_b128 v[178:181], v137 offset:34816
	ds_read_b128 v[182:185], v137 offset:35840
	ds_read_b128 v[186:189], v137 offset:36864
	ds_read_b128 v[190:193], v137 offset:37888
	ds_read_b128 v[194:197], v137 offset:38912
	ds_read_b128 v[198:201], v137 offset:39936
	s_nop 0
	global_load_lds_dwordx4 v0, s[16:17]
	v_mov_b32_e32 v0, v132
	s_mov_b32 m0, s51
	s_nop 0
	global_load_lds_dwordx4 v0, s[16:17]
	s_waitcnt vmcnt(8)
	s_waitcnt lgkmcnt(0)
	s_barrier
	s_setprio 1
	s_waitcnt lgkmcnt(0)
	v_mfma_f32_16x16x32_bf16 v[126:129], v[138:141], v[170:173], v[126:129]
	v_mfma_f32_16x16x32_bf16 v[122:125], v[146:149], v[170:173], v[122:125]
	v_mfma_f32_16x16x32_bf16 v[118:121], v[138:141], v[178:181], v[118:121]
	v_mfma_f32_16x16x32_bf16 v[110:113], v[146:149], v[178:181], v[110:113]
	v_mfma_f32_16x16x32_bf16 v[102:105], v[138:141], v[186:189], v[102:105]
	v_mfma_f32_16x16x32_bf16 v[94:97], v[146:149], v[186:189], v[94:97]
	v_mfma_f32_16x16x32_bf16 v[86:89], v[138:141], v[194:197], v[86:89]
	v_mfma_f32_16x16x32_bf16 v[78:81], v[146:149], v[194:197], v[78:81]
	v_mfma_f32_16x16x32_bf16 v[126:129], v[142:145], v[174:177], v[126:129]
	v_mfma_f32_16x16x32_bf16 v[122:125], v[150:153], v[174:177], v[122:125]
	v_mfma_f32_16x16x32_bf16 v[118:121], v[142:145], v[182:185], v[118:121]
	v_mfma_f32_16x16x32_bf16 v[110:113], v[150:153], v[182:185], v[110:113]
	v_mfma_f32_16x16x32_bf16 v[102:105], v[142:145], v[190:193], v[102:105]
	v_mfma_f32_16x16x32_bf16 v[94:97], v[150:153], v[190:193], v[94:97]
	v_mfma_f32_16x16x32_bf16 v[86:89], v[142:145], v[198:201], v[86:89]
	v_mfma_f32_16x16x32_bf16 v[78:81], v[150:153], v[198:201], v[78:81]
	s_setprio 0
	s_setprio 1
	v_mfma_f32_16x16x32_bf16 v[114:117], v[154:157], v[170:173], v[114:117]
	v_mfma_f32_16x16x32_bf16 v[106:109], v[162:165], v[170:173], v[106:109]
	v_mfma_f32_16x16x32_bf16 v[98:101], v[154:157], v[178:181], v[98:101]
	v_mfma_f32_16x16x32_bf16 v[90:93], v[162:165], v[178:181], v[90:93]
	v_mfma_f32_16x16x32_bf16 v[82:85], v[154:157], v[186:189], v[82:85]
	v_mfma_f32_16x16x32_bf16 v[74:77], v[162:165], v[186:189], v[74:77]
	v_mfma_f32_16x16x32_bf16 v[70:73], v[154:157], v[194:197], v[70:73]
	v_mfma_f32_16x16x32_bf16 v[62:65], v[162:165], v[194:197], v[62:65]
	v_mfma_f32_16x16x32_bf16 v[114:117], v[158:161], v[174:177], v[114:117]
	v_mfma_f32_16x16x32_bf16 v[106:109], v[166:169], v[174:177], v[106:109]
	v_mfma_f32_16x16x32_bf16 v[98:101], v[158:161], v[182:185], v[98:101]
	v_mfma_f32_16x16x32_bf16 v[90:93], v[166:169], v[182:185], v[90:93]
	v_mfma_f32_16x16x32_bf16 v[82:85], v[158:161], v[190:193], v[82:85]
	v_mfma_f32_16x16x32_bf16 v[74:77], v[166:169], v[190:193], v[74:77]
	v_mfma_f32_16x16x32_bf16 v[70:73], v[158:161], v[198:201], v[70:73]
	v_mfma_f32_16x16x32_bf16 v[62:65], v[166:169], v[198:201], v[62:65]
	s_setprio 0
	s_barrier
	v_mov_b32_e32 v0, v131
	ds_read_b128 v[170:173], v137 offset:49152
	ds_read_b128 v[174:177], v137 offset:50176
	ds_read_b128 v[178:181], v137 offset:51200
	ds_read_b128 v[182:185], v137 offset:52224
	ds_read_b128 v[186:189], v137 offset:53248
	ds_read_b128 v[190:193], v137 offset:54272
	ds_read_b128 v[194:197], v137 offset:55296
	ds_read_b128 v[198:201], v137 offset:56320
	s_mov_b32 m0, s61
	s_add_u32 s100, s12, s38
	s_addc_u32 s101, s13, s39
	v_mov_b32_e32 v0, v133
	global_load_lds_dwordx4 v131, s[100:101]
	s_mov_b32 m0, s60
	v_mov_b32_e32 v0, v131
	global_load_lds_dwordx4 v133, s[100:101]
	s_mov_b32 m0, s70
	s_nop 0
	global_load_lds_dwordx4 v0, s[14:15]
	v_mov_b32_e32 v0, v133
	s_mov_b32 m0, s69
	s_nop 0
	global_load_lds_dwordx4 v0, s[14:15]
	v_mov_b32_e32 v0, v130
	s_mov_b32 m0, s58
	s_add_u32 s100, s10, s38
	s_addc_u32 s101, s11, s39
	v_mov_b32_e32 v0, v132
	global_load_lds_dwordx4 v130, s[100:101]
	s_mov_b32 m0, s59
	s_nop 0
	global_load_lds_dwordx4 v132, s[100:101]
	s_waitcnt vmcnt(8)
	s_waitcnt lgkmcnt(0)
	s_barrier
	s_setprio 1
	s_waitcnt lgkmcnt(0)
	v_mfma_f32_16x16x32_bf16 v[66:69], v[138:141], v[170:173], v[66:69]
	v_mfma_f32_16x16x32_bf16 v[58:61], v[146:149], v[170:173], v[58:61]
	v_mfma_f32_16x16x32_bf16 v[54:57], v[138:141], v[178:181], v[54:57]
	v_mfma_f32_16x16x32_bf16 v[46:49], v[146:149], v[178:181], v[46:49]
	v_mfma_f32_16x16x32_bf16 v[38:41], v[138:141], v[186:189], v[38:41]
	v_mfma_f32_16x16x32_bf16 v[30:33], v[146:149], v[186:189], v[30:33]
	v_mfma_f32_16x16x32_bf16 v[22:25], v[138:141], v[194:197], v[22:25]
	v_mfma_f32_16x16x32_bf16 v[14:17], v[146:149], v[194:197], v[14:17]
	v_mfma_f32_16x16x32_bf16 v[66:69], v[142:145], v[174:177], v[66:69]
	v_mfma_f32_16x16x32_bf16 v[58:61], v[150:153], v[174:177], v[58:61]
	v_mfma_f32_16x16x32_bf16 v[54:57], v[142:145], v[182:185], v[54:57]
	v_mfma_f32_16x16x32_bf16 v[46:49], v[150:153], v[182:185], v[46:49]
	v_mfma_f32_16x16x32_bf16 v[38:41], v[142:145], v[190:193], v[38:41]
	v_mfma_f32_16x16x32_bf16 v[30:33], v[150:153], v[190:193], v[30:33]
	v_mfma_f32_16x16x32_bf16 v[22:25], v[142:145], v[198:201], v[22:25]
	v_mfma_f32_16x16x32_bf16 v[14:17], v[150:153], v[198:201], v[14:17]
	s_setprio 0
	s_setprio 1
	v_mfma_f32_16x16x32_bf16 v[50:53], v[154:157], v[170:173], v[50:53]
	v_mfma_f32_16x16x32_bf16 v[42:45], v[162:165], v[170:173], v[42:45]
	v_mfma_f32_16x16x32_bf16 v[34:37], v[154:157], v[178:181], v[34:37]
	v_mfma_f32_16x16x32_bf16 v[26:29], v[162:165], v[178:181], v[26:29]
	v_mfma_f32_16x16x32_bf16 v[18:21], v[154:157], v[186:189], v[18:21]
	v_mfma_f32_16x16x32_bf16 v[10:13], v[162:165], v[186:189], v[10:13]
	v_mfma_f32_16x16x32_bf16 v[6:9], v[154:157], v[194:197], v[6:9]
	v_mfma_f32_16x16x32_bf16 v[2:5], v[162:165], v[194:197], v[2:5]
	v_mfma_f32_16x16x32_bf16 v[50:53], v[158:161], v[174:177], v[50:53]
	v_mfma_f32_16x16x32_bf16 v[42:45], v[166:169], v[174:177], v[42:45]
	v_mfma_f32_16x16x32_bf16 v[34:37], v[158:161], v[182:185], v[34:37]
	v_mfma_f32_16x16x32_bf16 v[26:29], v[166:169], v[182:185], v[26:29]
	v_mfma_f32_16x16x32_bf16 v[18:21], v[158:161], v[190:193], v[18:21]
	v_mfma_f32_16x16x32_bf16 v[10:13], v[166:169], v[190:193], v[10:13]
	v_mfma_f32_16x16x32_bf16 v[6:9], v[158:161], v[198:201], v[6:9]
	v_mfma_f32_16x16x32_bf16 v[2:5], v[166:169], v[198:201], v[2:5]
	s_setprio 0
	s_barrier
	s_andn2_b64 vcc, exec, s[8:9]
	s_mov_b64 s[12:13], -1
	s_mov_b64 s[8:9], 0
	s_mov_b64 s[14:15], 0x100
	s_cbranch_vccz .LBB0_1473
	s_cmpk_lt_u32 s24, 0x100
	s_cbranch_scc0 .LBB0_1476
	s_barrier

.LBB0_1481:
	s_add_u32 s16, s4, s14
	s_addc_u32 s17, s5, s15
	s_add_u32 s22, s16, 0x100
	s_addc_u32 s23, s17, 0
	s_and_b64 s[10:11], s[12:13], exec
	s_cselect_b32 s11, s5, s23
	s_cselect_b32 s10, s4, s22
	s_add_u32 s14, s6, s14
	s_addc_u32 s15, s7, s15
	s_add_u32 s14, s14, 0x900
	s_addc_u32 s15, s15, 0
	s_add_i32 s70, 0, 0x10000
	s_and_b64 s[12:13], s[12:13], exec
	s_cselect_b32 s13, s58, s15
	s_cselect_b32 s12, s51, s14
	s_add_i32 s15, 0, 0x14000
	s_add_u32 s46, s16, 0x40080
	s_addc_u32 s47, s17, 0
	s_add_i32 s74, s70, s40
	s_add_i32 m0, s41, 0xc000
	s_add_i32 s75, s41, 0xe000
	s_add_i32 s68, s74, 0x2000
	v_add_u32_e32 v0, s70, v136
	s_add_u32 s22, s12, 0x80000
	ds_read_b128 v[138:141], v0
	ds_read_b128 v[142:145], v0 offset:1024
	ds_read_b128 v[146:149], v0 offset:2048
	ds_read_b128 v[150:153], v0 offset:3072
	v_add_u32_e32 v0, s15, v136
	s_addc_u32 s23, s13, 0
	s_add_i32 s69, s15, s40
	ds_read_b128 v[154:157], v0
	ds_read_b128 v[158:161], v0 offset:1024
	ds_read_b128 v[162:165], v0 offset:2048
	ds_read_b128 v[166:169], v0 offset:3072
	s_add_i32 s67, s69, 0x2000
	s_add_i32 s66, 0, 0x18000
	s_add_i32 s65, 0, 0x1c000
	s_add_u32 s16, s10, 0x40000
	s_addc_u32 s17, s11, 0
	s_add_i32 s64, s66, s40
	s_add_i32 s61, s64, 0x2000
	s_add_u32 s14, s12, 0x80080
	s_addc_u32 s15, s13, 0
	s_add_i32 s71, s65, s40
	s_add_i32 s70, s71, 0x2000
	v_mov_b32_e32 v0, v130
	ds_read_b128 v[170:173], v137
	ds_read_b128 v[174:177], v137 offset:1024
	ds_read_b128 v[178:181], v137 offset:2048
	ds_read_b128 v[182:185], v137 offset:3072
	ds_read_b128 v[186:189], v137 offset:4096
	ds_read_b128 v[190:193], v137 offset:5120
	ds_read_b128 v[194:197], v137 offset:6144
	ds_read_b128 v[198:201], v137 offset:7168
	s_nop 0
	global_load_lds_dwordx4 v0, s[46:47]
	v_mov_b32_e32 v0, v132
	s_mov_b32 m0, s75
	s_nop 0
	global_load_lds_dwordx4 v0, s[46:47]
	s_waitcnt vmcnt(8)
	s_waitcnt lgkmcnt(0)
	s_barrier
	s_setprio 1
	s_waitcnt lgkmcnt(0)
	v_mfma_f32_16x16x32_bf16 v[126:129], v[138:141], v[170:173], v[126:129]
	v_mfma_f32_16x16x32_bf16 v[122:125], v[146:149], v[170:173], v[122:125]
	v_mfma_f32_16x16x32_bf16 v[118:121], v[138:141], v[178:181], v[118:121]
	v_mfma_f32_16x16x32_bf16 v[110:113], v[146:149], v[178:181], v[110:113]
	v_mfma_f32_16x16x32_bf16 v[102:105], v[138:141], v[186:189], v[102:105]
	v_mfma_f32_16x16x32_bf16 v[94:97], v[146:149], v[186:189], v[94:97]
	v_mfma_f32_16x16x32_bf16 v[86:89], v[138:141], v[194:197], v[86:89]
	v_mfma_f32_16x16x32_bf16 v[78:81], v[146:149], v[194:197], v[78:81]
	v_mfma_f32_16x16x32_bf16 v[126:129], v[142:145], v[174:177], v[126:129]
	v_mfma_f32_16x16x32_bf16 v[122:125], v[150:153], v[174:177], v[122:125]
	v_mfma_f32_16x16x32_bf16 v[118:121], v[142:145], v[182:185], v[118:121]
	v_mfma_f32_16x16x32_bf16 v[110:113], v[150:153], v[182:185], v[110:113]
	v_mfma_f32_16x16x32_bf16 v[102:105], v[142:145], v[190:193], v[102:105]
	v_mfma_f32_16x16x32_bf16 v[94:97], v[150:153], v[190:193], v[94:97]
	v_mfma_f32_16x16x32_bf16 v[86:89], v[142:145], v[198:201], v[86:89]
	v_mfma_f32_16x16x32_bf16 v[78:81], v[150:153], v[198:201], v[78:81]
	s_setprio 0
	s_setprio 1
	v_mfma_f32_16x16x32_bf16 v[114:117], v[154:157], v[170:173], v[114:117]
	v_mfma_f32_16x16x32_bf16 v[106:109], v[162:165], v[170:173], v[106:109]
	v_mfma_f32_16x16x32_bf16 v[98:101], v[154:157], v[178:181], v[98:101]
	v_mfma_f32_16x16x32_bf16 v[90:93], v[162:165], v[178:181], v[90:93]
	v_mfma_f32_16x16x32_bf16 v[82:85], v[154:157], v[186:189], v[82:85]
	v_mfma_f32_16x16x32_bf16 v[74:77], v[162:165], v[186:189], v[74:77]
	v_mfma_f32_16x16x32_bf16 v[70:73], v[154:157], v[194:197], v[70:73]
	v_mfma_f32_16x16x32_bf16 v[62:65], v[162:165], v[194:197], v[62:65]
	v_mfma_f32_16x16x32_bf16 v[114:117], v[158:161], v[174:177], v[114:117]
	v_mfma_f32_16x16x32_bf16 v[106:109], v[166:169], v[174:177], v[106:109]
	v_mfma_f32_16x16x32_bf16 v[98:101], v[158:161], v[182:185], v[98:101]
	v_mfma_f32_16x16x32_bf16 v[90:93], v[166:169], v[182:185], v[90:93]
	v_mfma_f32_16x16x32_bf16 v[82:85], v[158:161], v[190:193], v[82:85]
	v_mfma_f32_16x16x32_bf16 v[74:77], v[166:169], v[190:193], v[74:77]
	v_mfma_f32_16x16x32_bf16 v[70:73], v[158:161], v[198:201], v[70:73]
	v_mfma_f32_16x16x32_bf16 v[62:65], v[166:169], v[198:201], v[62:65]
	s_setprio 0
	s_barrier
	v_mov_b32_e32 v0, v131
	s_mov_b32 m0, s74
	ds_read_b128 v[170:173], v137 offset:16384
	ds_read_b128 v[174:177], v137 offset:17408
	ds_read_b128 v[178:181], v137 offset:18432
	ds_read_b128 v[182:185], v137 offset:19456
	ds_read_b128 v[186:189], v137 offset:20480
	ds_read_b128 v[190:193], v137 offset:21504
	ds_read_b128 v[194:197], v137 offset:22528
	ds_read_b128 v[198:201], v137 offset:23552
	s_nop 0
	global_load_lds_dwordx4 v0, s[12:13]
	v_mov_b32_e32 v0, v133
	s_mov_b32 m0, s68
	s_nop 0
	global_load_lds_dwordx4 v0, s[12:13]
	v_mov_b32_e32 v0, v131
	s_mov_b32 m0, s69
	s_nop 0
	global_load_lds_dwordx4 v0, s[22:23]
	v_mov_b32_e32 v0, v133
	s_mov_b32 m0, s67
	s_nop 0
	global_load_lds_dwordx4 v0, s[22:23]
	v_mov_b32_e32 v0, v130
	s_mov_b32 m0, s41
	s_nop 0
	global_load_lds_dwordx4 v0, s[10:11]
	v_mov_b32_e32 v0, v132
	s_mov_b32 m0, s42
	s_nop 0
	global_load_lds_dwordx4 v0, s[10:11]
	s_waitcnt vmcnt(8)
	s_waitcnt lgkmcnt(0)
	s_barrier
	s_setprio 1
	s_waitcnt lgkmcnt(0)
	v_mfma_f32_16x16x32_bf16 v[66:69], v[138:141], v[170:173], v[66:69]
	v_mfma_f32_16x16x32_bf16 v[58:61], v[146:149], v[170:173], v[58:61]
	v_mfma_f32_16x16x32_bf16 v[54:57], v[138:141], v[178:181], v[54:57]
	v_mfma_f32_16x16x32_bf16 v[46:49], v[146:149], v[178:181], v[46:49]
	v_mfma_f32_16x16x32_bf16 v[38:41], v[138:141], v[186:189], v[38:41]
	v_mfma_f32_16x16x32_bf16 v[30:33], v[146:149], v[186:189], v[30:33]
	v_mfma_f32_16x16x32_bf16 v[22:25], v[138:141], v[194:197], v[22:25]
	v_mfma_f32_16x16x32_bf16 v[14:17], v[146:149], v[194:197], v[14:17]
	v_mfma_f32_16x16x32_bf16 v[66:69], v[142:145], v[174:177], v[66:69]
	v_mfma_f32_16x16x32_bf16 v[58:61], v[150:153], v[174:177], v[58:61]
	v_mfma_f32_16x16x32_bf16 v[54:57], v[142:145], v[182:185], v[54:57]
	v_mfma_f32_16x16x32_bf16 v[46:49], v[150:153], v[182:185], v[46:49]
	v_mfma_f32_16x16x32_bf16 v[38:41], v[142:145], v[190:193], v[38:41]
	v_mfma_f32_16x16x32_bf16 v[30:33], v[150:153], v[190:193], v[30:33]
	v_mfma_f32_16x16x32_bf16 v[22:25], v[142:145], v[198:201], v[22:25]
	v_mfma_f32_16x16x32_bf16 v[14:17], v[150:153], v[198:201], v[14:17]
	s_setprio 0
	s_setprio 1
	v_mfma_f32_16x16x32_bf16 v[50:53], v[154:157], v[170:173], v[50:53]
	v_mfma_f32_16x16x32_bf16 v[42:45], v[162:165], v[170:173], v[42:45]
	v_mfma_f32_16x16x32_bf16 v[34:37], v[154:157], v[178:181], v[34:37]
	v_mfma_f32_16x16x32_bf16 v[26:29], v[162:165], v[178:181], v[26:29]
	v_mfma_f32_16x16x32_bf16 v[18:21], v[154:157], v[186:189], v[18:21]
	v_mfma_f32_16x16x32_bf16 v[10:13], v[162:165], v[186:189], v[10:13]
	v_mfma_f32_16x16x32_bf16 v[6:9], v[154:157], v[194:197], v[6:9]
	v_mfma_f32_16x16x32_bf16 v[2:5], v[162:165], v[194:197], v[2:5]
	v_mfma_f32_16x16x32_bf16 v[50:53], v[158:161], v[174:177], v[50:53]
	v_mfma_f32_16x16x32_bf16 v[42:45], v[166:169], v[174:177], v[42:45]
	v_mfma_f32_16x16x32_bf16 v[34:37], v[158:161], v[182:185], v[34:37]
	v_mfma_f32_16x16x32_bf16 v[26:29], v[166:169], v[182:185], v[26:29]
	v_mfma_f32_16x16x32_bf16 v[18:21], v[158:161], v[190:193], v[18:21]
	v_mfma_f32_16x16x32_bf16 v[10:13], v[166:169], v[190:193], v[10:13]
	v_mfma_f32_16x16x32_bf16 v[6:9], v[158:161], v[198:201], v[6:9]
	v_mfma_f32_16x16x32_bf16 v[2:5], v[166:169], v[198:201], v[2:5]
	s_setprio 0
	s_barrier
	v_add_u32_e32 v0, s66, v136
	ds_read_b128 v[138:141], v0
	ds_read_b128 v[142:145], v0 offset:1024
	ds_read_b128 v[146:149], v0 offset:2048
	ds_read_b128 v[150:153], v0 offset:3072
	v_add_u32_e32 v0, s65, v136
	ds_read_b128 v[154:157], v0
	ds_read_b128 v[158:161], v0 offset:1024
	ds_read_b128 v[162:165], v0 offset:2048
	ds_read_b128 v[166:169], v0 offset:3072
	v_mov_b32_e32 v0, v130
	s_mov_b32 m0, s43
	ds_read_b128 v[170:173], v137 offset:32768
	ds_read_b128 v[174:177], v137 offset:33792
	ds_read_b128 v[178:181], v137 offset:34816
	ds_read_b128 v[182:185], v137 offset:35840
	ds_read_b128 v[186:189], v137 offset:36864
	ds_read_b128 v[190:193], v137 offset:37888
	ds_read_b128 v[194:197], v137 offset:38912
	ds_read_b128 v[198:201], v137 offset:39936
	s_nop 0
	global_load_lds_dwordx4 v0, s[16:17]
	v_mov_b32_e32 v0, v132
	s_mov_b32 m0, s50
	s_nop 0
	global_load_lds_dwordx4 v0, s[16:17]
	s_waitcnt vmcnt(8)
	s_waitcnt lgkmcnt(0)
	s_barrier
	s_setprio 1
	s_waitcnt lgkmcnt(0)
	v_mfma_f32_16x16x32_bf16 v[126:129], v[138:141], v[170:173], v[126:129]
	v_mfma_f32_16x16x32_bf16 v[122:125], v[146:149], v[170:173], v[122:125]
	v_mfma_f32_16x16x32_bf16 v[118:121], v[138:141], v[178:181], v[118:121]
	v_mfma_f32_16x16x32_bf16 v[110:113], v[146:149], v[178:181], v[110:113]
	v_mfma_f32_16x16x32_bf16 v[102:105], v[138:141], v[186:189], v[102:105]
	v_mfma_f32_16x16x32_bf16 v[94:97], v[146:149], v[186:189], v[94:97]
	v_mfma_f32_16x16x32_bf16 v[86:89], v[138:141], v[194:197], v[86:89]
	v_mfma_f32_16x16x32_bf16 v[78:81], v[146:149], v[194:197], v[78:81]
	v_mfma_f32_16x16x32_bf16 v[126:129], v[142:145], v[174:177], v[126:129]
	v_mfma_f32_16x16x32_bf16 v[122:125], v[150:153], v[174:177], v[122:125]
	v_mfma_f32_16x16x32_bf16 v[118:121], v[142:145], v[182:185], v[118:121]
	v_mfma_f32_16x16x32_bf16 v[110:113], v[150:153], v[182:185], v[110:113]
	v_mfma_f32_16x16x32_bf16 v[102:105], v[142:145], v[190:193], v[102:105]
	v_mfma_f32_16x16x32_bf16 v[94:97], v[150:153], v[190:193], v[94:97]
	v_mfma_f32_16x16x32_bf16 v[86:89], v[142:145], v[198:201], v[86:89]
	v_mfma_f32_16x16x32_bf16 v[78:81], v[150:153], v[198:201], v[78:81]
	s_setprio 0
	s_setprio 1
	v_mfma_f32_16x16x32_bf16 v[114:117], v[154:157], v[170:173], v[114:117]
	v_mfma_f32_16x16x32_bf16 v[106:109], v[162:165], v[170:173], v[106:109]
	v_mfma_f32_16x16x32_bf16 v[98:101], v[154:157], v[178:181], v[98:101]
	v_mfma_f32_16x16x32_bf16 v[90:93], v[162:165], v[178:181], v[90:93]
	v_mfma_f32_16x16x32_bf16 v[82:85], v[154:157], v[186:189], v[82:85]
	v_mfma_f32_16x16x32_bf16 v[74:77], v[162:165], v[186:189], v[74:77]
	v_mfma_f32_16x16x32_bf16 v[70:73], v[154:157], v[194:197], v[70:73]
	v_mfma_f32_16x16x32_bf16 v[62:65], v[162:165], v[194:197], v[62:65]
	v_mfma_f32_16x16x32_bf16 v[114:117], v[158:161], v[174:177], v[114:117]
	v_mfma_f32_16x16x32_bf16 v[106:109], v[166:169], v[174:177], v[106:109]
	v_mfma_f32_16x16x32_bf16 v[98:101], v[158:161], v[182:185], v[98:101]
	v_mfma_f32_16x16x32_bf16 v[90:93], v[166:169], v[182:185], v[90:93]
	v_mfma_f32_16x16x32_bf16 v[82:85], v[158:161], v[190:193], v[82:85]
	v_mfma_f32_16x16x32_bf16 v[74:77], v[166:169], v[190:193], v[74:77]
	v_mfma_f32_16x16x32_bf16 v[70:73], v[158:161], v[198:201], v[70:73]
	v_mfma_f32_16x16x32_bf16 v[62:65], v[166:169], v[198:201], v[62:65]
	s_setprio 0
	s_barrier
	v_mov_b32_e32 v0, v131
	ds_read_b128 v[170:173], v137 offset:49152
	ds_read_b128 v[174:177], v137 offset:50176
	ds_read_b128 v[178:181], v137 offset:51200
	ds_read_b128 v[182:185], v137 offset:52224
	ds_read_b128 v[186:189], v137 offset:53248
	ds_read_b128 v[190:193], v137 offset:54272
	ds_read_b128 v[194:197], v137 offset:55296
	ds_read_b128 v[198:201], v137 offset:56320
	s_mov_b32 m0, s64
	s_add_u32 s100, s12, s38
	s_addc_u32 s101, s13, s39
	v_mov_b32_e32 v0, v133
	global_load_lds_dwordx4 v131, s[100:101]
	s_mov_b32 m0, s61
	v_mov_b32_e32 v0, v131
	global_load_lds_dwordx4 v133, s[100:101]
	s_mov_b32 m0, s71
	s_nop 0
	global_load_lds_dwordx4 v0, s[14:15]
	v_mov_b32_e32 v0, v133
	s_mov_b32 m0, s70
	s_nop 0
	global_load_lds_dwordx4 v0, s[14:15]
	v_mov_b32_e32 v0, v130
	s_mov_b32 m0, s59
	s_add_u32 s100, s10, s38
	s_addc_u32 s101, s11, s39
	v_mov_b32_e32 v0, v132
	global_load_lds_dwordx4 v130, s[100:101]
	s_mov_b32 m0, s60
	s_nop 0
	global_load_lds_dwordx4 v132, s[100:101]
	s_waitcnt vmcnt(8)
	s_waitcnt lgkmcnt(0)
	s_barrier
	s_setprio 1
	s_waitcnt lgkmcnt(0)
	v_mfma_f32_16x16x32_bf16 v[66:69], v[138:141], v[170:173], v[66:69]
	v_mfma_f32_16x16x32_bf16 v[58:61], v[146:149], v[170:173], v[58:61]
	v_mfma_f32_16x16x32_bf16 v[54:57], v[138:141], v[178:181], v[54:57]
	v_mfma_f32_16x16x32_bf16 v[46:49], v[146:149], v[178:181], v[46:49]
	v_mfma_f32_16x16x32_bf16 v[38:41], v[138:141], v[186:189], v[38:41]
	v_mfma_f32_16x16x32_bf16 v[30:33], v[146:149], v[186:189], v[30:33]
	v_mfma_f32_16x16x32_bf16 v[22:25], v[138:141], v[194:197], v[22:25]
	v_mfma_f32_16x16x32_bf16 v[14:17], v[146:149], v[194:197], v[14:17]
	v_mfma_f32_16x16x32_bf16 v[66:69], v[142:145], v[174:177], v[66:69]
	v_mfma_f32_16x16x32_bf16 v[58:61], v[150:153], v[174:177], v[58:61]
	v_mfma_f32_16x16x32_bf16 v[54:57], v[142:145], v[182:185], v[54:57]
	v_mfma_f32_16x16x32_bf16 v[46:49], v[150:153], v[182:185], v[46:49]
	v_mfma_f32_16x16x32_bf16 v[38:41], v[142:145], v[190:193], v[38:41]
	v_mfma_f32_16x16x32_bf16 v[30:33], v[150:153], v[190:193], v[30:33]
	v_mfma_f32_16x16x32_bf16 v[22:25], v[142:145], v[198:201], v[22:25]
	v_mfma_f32_16x16x32_bf16 v[14:17], v[150:153], v[198:201], v[14:17]
	s_setprio 0
	s_setprio 1
	v_mfma_f32_16x16x32_bf16 v[50:53], v[154:157], v[170:173], v[50:53]
	v_mfma_f32_16x16x32_bf16 v[42:45], v[162:165], v[170:173], v[42:45]
	v_mfma_f32_16x16x32_bf16 v[34:37], v[154:157], v[178:181], v[34:37]
	v_mfma_f32_16x16x32_bf16 v[26:29], v[162:165], v[178:181], v[26:29]
	v_mfma_f32_16x16x32_bf16 v[18:21], v[154:157], v[186:189], v[18:21]
	v_mfma_f32_16x16x32_bf16 v[10:13], v[162:165], v[186:189], v[10:13]
	v_mfma_f32_16x16x32_bf16 v[6:9], v[154:157], v[194:197], v[6:9]
	v_mfma_f32_16x16x32_bf16 v[2:5], v[162:165], v[194:197], v[2:5]
	v_mfma_f32_16x16x32_bf16 v[50:53], v[158:161], v[174:177], v[50:53]
	v_mfma_f32_16x16x32_bf16 v[42:45], v[166:169], v[174:177], v[42:45]
	v_mfma_f32_16x16x32_bf16 v[34:37], v[158:161], v[182:185], v[34:37]
	v_mfma_f32_16x16x32_bf16 v[26:29], v[166:169], v[182:185], v[26:29]
	v_mfma_f32_16x16x32_bf16 v[18:21], v[158:161], v[190:193], v[18:21]
	v_mfma_f32_16x16x32_bf16 v[10:13], v[166:169], v[190:193], v[10:13]
	v_mfma_f32_16x16x32_bf16 v[6:9], v[158:161], v[198:201], v[6:9]
	v_mfma_f32_16x16x32_bf16 v[2:5], v[166:169], v[198:201], v[2:5]
	s_setprio 0
	s_barrier
	s_andn2_b64 vcc, exec, s[8:9]
	s_mov_b64 s[12:13], -1
	s_mov_b64 s[8:9], 0
	s_mov_b64 s[14:15], 0x100
	s_cbranch_vccz .LBB0_1481
	s_cmpk_lt_u32 s24, 0x100
	s_cbranch_scc0 .LBB0_1484
	s_barrier

.LBB0_1570:
	s_add_u32 s48, s41, s6
	s_addc_u32 s49, s42, s7
	s_add_u32 s8, s48, 0x9800100
	s_addc_u32 s9, s49, 0
	s_add_u32 s10, s43, s6
	s_addc_u32 s11, s46, s7
	s_cmpk_eq_i32 s6, 0x700
	s_cselect_b32 s9, s3, s9
	s_cselect_b32 s8, s2, s8
	s_cselect_b32 s11, s26, s11
	s_cselect_b32 s10, s25, s10
	s_add_i32 s50, 0, 0x10000
	v_add_u32_e32 v0, s50, v169
	s_add_i32 s51, 0, 0x14000
	ds_read_b128 v[172:175], v0
	ds_read_b128 v[176:179], v0 offset:1024
	ds_read_b128 v[180:183], v0 offset:2048
	ds_read_b128 v[184:187], v0 offset:3072
	v_add_u32_e32 v0, s51, v169
	ds_read_b128 v[188:191], v0
	ds_read_b128 v[192:195], v0 offset:1024
	ds_read_b128 v[196:199], v0 offset:2048
	ds_read_b128 v[200:203], v0 offset:3072
	v_mov_b32_e32 v0, v164
	ds_read_b128 v[204:207], v170
	ds_read_b128 v[208:211], v170 offset:1024
	ds_read_b128 v[212:215], v170 offset:2048
	ds_read_b128 v[216:219], v170 offset:3072
	ds_read_b128 v[220:223], v170 offset:4096
	ds_read_b128 v[224:227], v170 offset:5120
	ds_read_b128 v[232:235], v170 offset:6144
	ds_read_b128 v[242:245], v170 offset:7168
	s_mov_b64 s[58:59], 0x9840080
	s_add_u32 s100, s48, s58
	s_addc_u32 s101, s49, s59
	s_add_i32 m0, s17, 0xc000
	v_mov_b32_e32 v0, v166
	global_load_lds_dwordx4 v164, s[100:101]
	s_add_i32 m0, s17, 0xe000
	s_nop 0
	global_load_lds_dwordx4 v166, s[100:101]
	s_waitcnt vmcnt(8)
	s_waitcnt lgkmcnt(0)
	s_barrier
	s_setprio 1
	s_waitcnt lgkmcnt(0)
	v_mfma_f32_16x16x32_bf16 v[160:163], v[172:175], v[204:207], v[160:163]
	v_mfma_f32_16x16x32_bf16 v[156:159], v[180:183], v[204:207], v[156:159]
	v_mfma_f32_16x16x32_bf16 v[112:115], v[172:175], v[212:215], v[112:115]
	v_mfma_f32_16x16x32_bf16 v[108:111], v[180:183], v[212:215], v[108:111]
	v_mfma_f32_16x16x32_bf16 v[96:99], v[172:175], v[220:223], v[96:99]
	v_mfma_f32_16x16x32_bf16 v[92:95], v[180:183], v[220:223], v[92:95]
	v_mfma_f32_16x16x32_bf16 v[80:83], v[172:175], v[232:235], v[80:83]
	v_mfma_f32_16x16x32_bf16 v[76:79], v[180:183], v[232:235], v[76:79]
	v_mfma_f32_16x16x32_bf16 v[160:163], v[176:179], v[208:211], v[160:163]
	v_mfma_f32_16x16x32_bf16 v[156:159], v[184:187], v[208:211], v[156:159]
	v_mfma_f32_16x16x32_bf16 v[112:115], v[176:179], v[216:219], v[112:115]
	v_mfma_f32_16x16x32_bf16 v[108:111], v[184:187], v[216:219], v[108:111]
	v_mfma_f32_16x16x32_bf16 v[96:99], v[176:179], v[224:227], v[96:99]
	v_mfma_f32_16x16x32_bf16 v[92:95], v[184:187], v[224:227], v[92:95]
	v_mfma_f32_16x16x32_bf16 v[80:83], v[176:179], v[242:245], v[80:83]
	v_mfma_f32_16x16x32_bf16 v[76:79], v[184:187], v[242:245], v[76:79]
	s_setprio 0
	s_setprio 1
	v_mfma_f32_16x16x32_bf16 v[128:131], v[188:191], v[204:207], v[128:131]
	v_mfma_f32_16x16x32_bf16 v[120:123], v[196:199], v[204:207], v[120:123]
	v_mfma_f32_16x16x32_bf16 v[104:107], v[188:191], v[212:215], v[104:107]
	v_mfma_f32_16x16x32_bf16 v[100:103], v[196:199], v[212:215], v[100:103]
	v_mfma_f32_16x16x32_bf16 v[88:91], v[188:191], v[220:223], v[88:91]
	v_mfma_f32_16x16x32_bf16 v[84:87], v[196:199], v[220:223], v[84:87]
	v_mfma_f32_16x16x32_bf16 v[72:75], v[188:191], v[232:235], v[72:75]
	v_mfma_f32_16x16x32_bf16 v[68:71], v[196:199], v[232:235], v[68:71]
	v_mfma_f32_16x16x32_bf16 v[128:131], v[192:195], v[208:211], v[128:131]
	v_mfma_f32_16x16x32_bf16 v[120:123], v[200:203], v[208:211], v[120:123]
	v_mfma_f32_16x16x32_bf16 v[104:107], v[192:195], v[216:219], v[104:107]
	v_mfma_f32_16x16x32_bf16 v[100:103], v[200:203], v[216:219], v[100:103]
	v_mfma_f32_16x16x32_bf16 v[88:91], v[192:195], v[224:227], v[88:91]
	v_mfma_f32_16x16x32_bf16 v[84:87], v[200:203], v[224:227], v[84:87]
	v_mfma_f32_16x16x32_bf16 v[72:75], v[192:195], v[242:245], v[72:75]
	v_mfma_f32_16x16x32_bf16 v[68:71], v[200:203], v[242:245], v[68:71]
	s_setprio 0
	s_barrier
	v_mov_b32_e32 v0, v167
	s_add_i32 s48, s50, s16
	ds_read_b128 v[204:207], v170 offset:16384
	ds_read_b128 v[208:211], v170 offset:17408
	ds_read_b128 v[212:215], v170 offset:18432
	ds_read_b128 v[216:219], v170 offset:19456
	ds_read_b128 v[220:223], v170 offset:20480
	ds_read_b128 v[224:227], v170 offset:21504
	ds_read_b128 v[232:235], v170 offset:22528
	ds_read_b128 v[242:245], v170 offset:23552
	s_mov_b32 m0, s48
	s_nop 0
	global_load_lds_dwordx4 v0, s[10:11]
	v_mov_b32_e32 v0, v168
	s_add_i32 m0, s48, 0x2000
	s_add_u32 s48, s10, 0x40000
	global_load_lds_dwordx4 v0, s[10:11]
	s_addc_u32 s49, s11, 0
	v_mov_b32_e32 v0, v167
	s_add_i32 s50, s51, s16
	s_mov_b32 m0, s50
	s_nop 0
	global_load_lds_dwordx4 v0, s[48:49]
	v_mov_b32_e32 v0, v168
	s_add_i32 m0, s50, 0x2000
	s_nop 0
	global_load_lds_dwordx4 v0, s[48:49]
	v_mov_b32_e32 v0, v164
	s_mov_b32 m0, s17
	s_nop 0
	global_load_lds_dwordx4 v0, s[8:9]
	v_mov_b32_e32 v0, v166
	s_mov_b32 m0, s22
	s_nop 0
	global_load_lds_dwordx4 v0, s[8:9]
	s_waitcnt vmcnt(8)
	s_waitcnt lgkmcnt(0)
	s_barrier
	s_setprio 1
	s_waitcnt lgkmcnt(0)
	v_mfma_f32_16x16x32_bf16 v[64:67], v[172:175], v[204:207], v[64:67]
	v_mfma_f32_16x16x32_bf16 v[60:63], v[180:183], v[204:207], v[60:63]
	v_mfma_f32_16x16x32_bf16 v[48:51], v[172:175], v[212:215], v[48:51]
	v_mfma_f32_16x16x32_bf16 v[44:47], v[180:183], v[212:215], v[44:47]
	v_mfma_f32_16x16x32_bf16 v[32:35], v[172:175], v[220:223], v[32:35]
	v_mfma_f32_16x16x32_bf16 v[28:31], v[180:183], v[220:223], v[28:31]
	v_mfma_f32_16x16x32_bf16 v[16:19], v[172:175], v[232:235], v[16:19]
	v_mfma_f32_16x16x32_bf16 v[12:15], v[180:183], v[232:235], v[12:15]
	v_mfma_f32_16x16x32_bf16 v[64:67], v[176:179], v[208:211], v[64:67]
	v_mfma_f32_16x16x32_bf16 v[60:63], v[184:187], v[208:211], v[60:63]
	v_mfma_f32_16x16x32_bf16 v[48:51], v[176:179], v[216:219], v[48:51]
	v_mfma_f32_16x16x32_bf16 v[44:47], v[184:187], v[216:219], v[44:47]
	v_mfma_f32_16x16x32_bf16 v[32:35], v[176:179], v[224:227], v[32:35]
	v_mfma_f32_16x16x32_bf16 v[28:31], v[184:187], v[224:227], v[28:31]
	v_mfma_f32_16x16x32_bf16 v[16:19], v[176:179], v[242:245], v[16:19]
	v_mfma_f32_16x16x32_bf16 v[12:15], v[184:187], v[242:245], v[12:15]
	s_setprio 0
	s_setprio 1
	v_mfma_f32_16x16x32_bf16 v[56:59], v[188:191], v[204:207], v[56:59]
	v_mfma_f32_16x16x32_bf16 v[52:55], v[196:199], v[204:207], v[52:55]
	v_mfma_f32_16x16x32_bf16 v[40:43], v[188:191], v[212:215], v[40:43]
	v_mfma_f32_16x16x32_bf16 v[36:39], v[196:199], v[212:215], v[36:39]
	v_mfma_f32_16x16x32_bf16 v[24:27], v[188:191], v[220:223], v[24:27]
	v_mfma_f32_16x16x32_bf16 v[20:23], v[196:199], v[220:223], v[20:23]
	v_mfma_f32_16x16x32_bf16 v[8:11], v[188:191], v[232:235], v[8:11]
	v_mfma_f32_16x16x32_bf16 v[2:5], v[196:199], v[232:235], v[4:7]
	v_mfma_f32_16x16x32_bf16 v[56:59], v[192:195], v[208:211], v[56:59]
	v_mfma_f32_16x16x32_bf16 v[52:55], v[200:203], v[208:211], v[52:55]
	v_mfma_f32_16x16x32_bf16 v[40:43], v[192:195], v[216:219], v[40:43]
	v_mfma_f32_16x16x32_bf16 v[36:39], v[200:203], v[216:219], v[36:39]
	v_mfma_f32_16x16x32_bf16 v[24:27], v[192:195], v[224:227], v[24:27]
	v_mfma_f32_16x16x32_bf16 v[20:23], v[200:203], v[224:227], v[20:23]
	v_mfma_f32_16x16x32_bf16 v[8:11], v[192:195], v[242:245], v[8:11]
	v_mfma_f32_16x16x32_bf16 v[2:5], v[200:203], v[242:245], v[2:5]
	s_setprio 0
	s_barrier
	s_add_i32 s50, 0, 0x18000
	v_add_u32_e32 v0, s50, v169
	s_add_i32 s51, 0, 0x1c000
	ds_read_b128 v[172:175], v0
	ds_read_b128 v[176:179], v0 offset:1024
	ds_read_b128 v[180:183], v0 offset:2048
	ds_read_b128 v[184:187], v0 offset:3072
	v_add_u32_e32 v0, s51, v169
	ds_read_b128 v[188:191], v0
	ds_read_b128 v[192:195], v0 offset:1024
	ds_read_b128 v[196:199], v0 offset:2048
	ds_read_b128 v[200:203], v0 offset:3072
	s_add_u32 s48, s8, 0x40000
	v_mov_b32_e32 v0, v164
	s_mov_b32 m0, s23
	ds_read_b128 v[204:207], v170 offset:32768
	ds_read_b128 v[208:211], v170 offset:33792
	ds_read_b128 v[212:215], v170 offset:34816
	ds_read_b128 v[216:219], v170 offset:35840
	ds_read_b128 v[220:223], v170 offset:36864
	ds_read_b128 v[224:227], v170 offset:37888
	ds_read_b128 v[232:235], v170 offset:38912
	ds_read_b128 v[242:245], v170 offset:39936
	s_addc_u32 s49, s9, 0
	s_nop 0
	global_load_lds_dwordx4 v0, s[48:49]
	v_mov_b32_e32 v0, v166
	s_mov_b32 m0, s24
	s_nop 0
	global_load_lds_dwordx4 v0, s[48:49]
	s_waitcnt vmcnt(8)
	s_waitcnt lgkmcnt(0)
	s_barrier
	s_setprio 1
	s_waitcnt lgkmcnt(0)
	v_mfma_f32_16x16x32_bf16 v[160:163], v[172:175], v[204:207], v[160:163]
	v_mfma_f32_16x16x32_bf16 v[156:159], v[180:183], v[204:207], v[156:159]
	v_mfma_f32_16x16x32_bf16 v[112:115], v[172:175], v[212:215], v[112:115]
	v_mfma_f32_16x16x32_bf16 v[108:111], v[180:183], v[212:215], v[108:111]
	v_mfma_f32_16x16x32_bf16 v[96:99], v[172:175], v[220:223], v[96:99]
	v_mfma_f32_16x16x32_bf16 v[92:95], v[180:183], v[220:223], v[92:95]
	v_mfma_f32_16x16x32_bf16 v[80:83], v[172:175], v[232:235], v[80:83]
	v_mfma_f32_16x16x32_bf16 v[76:79], v[180:183], v[232:235], v[76:79]
	v_mfma_f32_16x16x32_bf16 v[160:163], v[176:179], v[208:211], v[160:163]
	v_mfma_f32_16x16x32_bf16 v[156:159], v[184:187], v[208:211], v[156:159]
	v_mfma_f32_16x16x32_bf16 v[112:115], v[176:179], v[216:219], v[112:115]
	v_mfma_f32_16x16x32_bf16 v[108:111], v[184:187], v[216:219], v[108:111]
	v_mfma_f32_16x16x32_bf16 v[96:99], v[176:179], v[224:227], v[96:99]
	v_mfma_f32_16x16x32_bf16 v[92:95], v[184:187], v[224:227], v[92:95]
	v_mfma_f32_16x16x32_bf16 v[80:83], v[176:179], v[242:245], v[80:83]
	v_mfma_f32_16x16x32_bf16 v[76:79], v[184:187], v[242:245], v[76:79]
	s_setprio 0
	s_setprio 1
	v_mfma_f32_16x16x32_bf16 v[128:131], v[188:191], v[204:207], v[128:131]
	v_mfma_f32_16x16x32_bf16 v[120:123], v[196:199], v[204:207], v[120:123]
	v_mfma_f32_16x16x32_bf16 v[104:107], v[188:191], v[212:215], v[104:107]
	v_mfma_f32_16x16x32_bf16 v[100:103], v[196:199], v[212:215], v[100:103]
	v_mfma_f32_16x16x32_bf16 v[88:91], v[188:191], v[220:223], v[88:91]
	v_mfma_f32_16x16x32_bf16 v[84:87], v[196:199], v[220:223], v[84:87]
	v_mfma_f32_16x16x32_bf16 v[72:75], v[188:191], v[232:235], v[72:75]
	v_mfma_f32_16x16x32_bf16 v[68:71], v[196:199], v[232:235], v[68:71]
	v_mfma_f32_16x16x32_bf16 v[128:131], v[192:195], v[208:211], v[128:131]
	v_mfma_f32_16x16x32_bf16 v[120:123], v[200:203], v[208:211], v[120:123]
	v_mfma_f32_16x16x32_bf16 v[104:107], v[192:195], v[216:219], v[104:107]
	v_mfma_f32_16x16x32_bf16 v[100:103], v[200:203], v[216:219], v[100:103]
	v_mfma_f32_16x16x32_bf16 v[88:91], v[192:195], v[224:227], v[88:91]
	v_mfma_f32_16x16x32_bf16 v[84:87], v[200:203], v[224:227], v[84:87]
	v_mfma_f32_16x16x32_bf16 v[72:75], v[192:195], v[242:245], v[72:75]
	v_mfma_f32_16x16x32_bf16 v[68:71], v[200:203], v[242:245], v[68:71]
	s_setprio 0
	s_barrier
	v_mov_b32_e32 v0, v167
	ds_read_b128 v[204:207], v170 offset:49152
	ds_read_b128 v[208:211], v170 offset:50176
	ds_read_b128 v[212:215], v170 offset:51200
	ds_read_b128 v[216:219], v170 offset:52224
	ds_read_b128 v[220:223], v170 offset:53248
	ds_read_b128 v[224:227], v170 offset:54272
	ds_read_b128 v[232:235], v170 offset:55296
	ds_read_b128 v[242:245], v170 offset:56320
	s_add_i32 s48, s50, s16
	s_add_u32 s100, s10, s38
	s_addc_u32 s101, s11, s39
	s_mov_b32 m0, s48
	v_mov_b32_e32 v0, v168
	global_load_lds_dwordx4 v167, s[100:101]
	s_add_i32 m0, s48, 0x2000
	s_nop 0
	s_add_u32 s10, s10, 0x40080
	s_addc_u32 s11, s11, 0
	v_mov_b32_e32 v0, v167
	s_add_i32 s48, s51, s16
	global_load_lds_dwordx4 v168, s[100:101]
	s_mov_b32 m0, s48
	s_nop 0
	global_load_lds_dwordx4 v0, s[10:11]
	v_mov_b32_e32 v0, v168
	s_add_i32 m0, s48, 0x2000
	s_nop 0
	global_load_lds_dwordx4 v0, s[10:11]
	v_mov_b32_e32 v0, v164
	s_mov_b32 m0, s37
	s_add_u32 s100, s8, s38
	s_addc_u32 s101, s9, s39
	v_mov_b32_e32 v0, v166
	global_load_lds_dwordx4 v164, s[100:101]
	s_mov_b32 m0, s40
	s_nop 0
	global_load_lds_dwordx4 v166, s[100:101]
	s_waitcnt vmcnt(8)
	s_waitcnt lgkmcnt(0)
	s_barrier
	s_setprio 1
	s_waitcnt lgkmcnt(0)
	v_mfma_f32_16x16x32_bf16 v[64:67], v[172:175], v[204:207], v[64:67]
	v_mfma_f32_16x16x32_bf16 v[60:63], v[180:183], v[204:207], v[60:63]
	v_mfma_f32_16x16x32_bf16 v[48:51], v[172:175], v[212:215], v[48:51]
	v_mfma_f32_16x16x32_bf16 v[44:47], v[180:183], v[212:215], v[44:47]
	v_mfma_f32_16x16x32_bf16 v[32:35], v[172:175], v[220:223], v[32:35]
	v_mfma_f32_16x16x32_bf16 v[28:31], v[180:183], v[220:223], v[28:31]
	v_mfma_f32_16x16x32_bf16 v[16:19], v[172:175], v[232:235], v[16:19]
	v_mfma_f32_16x16x32_bf16 v[12:15], v[180:183], v[232:235], v[12:15]
	v_mfma_f32_16x16x32_bf16 v[64:67], v[176:179], v[208:211], v[64:67]
	v_mfma_f32_16x16x32_bf16 v[60:63], v[184:187], v[208:211], v[60:63]
	v_mfma_f32_16x16x32_bf16 v[48:51], v[176:179], v[216:219], v[48:51]
	v_mfma_f32_16x16x32_bf16 v[44:47], v[184:187], v[216:219], v[44:47]
	v_mfma_f32_16x16x32_bf16 v[32:35], v[176:179], v[224:227], v[32:35]
	v_mfma_f32_16x16x32_bf16 v[28:31], v[184:187], v[224:227], v[28:31]
	v_mfma_f32_16x16x32_bf16 v[16:19], v[176:179], v[242:245], v[16:19]
	v_mfma_f32_16x16x32_bf16 v[12:15], v[184:187], v[242:245], v[12:15]
	s_setprio 0
	s_setprio 1
	v_mfma_f32_16x16x32_bf16 v[56:59], v[188:191], v[204:207], v[56:59]
	v_mfma_f32_16x16x32_bf16 v[52:55], v[196:199], v[204:207], v[52:55]
	v_mfma_f32_16x16x32_bf16 v[40:43], v[188:191], v[212:215], v[40:43]
	v_mfma_f32_16x16x32_bf16 v[36:39], v[196:199], v[212:215], v[36:39]
	v_mfma_f32_16x16x32_bf16 v[24:27], v[188:191], v[220:223], v[24:27]
	v_mfma_f32_16x16x32_bf16 v[20:23], v[196:199], v[220:223], v[20:23]
	v_mfma_f32_16x16x32_bf16 v[6:9], v[188:191], v[232:235], v[8:11]
	v_mfma_f32_16x16x32_bf16 v[2:5], v[196:199], v[232:235], v[2:5]
	v_mfma_f32_16x16x32_bf16 v[56:59], v[192:195], v[208:211], v[56:59]
	v_mfma_f32_16x16x32_bf16 v[52:55], v[200:203], v[208:211], v[52:55]
	v_mfma_f32_16x16x32_bf16 v[40:43], v[192:195], v[216:219], v[40:43]
	v_mfma_f32_16x16x32_bf16 v[36:39], v[200:203], v[216:219], v[36:39]
	v_mfma_f32_16x16x32_bf16 v[24:27], v[192:195], v[224:227], v[24:27]
	v_mfma_f32_16x16x32_bf16 v[20:23], v[200:203], v[224:227], v[20:23]
	v_mfma_f32_16x16x32_bf16 v[8:11], v[192:195], v[242:245], v[6:9]
	v_mfma_f32_16x16x32_bf16 v[4:7], v[200:203], v[242:245], v[2:5]
	s_setprio 0
	s_barrier
	s_add_i32 s47, s47, 2
	s_add_u32 s6, s6, 0x100
	s_addc_u32 s7, s7, 0
	s_cmp_gt_u32 s47, 13
	s_cbranch_scc1 .LBB0_1573

.LBB0_1681:
	s_add_u32 s48, s6, s2
	s_addc_u32 s49, s7, s3
	s_add_u32 s10, s48, 0x100
	s_addc_u32 s11, s49, 0
	s_add_u32 s12, s37, s2
	s_addc_u32 s13, s40, s3
	s_add_i32 s47, 0, 0x10000
	s_cmp_eq_u32 s46, 12
	s_cselect_b32 s11, s7, s11
	s_cselect_b32 s10, s6, s10
	v_add_u32_e32 v0, s47, v136
	s_cselect_b32 s13, s9, s13
	s_cselect_b32 s12, s8, s12
	s_add_i32 s50, 0, 0x14000
	ds_read_b128 v[138:141], v0
	ds_read_b128 v[142:145], v0 offset:1024
	ds_read_b128 v[146:149], v0 offset:2048
	ds_read_b128 v[150:153], v0 offset:3072
	v_add_u32_e32 v0, s50, v136
	ds_read_b128 v[154:157], v0
	ds_read_b128 v[158:161], v0 offset:1024
	ds_read_b128 v[162:165], v0 offset:2048
	ds_read_b128 v[166:169], v0 offset:3072
	v_mov_b32_e32 v0, v130
	ds_read_b128 v[170:173], v137
	ds_read_b128 v[174:177], v137 offset:1024
	ds_read_b128 v[178:181], v137 offset:2048
	ds_read_b128 v[182:185], v137 offset:3072
	ds_read_b128 v[186:189], v137 offset:4096
	ds_read_b128 v[190:193], v137 offset:5120
	ds_read_b128 v[194:197], v137 offset:6144
	ds_read_b128 v[198:201], v137 offset:7168
	s_add_i32 m0, s23, 0xc000
	s_add_u32 s100, s48, s56
	s_addc_u32 s101, s49, s57
	v_mov_b32_e32 v0, v132
	global_load_lds_dwordx4 v130, s[100:101]
	s_add_i32 m0, s23, 0xe000
	s_nop 0
	global_load_lds_dwordx4 v132, s[100:101]
	s_waitcnt vmcnt(8)
	s_waitcnt lgkmcnt(0)
	s_barrier
	s_setprio 1
	s_waitcnt lgkmcnt(0)
	v_mfma_f32_16x16x32_bf16 v[126:129], v[138:141], v[170:173], v[126:129]
	v_mfma_f32_16x16x32_bf16 v[122:125], v[146:149], v[170:173], v[122:125]
	v_mfma_f32_16x16x32_bf16 v[110:113], v[138:141], v[178:181], v[110:113]
	v_mfma_f32_16x16x32_bf16 v[106:109], v[146:149], v[178:181], v[106:109]
	v_mfma_f32_16x16x32_bf16 v[94:97], v[138:141], v[186:189], v[94:97]
	v_mfma_f32_16x16x32_bf16 v[90:93], v[146:149], v[186:189], v[90:93]
	v_mfma_f32_16x16x32_bf16 v[78:81], v[138:141], v[194:197], v[78:81]
	v_mfma_f32_16x16x32_bf16 v[74:77], v[146:149], v[194:197], v[74:77]
	v_mfma_f32_16x16x32_bf16 v[126:129], v[142:145], v[174:177], v[126:129]
	v_mfma_f32_16x16x32_bf16 v[122:125], v[150:153], v[174:177], v[122:125]
	v_mfma_f32_16x16x32_bf16 v[110:113], v[142:145], v[182:185], v[110:113]
	v_mfma_f32_16x16x32_bf16 v[106:109], v[150:153], v[182:185], v[106:109]
	v_mfma_f32_16x16x32_bf16 v[94:97], v[142:145], v[190:193], v[94:97]
	v_mfma_f32_16x16x32_bf16 v[90:93], v[150:153], v[190:193], v[90:93]
	v_mfma_f32_16x16x32_bf16 v[78:81], v[142:145], v[198:201], v[78:81]
	v_mfma_f32_16x16x32_bf16 v[74:77], v[150:153], v[198:201], v[74:77]
	s_setprio 0
	s_setprio 1
	v_mfma_f32_16x16x32_bf16 v[118:121], v[154:157], v[170:173], v[118:121]
	v_mfma_f32_16x16x32_bf16 v[114:117], v[162:165], v[170:173], v[114:117]
	v_mfma_f32_16x16x32_bf16 v[102:105], v[154:157], v[178:181], v[102:105]
	v_mfma_f32_16x16x32_bf16 v[98:101], v[162:165], v[178:181], v[98:101]
	v_mfma_f32_16x16x32_bf16 v[86:89], v[154:157], v[186:189], v[86:89]
	v_mfma_f32_16x16x32_bf16 v[82:85], v[162:165], v[186:189], v[82:85]
	v_mfma_f32_16x16x32_bf16 v[70:73], v[154:157], v[194:197], v[70:73]
	v_mfma_f32_16x16x32_bf16 v[66:69], v[162:165], v[194:197], v[66:69]
	v_mfma_f32_16x16x32_bf16 v[118:121], v[158:161], v[174:177], v[118:121]
	v_mfma_f32_16x16x32_bf16 v[114:117], v[166:169], v[174:177], v[114:117]
	v_mfma_f32_16x16x32_bf16 v[102:105], v[158:161], v[182:185], v[102:105]
	v_mfma_f32_16x16x32_bf16 v[98:101], v[166:169], v[182:185], v[98:101]
	v_mfma_f32_16x16x32_bf16 v[86:89], v[158:161], v[190:193], v[86:89]
	v_mfma_f32_16x16x32_bf16 v[82:85], v[166:169], v[190:193], v[82:85]
	v_mfma_f32_16x16x32_bf16 v[70:73], v[158:161], v[198:201], v[70:73]
	v_mfma_f32_16x16x32_bf16 v[66:69], v[166:169], v[198:201], v[66:69]
	s_setprio 0
	s_barrier
	v_mov_b32_e32 v0, v134
	s_add_i32 s47, s47, s22
	ds_read_b128 v[170:173], v137 offset:16384
	ds_read_b128 v[174:177], v137 offset:17408
	ds_read_b128 v[178:181], v137 offset:18432
	ds_read_b128 v[182:185], v137 offset:19456
	ds_read_b128 v[186:189], v137 offset:20480
	ds_read_b128 v[190:193], v137 offset:21504
	ds_read_b128 v[194:197], v137 offset:22528
	ds_read_b128 v[198:201], v137 offset:23552
	s_mov_b32 m0, s47
	s_nop 0
	global_load_lds_dwordx4 v0, s[12:13]
	v_mov_b32_e32 v0, v135
	s_add_i32 m0, s47, 0x2000
	s_add_u32 s48, s12, 0x40000
	global_load_lds_dwordx4 v0, s[12:13]
	s_addc_u32 s49, s13, 0
	v_mov_b32_e32 v0, v134
	s_add_i32 s47, s50, s22
	s_mov_b32 m0, s47
	s_nop 0
	global_load_lds_dwordx4 v0, s[48:49]
	v_mov_b32_e32 v0, v135
	s_add_i32 m0, s47, 0x2000
	s_nop 0
	global_load_lds_dwordx4 v0, s[48:49]
	v_mov_b32_e32 v0, v130
	s_mov_b32 m0, s23
	s_nop 0
	global_load_lds_dwordx4 v0, s[10:11]
	v_mov_b32_e32 v0, v132
	s_mov_b32 m0, s24
	s_nop 0
	global_load_lds_dwordx4 v0, s[10:11]
	s_waitcnt vmcnt(8)
	s_waitcnt lgkmcnt(0)
	s_barrier
	s_setprio 1
	s_waitcnt lgkmcnt(0)
	v_mfma_f32_16x16x32_bf16 v[62:65], v[138:141], v[170:173], v[62:65]
	v_mfma_f32_16x16x32_bf16 v[58:61], v[146:149], v[170:173], v[58:61]
	v_mfma_f32_16x16x32_bf16 v[46:49], v[138:141], v[178:181], v[46:49]
	v_mfma_f32_16x16x32_bf16 v[42:45], v[146:149], v[178:181], v[42:45]
	v_mfma_f32_16x16x32_bf16 v[30:33], v[138:141], v[186:189], v[30:33]
	v_mfma_f32_16x16x32_bf16 v[26:29], v[146:149], v[186:189], v[26:29]
	v_mfma_f32_16x16x32_bf16 v[14:17], v[138:141], v[194:197], v[14:17]
	v_mfma_f32_16x16x32_bf16 v[10:13], v[146:149], v[194:197], v[10:13]
	v_mfma_f32_16x16x32_bf16 v[62:65], v[142:145], v[174:177], v[62:65]
	v_mfma_f32_16x16x32_bf16 v[58:61], v[150:153], v[174:177], v[58:61]
	v_mfma_f32_16x16x32_bf16 v[46:49], v[142:145], v[182:185], v[46:49]
	v_mfma_f32_16x16x32_bf16 v[42:45], v[150:153], v[182:185], v[42:45]
	v_mfma_f32_16x16x32_bf16 v[30:33], v[142:145], v[190:193], v[30:33]
	v_mfma_f32_16x16x32_bf16 v[26:29], v[150:153], v[190:193], v[26:29]
	v_mfma_f32_16x16x32_bf16 v[14:17], v[142:145], v[198:201], v[14:17]
	v_mfma_f32_16x16x32_bf16 v[10:13], v[150:153], v[198:201], v[10:13]
	s_setprio 0
	s_setprio 1
	v_mfma_f32_16x16x32_bf16 v[54:57], v[154:157], v[170:173], v[54:57]
	v_mfma_f32_16x16x32_bf16 v[50:53], v[162:165], v[170:173], v[50:53]
	v_mfma_f32_16x16x32_bf16 v[38:41], v[154:157], v[178:181], v[38:41]
	v_mfma_f32_16x16x32_bf16 v[34:37], v[162:165], v[178:181], v[34:37]
	v_mfma_f32_16x16x32_bf16 v[22:25], v[154:157], v[186:189], v[22:25]
	v_mfma_f32_16x16x32_bf16 v[18:21], v[162:165], v[186:189], v[18:21]
	v_mfma_f32_16x16x32_bf16 v[6:9], v[154:157], v[194:197], v[6:9]
	v_mfma_f32_16x16x32_bf16 v[2:5], v[162:165], v[194:197], v[2:5]
	v_mfma_f32_16x16x32_bf16 v[54:57], v[158:161], v[174:177], v[54:57]
	v_mfma_f32_16x16x32_bf16 v[50:53], v[166:169], v[174:177], v[50:53]
	v_mfma_f32_16x16x32_bf16 v[38:41], v[158:161], v[182:185], v[38:41]
	v_mfma_f32_16x16x32_bf16 v[34:37], v[166:169], v[182:185], v[34:37]
	v_mfma_f32_16x16x32_bf16 v[22:25], v[158:161], v[190:193], v[22:25]
	v_mfma_f32_16x16x32_bf16 v[18:21], v[166:169], v[190:193], v[18:21]
	v_mfma_f32_16x16x32_bf16 v[6:9], v[158:161], v[198:201], v[6:9]
	v_mfma_f32_16x16x32_bf16 v[2:5], v[166:169], v[198:201], v[2:5]
	s_setprio 0
	s_barrier
	s_add_i32 s47, 0, 0x18000
	v_add_u32_e32 v0, s47, v136
	s_add_i32 s50, 0, 0x1c000
	ds_read_b128 v[138:141], v0
	ds_read_b128 v[142:145], v0 offset:1024
	ds_read_b128 v[146:149], v0 offset:2048
	ds_read_b128 v[150:153], v0 offset:3072
	v_add_u32_e32 v0, s50, v136
	ds_read_b128 v[154:157], v0
	ds_read_b128 v[158:161], v0 offset:1024
	ds_read_b128 v[162:165], v0 offset:2048
	ds_read_b128 v[166:169], v0 offset:3072
	s_add_u32 s48, s10, 0x40000
	v_mov_b32_e32 v0, v130
	s_mov_b32 m0, s25
	ds_read_b128 v[170:173], v137 offset:32768
	ds_read_b128 v[174:177], v137 offset:33792
	ds_read_b128 v[178:181], v137 offset:34816
	ds_read_b128 v[182:185], v137 offset:35840
	ds_read_b128 v[186:189], v137 offset:36864
	ds_read_b128 v[190:193], v137 offset:37888
	ds_read_b128 v[194:197], v137 offset:38912
	ds_read_b128 v[198:201], v137 offset:39936
	s_addc_u32 s49, s11, 0
	s_nop 0
	global_load_lds_dwordx4 v0, s[48:49]
	v_mov_b32_e32 v0, v132
	s_mov_b32 m0, s26
	s_nop 0
	global_load_lds_dwordx4 v0, s[48:49]
	s_waitcnt vmcnt(8)
	s_waitcnt lgkmcnt(0)
	s_barrier
	s_setprio 1
	s_waitcnt lgkmcnt(0)
	v_mfma_f32_16x16x32_bf16 v[126:129], v[138:141], v[170:173], v[126:129]
	v_mfma_f32_16x16x32_bf16 v[122:125], v[146:149], v[170:173], v[122:125]
	v_mfma_f32_16x16x32_bf16 v[110:113], v[138:141], v[178:181], v[110:113]
	v_mfma_f32_16x16x32_bf16 v[106:109], v[146:149], v[178:181], v[106:109]
	v_mfma_f32_16x16x32_bf16 v[94:97], v[138:141], v[186:189], v[94:97]
	v_mfma_f32_16x16x32_bf16 v[90:93], v[146:149], v[186:189], v[90:93]
	v_mfma_f32_16x16x32_bf16 v[78:81], v[138:141], v[194:197], v[78:81]
	v_mfma_f32_16x16x32_bf16 v[74:77], v[146:149], v[194:197], v[74:77]
	v_mfma_f32_16x16x32_bf16 v[126:129], v[142:145], v[174:177], v[126:129]
	v_mfma_f32_16x16x32_bf16 v[122:125], v[150:153], v[174:177], v[122:125]
	v_mfma_f32_16x16x32_bf16 v[110:113], v[142:145], v[182:185], v[110:113]
	v_mfma_f32_16x16x32_bf16 v[106:109], v[150:153], v[182:185], v[106:109]
	v_mfma_f32_16x16x32_bf16 v[94:97], v[142:145], v[190:193], v[94:97]
	v_mfma_f32_16x16x32_bf16 v[90:93], v[150:153], v[190:193], v[90:93]
	v_mfma_f32_16x16x32_bf16 v[78:81], v[142:145], v[198:201], v[78:81]
	v_mfma_f32_16x16x32_bf16 v[74:77], v[150:153], v[198:201], v[74:77]
	s_setprio 0
	s_setprio 1
	v_mfma_f32_16x16x32_bf16 v[118:121], v[154:157], v[170:173], v[118:121]
	v_mfma_f32_16x16x32_bf16 v[114:117], v[162:165], v[170:173], v[114:117]
	v_mfma_f32_16x16x32_bf16 v[102:105], v[154:157], v[178:181], v[102:105]
	v_mfma_f32_16x16x32_bf16 v[98:101], v[162:165], v[178:181], v[98:101]
	v_mfma_f32_16x16x32_bf16 v[86:89], v[154:157], v[186:189], v[86:89]
	v_mfma_f32_16x16x32_bf16 v[82:85], v[162:165], v[186:189], v[82:85]
	v_mfma_f32_16x16x32_bf16 v[70:73], v[154:157], v[194:197], v[70:73]
	v_mfma_f32_16x16x32_bf16 v[66:69], v[162:165], v[194:197], v[66:69]
	v_mfma_f32_16x16x32_bf16 v[118:121], v[158:161], v[174:177], v[118:121]
	v_mfma_f32_16x16x32_bf16 v[114:117], v[166:169], v[174:177], v[114:117]
	v_mfma_f32_16x16x32_bf16 v[102:105], v[158:161], v[182:185], v[102:105]
	v_mfma_f32_16x16x32_bf16 v[98:101], v[166:169], v[182:185], v[98:101]
	v_mfma_f32_16x16x32_bf16 v[86:89], v[158:161], v[190:193], v[86:89]
	v_mfma_f32_16x16x32_bf16 v[82:85], v[166:169], v[190:193], v[82:85]
	v_mfma_f32_16x16x32_bf16 v[70:73], v[158:161], v[198:201], v[70:73]
	v_mfma_f32_16x16x32_bf16 v[66:69], v[166:169], v[198:201], v[66:69]
	s_setprio 0
	s_barrier
	v_mov_b32_e32 v0, v134
	ds_read_b128 v[170:173], v137 offset:49152
	ds_read_b128 v[174:177], v137 offset:50176
	ds_read_b128 v[178:181], v137 offset:51200
	ds_read_b128 v[182:185], v137 offset:52224
	ds_read_b128 v[186:189], v137 offset:53248
	ds_read_b128 v[190:193], v137 offset:54272
	ds_read_b128 v[194:197], v137 offset:55296
	ds_read_b128 v[198:201], v137 offset:56320
	s_add_i32 s47, s47, s22
	s_add_u32 s100, s12, s38
	s_addc_u32 s101, s13, s39
	s_mov_b32 m0, s47
	v_mov_b32_e32 v0, v135
	global_load_lds_dwordx4 v134, s[100:101]
	s_add_i32 m0, s47, 0x2000
	s_nop 0
	s_add_u32 s12, s12, 0x40080
	s_addc_u32 s13, s13, 0
	v_mov_b32_e32 v0, v134
	s_add_i32 s47, s50, s22
	global_load_lds_dwordx4 v135, s[100:101]
	s_mov_b32 m0, s47
	s_nop 0
	global_load_lds_dwordx4 v0, s[12:13]
	v_mov_b32_e32 v0, v135
	s_add_i32 m0, s47, 0x2000
	s_nop 0
	global_load_lds_dwordx4 v0, s[12:13]
	v_mov_b32_e32 v0, v130
	s_mov_b32 m0, s42
	s_add_u32 s100, s10, s38
	s_addc_u32 s101, s11, s39
	v_mov_b32_e32 v0, v132
	global_load_lds_dwordx4 v130, s[100:101]
	s_mov_b32 m0, s43
	s_nop 0
	global_load_lds_dwordx4 v132, s[100:101]
	s_waitcnt vmcnt(8)
	s_waitcnt lgkmcnt(0)
	s_barrier
	s_setprio 1
	s_waitcnt lgkmcnt(0)
	v_mfma_f32_16x16x32_bf16 v[62:65], v[138:141], v[170:173], v[62:65]
	v_mfma_f32_16x16x32_bf16 v[58:61], v[146:149], v[170:173], v[58:61]
	v_mfma_f32_16x16x32_bf16 v[46:49], v[138:141], v[178:181], v[46:49]
	v_mfma_f32_16x16x32_bf16 v[42:45], v[146:149], v[178:181], v[42:45]
	v_mfma_f32_16x16x32_bf16 v[30:33], v[138:141], v[186:189], v[30:33]
	v_mfma_f32_16x16x32_bf16 v[26:29], v[146:149], v[186:189], v[26:29]
	v_mfma_f32_16x16x32_bf16 v[14:17], v[138:141], v[194:197], v[14:17]
	v_mfma_f32_16x16x32_bf16 v[10:13], v[146:149], v[194:197], v[10:13]
	v_mfma_f32_16x16x32_bf16 v[62:65], v[142:145], v[174:177], v[62:65]
	v_mfma_f32_16x16x32_bf16 v[58:61], v[150:153], v[174:177], v[58:61]
	v_mfma_f32_16x16x32_bf16 v[46:49], v[142:145], v[182:185], v[46:49]
	v_mfma_f32_16x16x32_bf16 v[42:45], v[150:153], v[182:185], v[42:45]
	v_mfma_f32_16x16x32_bf16 v[30:33], v[142:145], v[190:193], v[30:33]
	v_mfma_f32_16x16x32_bf16 v[26:29], v[150:153], v[190:193], v[26:29]
	v_mfma_f32_16x16x32_bf16 v[14:17], v[142:145], v[198:201], v[14:17]
	v_mfma_f32_16x16x32_bf16 v[10:13], v[150:153], v[198:201], v[10:13]
	s_setprio 0
	s_setprio 1
	v_mfma_f32_16x16x32_bf16 v[54:57], v[154:157], v[170:173], v[54:57]
	v_mfma_f32_16x16x32_bf16 v[50:53], v[162:165], v[170:173], v[50:53]
	v_mfma_f32_16x16x32_bf16 v[38:41], v[154:157], v[178:181], v[38:41]
	v_mfma_f32_16x16x32_bf16 v[34:37], v[162:165], v[178:181], v[34:37]
	v_mfma_f32_16x16x32_bf16 v[22:25], v[154:157], v[186:189], v[22:25]
	v_mfma_f32_16x16x32_bf16 v[18:21], v[162:165], v[186:189], v[18:21]
	v_mfma_f32_16x16x32_bf16 v[6:9], v[154:157], v[194:197], v[6:9]
	v_mfma_f32_16x16x32_bf16 v[2:5], v[162:165], v[194:197], v[2:5]
	v_mfma_f32_16x16x32_bf16 v[54:57], v[158:161], v[174:177], v[54:57]
	v_mfma_f32_16x16x32_bf16 v[50:53], v[166:169], v[174:177], v[50:53]
	v_mfma_f32_16x16x32_bf16 v[38:41], v[158:161], v[182:185], v[38:41]
	v_mfma_f32_16x16x32_bf16 v[34:37], v[166:169], v[182:185], v[34:37]
	v_mfma_f32_16x16x32_bf16 v[22:25], v[158:161], v[190:193], v[22:25]
	v_mfma_f32_16x16x32_bf16 v[18:21], v[166:169], v[190:193], v[18:21]
	v_mfma_f32_16x16x32_bf16 v[6:9], v[158:161], v[198:201], v[6:9]
	v_mfma_f32_16x16x32_bf16 v[2:5], v[166:169], v[198:201], v[2:5]
	s_setprio 0
	s_barrier
	s_add_i32 s46, s46, 2
	s_add_u32 s2, s2, 0x100
	s_addc_u32 s3, s3, 0
	s_cmp_gt_u32 s46, 13
	s_cbranch_scc0 .LBB0_1681
	s_cmpk_lt_u32 s17, 0x100
	s_cbranch_scc0 .LBB0_1684
	s_barrier

.LBB0_1807:
	s_add_u32 s68, s4, s14
	s_addc_u32 s69, s5, s15
	s_add_u32 s16, s68, 0x100
	s_addc_u32 s17, s69, 0
	s_add_u32 s22, s50, s14
	s_addc_u32 s23, s51, s15
	s_add_i32 s67, 0, 0x10000
	s_cmp_eq_u32 s66, 12
	s_cselect_b32 s17, s5, s17
	s_cselect_b32 s16, s4, s16
	v_add_u32_e32 v0, s67, v126
	s_cselect_b32 s23, s13, s23
	s_cselect_b32 s22, s12, s22
	s_add_i32 s70, 0, 0x14000
	ds_read_b128 v[128:131], v0
	ds_read_b128 v[142:145], v0 offset:1024
	ds_read_b128 v[146:149], v0 offset:2048
	ds_read_b128 v[150:153], v0 offset:3072
	v_add_u32_e32 v0, s70, v126
	ds_read_b128 v[154:157], v0
	ds_read_b128 v[160:163], v0 offset:1024
	ds_read_b128 v[164:167], v0 offset:2048
	ds_read_b128 v[168:171], v0 offset:3072
	v_mov_b32_e32 v0, v122
	ds_read_b128 v[172:175], v127
	ds_read_b128 v[176:179], v127 offset:1024
	ds_read_b128 v[180:183], v127 offset:2048
	ds_read_b128 v[184:187], v127 offset:3072
	ds_read_b128 v[188:191], v127 offset:4096
	ds_read_b128 v[192:195], v127 offset:5120
	ds_read_b128 v[196:199], v127 offset:6144
	ds_read_b128 v[200:203], v127 offset:7168
	s_add_i32 m0, s43, 0xc000
	s_add_u32 s100, s68, s56
	s_addc_u32 s101, s69, s57
	v_mov_b32_e32 v0, v123
	global_load_lds_dwordx4 v122, s[100:101]
	s_add_i32 m0, s43, 0xe000
	s_nop 0
	global_load_lds_dwordx4 v123, s[100:101]
	s_waitcnt vmcnt(8)
	s_waitcnt lgkmcnt(0)
	s_barrier
	s_setprio 1
	s_waitcnt lgkmcnt(0)
	v_mfma_f32_16x16x32_bf16 v[138:141], v[128:131], v[172:175], v[138:141]
	v_mfma_f32_16x16x32_bf16 v[132:135], v[146:149], v[172:175], v[134:137]
	v_mfma_f32_16x16x32_bf16 v[110:113], v[128:131], v[180:183], v[110:113]
	v_mfma_f32_16x16x32_bf16 v[106:109], v[146:149], v[180:183], v[106:109]
	v_mfma_f32_16x16x32_bf16 v[94:97], v[128:131], v[188:191], v[94:97]
	v_mfma_f32_16x16x32_bf16 v[90:93], v[146:149], v[188:191], v[90:93]
	v_mfma_f32_16x16x32_bf16 v[78:81], v[128:131], v[196:199], v[78:81]
	v_mfma_f32_16x16x32_bf16 v[74:77], v[146:149], v[196:199], v[74:77]
	v_mfma_f32_16x16x32_bf16 v[138:141], v[142:145], v[176:179], v[138:141]
	v_mfma_f32_16x16x32_bf16 v[132:135], v[150:153], v[176:179], v[132:135]
	v_mfma_f32_16x16x32_bf16 v[110:113], v[142:145], v[184:187], v[110:113]
	v_mfma_f32_16x16x32_bf16 v[106:109], v[150:153], v[184:187], v[106:109]
	v_mfma_f32_16x16x32_bf16 v[94:97], v[142:145], v[192:195], v[94:97]
	v_mfma_f32_16x16x32_bf16 v[90:93], v[150:153], v[192:195], v[90:93]
	v_mfma_f32_16x16x32_bf16 v[78:81], v[142:145], v[200:203], v[78:81]
	v_mfma_f32_16x16x32_bf16 v[74:77], v[150:153], v[200:203], v[74:77]
	s_setprio 0
	s_setprio 1
	v_mfma_f32_16x16x32_bf16 v[118:121], v[154:157], v[172:175], v[118:121]
	v_mfma_f32_16x16x32_bf16 v[114:117], v[164:167], v[172:175], v[114:117]
	v_mfma_f32_16x16x32_bf16 v[102:105], v[154:157], v[180:183], v[102:105]
	v_mfma_f32_16x16x32_bf16 v[98:101], v[164:167], v[180:183], v[98:101]
	v_mfma_f32_16x16x32_bf16 v[86:89], v[154:157], v[188:191], v[86:89]
	v_mfma_f32_16x16x32_bf16 v[82:85], v[164:167], v[188:191], v[82:85]
	v_mfma_f32_16x16x32_bf16 v[70:73], v[154:157], v[196:199], v[70:73]
	v_mfma_f32_16x16x32_bf16 v[66:69], v[164:167], v[196:199], v[66:69]
	v_mfma_f32_16x16x32_bf16 v[118:121], v[160:163], v[176:179], v[118:121]
	v_mfma_f32_16x16x32_bf16 v[114:117], v[168:171], v[176:179], v[114:117]
	v_mfma_f32_16x16x32_bf16 v[102:105], v[160:163], v[184:187], v[102:105]
	v_mfma_f32_16x16x32_bf16 v[98:101], v[168:171], v[184:187], v[98:101]
	v_mfma_f32_16x16x32_bf16 v[86:89], v[160:163], v[192:195], v[86:89]
	v_mfma_f32_16x16x32_bf16 v[82:85], v[168:171], v[192:195], v[82:85]
	v_mfma_f32_16x16x32_bf16 v[70:73], v[160:163], v[200:203], v[70:73]
	v_mfma_f32_16x16x32_bf16 v[66:69], v[168:171], v[200:203], v[66:69]
	s_setprio 0
	s_barrier
	v_mov_b32_e32 v0, v124
	s_add_i32 s67, s67, s42
	ds_read_b128 v[172:175], v127 offset:16384
	ds_read_b128 v[176:179], v127 offset:17408
	ds_read_b128 v[180:183], v127 offset:18432
	ds_read_b128 v[184:187], v127 offset:19456
	ds_read_b128 v[188:191], v127 offset:20480
	ds_read_b128 v[192:195], v127 offset:21504
	ds_read_b128 v[196:199], v127 offset:22528
	ds_read_b128 v[200:203], v127 offset:23552
	s_mov_b32 m0, s67
	s_nop 0
	global_load_lds_dwordx4 v0, s[22:23]
	v_mov_b32_e32 v0, v125
	s_add_i32 m0, s67, 0x2000
	s_add_u32 s68, s22, 0x40000
	global_load_lds_dwordx4 v0, s[22:23]
	s_addc_u32 s69, s23, 0
	v_mov_b32_e32 v0, v124
	s_add_i32 s67, s70, s42
	s_mov_b32 m0, s67
	s_nop 0
	global_load_lds_dwordx4 v0, s[68:69]
	v_mov_b32_e32 v0, v125
	s_add_i32 m0, s67, 0x2000
	s_nop 0
	global_load_lds_dwordx4 v0, s[68:69]
	v_mov_b32_e32 v0, v122
	s_mov_b32 m0, s43
	s_nop 0
	global_load_lds_dwordx4 v0, s[16:17]
	v_mov_b32_e32 v0, v123
	s_mov_b32 m0, s46
	s_nop 0
	global_load_lds_dwordx4 v0, s[16:17]
	s_waitcnt vmcnt(8)
	s_waitcnt lgkmcnt(0)
	s_barrier
	s_setprio 1
	s_waitcnt lgkmcnt(0)
	v_mfma_f32_16x16x32_bf16 v[62:65], v[128:131], v[172:175], v[62:65]
	v_mfma_f32_16x16x32_bf16 v[58:61], v[146:149], v[172:175], v[58:61]
	v_mfma_f32_16x16x32_bf16 v[46:49], v[128:131], v[180:183], v[46:49]
	v_mfma_f32_16x16x32_bf16 v[42:45], v[146:149], v[180:183], v[42:45]
	v_mfma_f32_16x16x32_bf16 v[30:33], v[128:131], v[188:191], v[30:33]
	v_mfma_f32_16x16x32_bf16 v[26:29], v[146:149], v[188:191], v[26:29]
	v_mfma_f32_16x16x32_bf16 v[14:17], v[128:131], v[196:199], v[14:17]
	v_mfma_f32_16x16x32_bf16 v[10:13], v[146:149], v[196:199], v[10:13]
	v_mfma_f32_16x16x32_bf16 v[62:65], v[142:145], v[176:179], v[62:65]
	v_mfma_f32_16x16x32_bf16 v[58:61], v[150:153], v[176:179], v[58:61]
	v_mfma_f32_16x16x32_bf16 v[46:49], v[142:145], v[184:187], v[46:49]
	v_mfma_f32_16x16x32_bf16 v[42:45], v[150:153], v[184:187], v[42:45]
	v_mfma_f32_16x16x32_bf16 v[30:33], v[142:145], v[192:195], v[30:33]
	v_mfma_f32_16x16x32_bf16 v[26:29], v[150:153], v[192:195], v[26:29]
	v_mfma_f32_16x16x32_bf16 v[14:17], v[142:145], v[200:203], v[14:17]
	v_mfma_f32_16x16x32_bf16 v[10:13], v[150:153], v[200:203], v[10:13]
	s_setprio 0
	s_setprio 1
	v_mfma_f32_16x16x32_bf16 v[54:57], v[154:157], v[172:175], v[54:57]
	v_mfma_f32_16x16x32_bf16 v[50:53], v[164:167], v[172:175], v[50:53]
	v_mfma_f32_16x16x32_bf16 v[38:41], v[154:157], v[180:183], v[38:41]
	v_mfma_f32_16x16x32_bf16 v[34:37], v[164:167], v[180:183], v[34:37]
	v_mfma_f32_16x16x32_bf16 v[22:25], v[154:157], v[188:191], v[22:25]
	v_mfma_f32_16x16x32_bf16 v[18:21], v[164:167], v[188:191], v[18:21]
	v_mfma_f32_16x16x32_bf16 v[6:9], v[154:157], v[196:199], v[6:9]
	v_mfma_f32_16x16x32_bf16 v[2:5], v[164:167], v[196:199], v[2:5]
	v_mfma_f32_16x16x32_bf16 v[54:57], v[160:163], v[176:179], v[54:57]
	v_mfma_f32_16x16x32_bf16 v[50:53], v[168:171], v[176:179], v[50:53]
	v_mfma_f32_16x16x32_bf16 v[38:41], v[160:163], v[184:187], v[38:41]
	v_mfma_f32_16x16x32_bf16 v[34:37], v[168:171], v[184:187], v[34:37]
	v_mfma_f32_16x16x32_bf16 v[22:25], v[160:163], v[192:195], v[22:25]
	v_mfma_f32_16x16x32_bf16 v[18:21], v[168:171], v[192:195], v[18:21]
	v_mfma_f32_16x16x32_bf16 v[6:9], v[160:163], v[200:203], v[6:9]
	v_mfma_f32_16x16x32_bf16 v[2:5], v[168:171], v[200:203], v[2:5]
	s_setprio 0
	s_barrier
	s_add_i32 s67, 0, 0x18000
	v_add_u32_e32 v0, s67, v126
	s_add_i32 s70, 0, 0x1c000
	ds_read_b128 v[128:131], v0
	ds_read_b128 v[142:145], v0 offset:1024
	ds_read_b128 v[146:149], v0 offset:2048
	ds_read_b128 v[150:153], v0 offset:3072
	v_add_u32_e32 v0, s70, v126
	ds_read_b128 v[154:157], v0
	ds_read_b128 v[160:163], v0 offset:1024
	ds_read_b128 v[164:167], v0 offset:2048
	ds_read_b128 v[168:171], v0 offset:3072
	s_add_u32 s68, s16, 0x40000
	v_mov_b32_e32 v0, v122
	s_mov_b32 m0, s47
	ds_read_b128 v[172:175], v127 offset:32768
	ds_read_b128 v[176:179], v127 offset:33792
	ds_read_b128 v[180:183], v127 offset:34816
	ds_read_b128 v[184:187], v127 offset:35840
	ds_read_b128 v[188:191], v127 offset:36864
	ds_read_b128 v[192:195], v127 offset:37888
	ds_read_b128 v[196:199], v127 offset:38912
	ds_read_b128 v[200:203], v127 offset:39936
	s_addc_u32 s69, s17, 0
	s_nop 0
	global_load_lds_dwordx4 v0, s[68:69]
	v_mov_b32_e32 v0, v123
	s_mov_b32 m0, s48
	s_nop 0
	global_load_lds_dwordx4 v0, s[68:69]
	s_waitcnt vmcnt(8)
	s_waitcnt lgkmcnt(0)
	s_barrier
	s_setprio 1
	s_waitcnt lgkmcnt(0)
	v_mfma_f32_16x16x32_bf16 v[136:139], v[128:131], v[172:175], v[138:141]
	v_mfma_f32_16x16x32_bf16 v[132:135], v[146:149], v[172:175], v[132:135]
	v_mfma_f32_16x16x32_bf16 v[110:113], v[128:131], v[180:183], v[110:113]
	v_mfma_f32_16x16x32_bf16 v[106:109], v[146:149], v[180:183], v[106:109]
	v_mfma_f32_16x16x32_bf16 v[94:97], v[128:131], v[188:191], v[94:97]
	v_mfma_f32_16x16x32_bf16 v[90:93], v[146:149], v[188:191], v[90:93]
	v_mfma_f32_16x16x32_bf16 v[78:81], v[128:131], v[196:199], v[78:81]
	v_mfma_f32_16x16x32_bf16 v[74:77], v[146:149], v[196:199], v[74:77]
	v_mfma_f32_16x16x32_bf16 v[138:141], v[142:145], v[176:179], v[136:139]
	v_mfma_f32_16x16x32_bf16 v[134:137], v[150:153], v[176:179], v[132:135]
	v_mfma_f32_16x16x32_bf16 v[110:113], v[142:145], v[184:187], v[110:113]
	v_mfma_f32_16x16x32_bf16 v[106:109], v[150:153], v[184:187], v[106:109]
	v_mfma_f32_16x16x32_bf16 v[94:97], v[142:145], v[192:195], v[94:97]
	v_mfma_f32_16x16x32_bf16 v[90:93], v[150:153], v[192:195], v[90:93]
	v_mfma_f32_16x16x32_bf16 v[78:81], v[142:145], v[200:203], v[78:81]
	v_mfma_f32_16x16x32_bf16 v[74:77], v[150:153], v[200:203], v[74:77]
	s_setprio 0
	s_setprio 1
	v_mfma_f32_16x16x32_bf16 v[118:121], v[154:157], v[172:175], v[118:121]
	v_mfma_f32_16x16x32_bf16 v[114:117], v[164:167], v[172:175], v[114:117]
	v_mfma_f32_16x16x32_bf16 v[102:105], v[154:157], v[180:183], v[102:105]
	v_mfma_f32_16x16x32_bf16 v[98:101], v[164:167], v[180:183], v[98:101]
	v_mfma_f32_16x16x32_bf16 v[86:89], v[154:157], v[188:191], v[86:89]
	v_mfma_f32_16x16x32_bf16 v[82:85], v[164:167], v[188:191], v[82:85]
	v_mfma_f32_16x16x32_bf16 v[70:73], v[154:157], v[196:199], v[70:73]
	v_mfma_f32_16x16x32_bf16 v[66:69], v[164:167], v[196:199], v[66:69]
	v_mfma_f32_16x16x32_bf16 v[118:121], v[160:163], v[176:179], v[118:121]
	v_mfma_f32_16x16x32_bf16 v[114:117], v[168:171], v[176:179], v[114:117]
	v_mfma_f32_16x16x32_bf16 v[102:105], v[160:163], v[184:187], v[102:105]
	v_mfma_f32_16x16x32_bf16 v[98:101], v[168:171], v[184:187], v[98:101]
	v_mfma_f32_16x16x32_bf16 v[86:89], v[160:163], v[192:195], v[86:89]
	v_mfma_f32_16x16x32_bf16 v[82:85], v[168:171], v[192:195], v[82:85]
	v_mfma_f32_16x16x32_bf16 v[70:73], v[160:163], v[200:203], v[70:73]
	v_mfma_f32_16x16x32_bf16 v[66:69], v[168:171], v[200:203], v[66:69]
	s_setprio 0
	s_barrier
	v_mov_b32_e32 v0, v124
	ds_read_b128 v[172:175], v127 offset:49152
	ds_read_b128 v[176:179], v127 offset:50176
	ds_read_b128 v[180:183], v127 offset:51200
	ds_read_b128 v[184:187], v127 offset:52224
	ds_read_b128 v[188:191], v127 offset:53248
	ds_read_b128 v[192:195], v127 offset:54272
	ds_read_b128 v[196:199], v127 offset:55296
	ds_read_b128 v[200:203], v127 offset:56320
	s_add_i32 s67, s67, s42
	s_add_u32 s100, s22, s38
	s_addc_u32 s101, s23, s39
	s_mov_b32 m0, s67
	v_mov_b32_e32 v0, v125
	global_load_lds_dwordx4 v124, s[100:101]
	s_add_i32 m0, s67, 0x2000
	s_nop 0
	s_add_u32 s22, s22, 0x40080
	s_addc_u32 s23, s23, 0
	v_mov_b32_e32 v0, v124
	s_add_i32 s67, s70, s42
	global_load_lds_dwordx4 v125, s[100:101]
	s_mov_b32 m0, s67
	s_nop 0
	global_load_lds_dwordx4 v0, s[22:23]
	v_mov_b32_e32 v0, v125
	s_add_i32 m0, s67, 0x2000
	s_nop 0
	global_load_lds_dwordx4 v0, s[22:23]
	v_mov_b32_e32 v0, v122
	s_mov_b32 m0, s64
	s_add_u32 s100, s16, s38
	s_addc_u32 s101, s17, s39
	v_mov_b32_e32 v0, v123
	global_load_lds_dwordx4 v122, s[100:101]
	s_mov_b32 m0, s65
	s_nop 0
	global_load_lds_dwordx4 v123, s[100:101]
	s_waitcnt vmcnt(8)
	s_waitcnt lgkmcnt(0)
	s_barrier
	s_setprio 1
	s_waitcnt lgkmcnt(0)
	v_mfma_f32_16x16x32_bf16 v[62:65], v[128:131], v[172:175], v[62:65]
	v_mfma_f32_16x16x32_bf16 v[58:61], v[146:149], v[172:175], v[58:61]
	v_mfma_f32_16x16x32_bf16 v[46:49], v[128:131], v[180:183], v[46:49]
	v_mfma_f32_16x16x32_bf16 v[42:45], v[146:149], v[180:183], v[42:45]
	v_mfma_f32_16x16x32_bf16 v[30:33], v[128:131], v[188:191], v[30:33]
	v_mfma_f32_16x16x32_bf16 v[26:29], v[146:149], v[188:191], v[26:29]
	v_mfma_f32_16x16x32_bf16 v[14:17], v[128:131], v[196:199], v[14:17]
	v_mfma_f32_16x16x32_bf16 v[10:13], v[146:149], v[196:199], v[10:13]
	v_mfma_f32_16x16x32_bf16 v[62:65], v[142:145], v[176:179], v[62:65]
	v_mfma_f32_16x16x32_bf16 v[58:61], v[150:153], v[176:179], v[58:61]
	v_mfma_f32_16x16x32_bf16 v[46:49], v[142:145], v[184:187], v[46:49]
	v_mfma_f32_16x16x32_bf16 v[42:45], v[150:153], v[184:187], v[42:45]
	v_mfma_f32_16x16x32_bf16 v[30:33], v[142:145], v[192:195], v[30:33]
	v_mfma_f32_16x16x32_bf16 v[26:29], v[150:153], v[192:195], v[26:29]
	v_mfma_f32_16x16x32_bf16 v[14:17], v[142:145], v[200:203], v[14:17]
	v_mfma_f32_16x16x32_bf16 v[10:13], v[150:153], v[200:203], v[10:13]
	s_setprio 0
	s_setprio 1
	v_mfma_f32_16x16x32_bf16 v[54:57], v[154:157], v[172:175], v[54:57]
	v_mfma_f32_16x16x32_bf16 v[50:53], v[164:167], v[172:175], v[50:53]
	v_mfma_f32_16x16x32_bf16 v[38:41], v[154:157], v[180:183], v[38:41]
	v_mfma_f32_16x16x32_bf16 v[34:37], v[164:167], v[180:183], v[34:37]
	v_mfma_f32_16x16x32_bf16 v[22:25], v[154:157], v[188:191], v[22:25]
	v_mfma_f32_16x16x32_bf16 v[18:21], v[164:167], v[188:191], v[18:21]
	v_mfma_f32_16x16x32_bf16 v[6:9], v[154:157], v[196:199], v[6:9]
	v_mfma_f32_16x16x32_bf16 v[2:5], v[164:167], v[196:199], v[2:5]
	v_mfma_f32_16x16x32_bf16 v[54:57], v[160:163], v[176:179], v[54:57]
	v_mfma_f32_16x16x32_bf16 v[50:53], v[168:171], v[176:179], v[50:53]
	v_mfma_f32_16x16x32_bf16 v[38:41], v[160:163], v[184:187], v[38:41]
	v_mfma_f32_16x16x32_bf16 v[34:37], v[168:171], v[184:187], v[34:37]
	v_mfma_f32_16x16x32_bf16 v[22:25], v[160:163], v[192:195], v[22:25]
	v_mfma_f32_16x16x32_bf16 v[18:21], v[168:171], v[192:195], v[18:21]
	v_mfma_f32_16x16x32_bf16 v[6:9], v[160:163], v[200:203], v[6:9]
	v_mfma_f32_16x16x32_bf16 v[2:5], v[168:171], v[200:203], v[2:5]
	s_setprio 0
	s_barrier
	s_add_i32 s66, s66, 2
	s_add_u32 s14, s14, 0x100
	s_addc_u32 s15, s15, 0
	s_cmp_gt_u32 s66, 13
	s_cbranch_scc0 .LBB0_1807
	s_cmpk_lt_u32 s26, 0x100
	s_cbranch_scc0 .LBB0_1810
	s_barrier

.LBB0_1886:
	s_add_u32 s6, s4, 0xfffc0080
	s_addc_u32 s7, s5, -1
	s_add_i32 s47, 0, 0x10000
	s_cmp_eq_u32 s46, 12
	s_cselect_b32 s7, s3, s7
	s_cselect_b32 s6, s2, s6
	v_add_u32_e32 v0, s47, v127
	s_cselect_b32 s11, s40, s43
	s_cselect_b32 s10, s26, s37
	s_add_i32 s50, 0, 0x14000
	ds_read_b128 v[130:133], v0
	ds_read_b128 v[134:137], v0 offset:1024
	ds_read_b128 v[138:141], v0 offset:2048
	ds_read_b128 v[142:145], v0 offset:3072
	v_add_u32_e32 v0, s50, v127
	ds_read_b128 v[146:149], v0
	ds_read_b128 v[158:161], v0 offset:1024
	ds_read_b128 v[162:165], v0 offset:2048
	ds_read_b128 v[166:169], v0 offset:3072
	v_mov_b32_e32 v0, v122
	ds_read_b128 v[170:173], v128
	ds_read_b128 v[174:177], v128 offset:1024
	ds_read_b128 v[178:181], v128 offset:2048
	ds_read_b128 v[182:185], v128 offset:3072
	ds_read_b128 v[186:189], v128 offset:4096
	ds_read_b128 v[190:193], v128 offset:5120
	ds_read_b128 v[194:197], v128 offset:6144
	ds_read_b128 v[198:201], v128 offset:7168
	s_add_i32 m0, s17, 0xc000
	s_nop 0
	global_load_lds_dwordx4 v0, s[4:5]
	v_mov_b32_e32 v0, v123
	s_add_i32 m0, s17, 0xe000
	s_nop 0
	global_load_lds_dwordx4 v0, s[4:5]
	s_waitcnt vmcnt(8)
	s_waitcnt lgkmcnt(0)
	s_barrier
	s_setprio 1
	s_waitcnt lgkmcnt(0)
	v_mfma_f32_16x16x32_bf16 v[154:157], v[130:133], v[170:173], v[154:157]
	v_mfma_f32_16x16x32_bf16 v[150:153], v[138:141], v[170:173], v[150:153]
	v_mfma_f32_16x16x32_bf16 v[110:113], v[130:133], v[178:181], v[110:113]
	v_mfma_f32_16x16x32_bf16 v[106:109], v[138:141], v[178:181], v[106:109]
	v_mfma_f32_16x16x32_bf16 v[94:97], v[130:133], v[186:189], v[94:97]
	v_mfma_f32_16x16x32_bf16 v[90:93], v[138:141], v[186:189], v[90:93]
	v_mfma_f32_16x16x32_bf16 v[78:81], v[130:133], v[194:197], v[78:81]
	v_mfma_f32_16x16x32_bf16 v[74:77], v[138:141], v[194:197], v[74:77]
	v_mfma_f32_16x16x32_bf16 v[154:157], v[134:137], v[174:177], v[154:157]
	v_mfma_f32_16x16x32_bf16 v[150:153], v[142:145], v[174:177], v[150:153]
	v_mfma_f32_16x16x32_bf16 v[110:113], v[134:137], v[182:185], v[110:113]
	v_mfma_f32_16x16x32_bf16 v[106:109], v[142:145], v[182:185], v[106:109]
	v_mfma_f32_16x16x32_bf16 v[94:97], v[134:137], v[190:193], v[94:97]
	v_mfma_f32_16x16x32_bf16 v[90:93], v[142:145], v[190:193], v[90:93]
	v_mfma_f32_16x16x32_bf16 v[78:81], v[134:137], v[198:201], v[78:81]
	v_mfma_f32_16x16x32_bf16 v[74:77], v[142:145], v[198:201], v[74:77]
	s_setprio 0
	s_setprio 1
	v_mfma_f32_16x16x32_bf16 v[118:121], v[146:149], v[170:173], v[118:121]
	v_mfma_f32_16x16x32_bf16 v[114:117], v[162:165], v[170:173], v[114:117]
	v_mfma_f32_16x16x32_bf16 v[102:105], v[146:149], v[178:181], v[102:105]
	v_mfma_f32_16x16x32_bf16 v[98:101], v[162:165], v[178:181], v[98:101]
	v_mfma_f32_16x16x32_bf16 v[86:89], v[146:149], v[186:189], v[86:89]
	v_mfma_f32_16x16x32_bf16 v[82:85], v[162:165], v[186:189], v[82:85]
	v_mfma_f32_16x16x32_bf16 v[70:73], v[146:149], v[194:197], v[70:73]
	v_mfma_f32_16x16x32_bf16 v[66:69], v[162:165], v[194:197], v[66:69]
	v_mfma_f32_16x16x32_bf16 v[118:121], v[158:161], v[174:177], v[118:121]
	v_mfma_f32_16x16x32_bf16 v[114:117], v[166:169], v[174:177], v[114:117]
	v_mfma_f32_16x16x32_bf16 v[102:105], v[158:161], v[182:185], v[102:105]
	v_mfma_f32_16x16x32_bf16 v[98:101], v[166:169], v[182:185], v[98:101]
	v_mfma_f32_16x16x32_bf16 v[86:89], v[158:161], v[190:193], v[86:89]
	v_mfma_f32_16x16x32_bf16 v[82:85], v[166:169], v[190:193], v[82:85]
	v_mfma_f32_16x16x32_bf16 v[70:73], v[158:161], v[198:201], v[70:73]
	v_mfma_f32_16x16x32_bf16 v[66:69], v[166:169], v[198:201], v[66:69]
	s_setprio 0
	s_barrier
	v_mov_b32_e32 v0, v125
	s_add_i32 s47, s47, s16
	ds_read_b128 v[170:173], v128 offset:16384
	ds_read_b128 v[174:177], v128 offset:17408
	ds_read_b128 v[178:181], v128 offset:18432
	ds_read_b128 v[182:185], v128 offset:19456
	ds_read_b128 v[186:189], v128 offset:20480
	ds_read_b128 v[190:193], v128 offset:21504
	ds_read_b128 v[194:197], v128 offset:22528
	ds_read_b128 v[198:201], v128 offset:23552
	s_mov_b32 m0, s47
	s_nop 0
	global_load_lds_dwordx4 v0, s[10:11]
	v_mov_b32_e32 v0, v126
	s_add_i32 m0, s47, 0x2000
	s_add_u32 s48, s10, 0x40000
	global_load_lds_dwordx4 v0, s[10:11]
	s_addc_u32 s49, s11, 0
	v_mov_b32_e32 v0, v125
	s_add_i32 s47, s50, s16
	s_mov_b32 m0, s47
	s_nop 0
	global_load_lds_dwordx4 v0, s[48:49]
	v_mov_b32_e32 v0, v126
	s_add_i32 m0, s47, 0x2000
	s_nop 0
	global_load_lds_dwordx4 v0, s[48:49]
	v_mov_b32_e32 v0, v122
	s_mov_b32 m0, s17
	s_nop 0
	global_load_lds_dwordx4 v0, s[6:7]
	v_mov_b32_e32 v0, v123
	s_mov_b32 m0, s22
	s_nop 0
	global_load_lds_dwordx4 v0, s[6:7]
	s_waitcnt vmcnt(8)
	s_waitcnt lgkmcnt(0)
	s_barrier
	s_setprio 1
	s_waitcnt lgkmcnt(0)
	v_mfma_f32_16x16x32_bf16 v[62:65], v[130:133], v[170:173], v[62:65]
	v_mfma_f32_16x16x32_bf16 v[58:61], v[138:141], v[170:173], v[58:61]
	v_mfma_f32_16x16x32_bf16 v[46:49], v[130:133], v[178:181], v[46:49]
	v_mfma_f32_16x16x32_bf16 v[42:45], v[138:141], v[178:181], v[42:45]
	v_mfma_f32_16x16x32_bf16 v[30:33], v[130:133], v[186:189], v[30:33]
	v_mfma_f32_16x16x32_bf16 v[26:29], v[138:141], v[186:189], v[26:29]
	v_mfma_f32_16x16x32_bf16 v[14:17], v[130:133], v[194:197], v[14:17]
	v_mfma_f32_16x16x32_bf16 v[10:13], v[138:141], v[194:197], v[10:13]
	v_mfma_f32_16x16x32_bf16 v[62:65], v[134:137], v[174:177], v[62:65]
	v_mfma_f32_16x16x32_bf16 v[58:61], v[142:145], v[174:177], v[58:61]
	v_mfma_f32_16x16x32_bf16 v[46:49], v[134:137], v[182:185], v[46:49]
	v_mfma_f32_16x16x32_bf16 v[42:45], v[142:145], v[182:185], v[42:45]
	v_mfma_f32_16x16x32_bf16 v[30:33], v[134:137], v[190:193], v[30:33]
	v_mfma_f32_16x16x32_bf16 v[26:29], v[142:145], v[190:193], v[26:29]
	v_mfma_f32_16x16x32_bf16 v[14:17], v[134:137], v[198:201], v[14:17]
	v_mfma_f32_16x16x32_bf16 v[10:13], v[142:145], v[198:201], v[10:13]
	s_setprio 0
	s_setprio 1
	v_mfma_f32_16x16x32_bf16 v[54:57], v[146:149], v[170:173], v[54:57]
	v_mfma_f32_16x16x32_bf16 v[50:53], v[162:165], v[170:173], v[50:53]
	v_mfma_f32_16x16x32_bf16 v[38:41], v[146:149], v[178:181], v[38:41]
	v_mfma_f32_16x16x32_bf16 v[34:37], v[162:165], v[178:181], v[34:37]
	v_mfma_f32_16x16x32_bf16 v[22:25], v[146:149], v[186:189], v[22:25]
	v_mfma_f32_16x16x32_bf16 v[18:21], v[162:165], v[186:189], v[18:21]
	v_mfma_f32_16x16x32_bf16 v[6:9], v[146:149], v[194:197], v[6:9]
	v_mfma_f32_16x16x32_bf16 v[2:5], v[162:165], v[194:197], v[2:5]
	v_mfma_f32_16x16x32_bf16 v[54:57], v[158:161], v[174:177], v[54:57]
	v_mfma_f32_16x16x32_bf16 v[50:53], v[166:169], v[174:177], v[50:53]
	v_mfma_f32_16x16x32_bf16 v[38:41], v[158:161], v[182:185], v[38:41]
	v_mfma_f32_16x16x32_bf16 v[34:37], v[166:169], v[182:185], v[34:37]
	v_mfma_f32_16x16x32_bf16 v[22:25], v[158:161], v[190:193], v[22:25]
	v_mfma_f32_16x16x32_bf16 v[18:21], v[166:169], v[190:193], v[18:21]
	v_mfma_f32_16x16x32_bf16 v[6:9], v[158:161], v[198:201], v[6:9]
	v_mfma_f32_16x16x32_bf16 v[2:5], v[166:169], v[198:201], v[2:5]
	s_setprio 0
	s_barrier
	s_add_i32 s47, 0, 0x18000
	v_add_u32_e32 v0, s47, v127
	s_add_i32 s50, 0, 0x1c000
	ds_read_b128 v[130:133], v0
	ds_read_b128 v[134:137], v0 offset:1024
	ds_read_b128 v[138:141], v0 offset:2048
	ds_read_b128 v[142:145], v0 offset:3072
	v_add_u32_e32 v0, s50, v127
	ds_read_b128 v[146:149], v0
	ds_read_b128 v[158:161], v0 offset:1024
	ds_read_b128 v[162:165], v0 offset:2048
	ds_read_b128 v[166:169], v0 offset:3072
	s_add_u32 s48, s6, 0x40000
	v_mov_b32_e32 v0, v122
	s_mov_b32 m0, s23
	ds_read_b128 v[170:173], v128 offset:32768
	ds_read_b128 v[174:177], v128 offset:33792
	ds_read_b128 v[178:181], v128 offset:34816
	ds_read_b128 v[182:185], v128 offset:35840
	ds_read_b128 v[186:189], v128 offset:36864
	ds_read_b128 v[190:193], v128 offset:37888
	ds_read_b128 v[194:197], v128 offset:38912
	ds_read_b128 v[198:201], v128 offset:39936
	s_addc_u32 s49, s7, 0
	s_nop 0
	global_load_lds_dwordx4 v0, s[48:49]
	v_mov_b32_e32 v0, v123
	s_mov_b32 m0, s24
	s_nop 0
	global_load_lds_dwordx4 v0, s[48:49]
	s_waitcnt vmcnt(8)
	s_waitcnt lgkmcnt(0)
	s_barrier
	s_setprio 1
	s_waitcnt lgkmcnt(0)
	v_mfma_f32_16x16x32_bf16 v[154:157], v[130:133], v[170:173], v[154:157]
	v_mfma_f32_16x16x32_bf16 v[150:153], v[138:141], v[170:173], v[150:153]
	v_mfma_f32_16x16x32_bf16 v[110:113], v[130:133], v[178:181], v[110:113]
	v_mfma_f32_16x16x32_bf16 v[106:109], v[138:141], v[178:181], v[106:109]
	v_mfma_f32_16x16x32_bf16 v[94:97], v[130:133], v[186:189], v[94:97]
	v_mfma_f32_16x16x32_bf16 v[90:93], v[138:141], v[186:189], v[90:93]
	v_mfma_f32_16x16x32_bf16 v[78:81], v[130:133], v[194:197], v[78:81]
	v_mfma_f32_16x16x32_bf16 v[74:77], v[138:141], v[194:197], v[74:77]
	v_mfma_f32_16x16x32_bf16 v[154:157], v[134:137], v[174:177], v[154:157]
	v_mfma_f32_16x16x32_bf16 v[150:153], v[142:145], v[174:177], v[150:153]
	v_mfma_f32_16x16x32_bf16 v[110:113], v[134:137], v[182:185], v[110:113]
	v_mfma_f32_16x16x32_bf16 v[106:109], v[142:145], v[182:185], v[106:109]
	v_mfma_f32_16x16x32_bf16 v[94:97], v[134:137], v[190:193], v[94:97]
	v_mfma_f32_16x16x32_bf16 v[90:93], v[142:145], v[190:193], v[90:93]
	v_mfma_f32_16x16x32_bf16 v[78:81], v[134:137], v[198:201], v[78:81]
	v_mfma_f32_16x16x32_bf16 v[74:77], v[142:145], v[198:201], v[74:77]
	s_setprio 0
	s_setprio 1
	v_mfma_f32_16x16x32_bf16 v[118:121], v[146:149], v[170:173], v[118:121]
	v_mfma_f32_16x16x32_bf16 v[114:117], v[162:165], v[170:173], v[114:117]
	v_mfma_f32_16x16x32_bf16 v[102:105], v[146:149], v[178:181], v[102:105]
	v_mfma_f32_16x16x32_bf16 v[98:101], v[162:165], v[178:181], v[98:101]
	v_mfma_f32_16x16x32_bf16 v[86:89], v[146:149], v[186:189], v[86:89]
	v_mfma_f32_16x16x32_bf16 v[82:85], v[162:165], v[186:189], v[82:85]
	v_mfma_f32_16x16x32_bf16 v[70:73], v[146:149], v[194:197], v[70:73]
	v_mfma_f32_16x16x32_bf16 v[66:69], v[162:165], v[194:197], v[66:69]
	v_mfma_f32_16x16x32_bf16 v[118:121], v[158:161], v[174:177], v[118:121]
	v_mfma_f32_16x16x32_bf16 v[114:117], v[166:169], v[174:177], v[114:117]
	v_mfma_f32_16x16x32_bf16 v[102:105], v[158:161], v[182:185], v[102:105]
	v_mfma_f32_16x16x32_bf16 v[98:101], v[166:169], v[182:185], v[98:101]
	v_mfma_f32_16x16x32_bf16 v[86:89], v[158:161], v[190:193], v[86:89]
	v_mfma_f32_16x16x32_bf16 v[82:85], v[166:169], v[190:193], v[82:85]
	v_mfma_f32_16x16x32_bf16 v[70:73], v[158:161], v[198:201], v[70:73]
	v_mfma_f32_16x16x32_bf16 v[66:69], v[166:169], v[198:201], v[66:69]
	s_setprio 0
	s_barrier
	v_mov_b32_e32 v0, v125
	ds_read_b128 v[170:173], v128 offset:49152
	ds_read_b128 v[174:177], v128 offset:50176
	ds_read_b128 v[178:181], v128 offset:51200
	ds_read_b128 v[182:185], v128 offset:52224
	ds_read_b128 v[186:189], v128 offset:53248
	ds_read_b128 v[190:193], v128 offset:54272
	ds_read_b128 v[194:197], v128 offset:55296
	ds_read_b128 v[198:201], v128 offset:56320
	s_add_i32 s47, s47, s16
	s_add_u32 s100, s10, s38
	s_addc_u32 s101, s11, s39
	s_mov_b32 m0, s47
	v_mov_b32_e32 v0, v126
	global_load_lds_dwordx4 v125, s[100:101]
	s_add_i32 m0, s47, 0x2000
	s_nop 0
	s_add_u32 s10, s10, 0x40080
	s_addc_u32 s11, s11, 0
	v_mov_b32_e32 v0, v125
	s_add_i32 s47, s50, s16
	global_load_lds_dwordx4 v126, s[100:101]
	s_mov_b32 m0, s47
	s_nop 0
	global_load_lds_dwordx4 v0, s[10:11]
	v_mov_b32_e32 v0, v126
	s_add_i32 m0, s47, 0x2000
	s_nop 0
	global_load_lds_dwordx4 v0, s[10:11]
	v_mov_b32_e32 v0, v122
	s_mov_b32 m0, s41
	s_add_u32 s100, s6, s38
	s_addc_u32 s101, s7, s39
	v_mov_b32_e32 v0, v123
	global_load_lds_dwordx4 v122, s[100:101]
	s_mov_b32 m0, s42
	s_nop 0
	global_load_lds_dwordx4 v123, s[100:101]
	s_waitcnt vmcnt(8)
	s_waitcnt lgkmcnt(0)
	s_barrier
	s_setprio 1
	s_waitcnt lgkmcnt(0)
	v_mfma_f32_16x16x32_bf16 v[62:65], v[130:133], v[170:173], v[62:65]
	v_mfma_f32_16x16x32_bf16 v[58:61], v[138:141], v[170:173], v[58:61]
	v_mfma_f32_16x16x32_bf16 v[46:49], v[130:133], v[178:181], v[46:49]
	v_mfma_f32_16x16x32_bf16 v[42:45], v[138:141], v[178:181], v[42:45]
	v_mfma_f32_16x16x32_bf16 v[30:33], v[130:133], v[186:189], v[30:33]
	v_mfma_f32_16x16x32_bf16 v[26:29], v[138:141], v[186:189], v[26:29]
	v_mfma_f32_16x16x32_bf16 v[14:17], v[130:133], v[194:197], v[14:17]
	v_mfma_f32_16x16x32_bf16 v[10:13], v[138:141], v[194:197], v[10:13]
	v_mfma_f32_16x16x32_bf16 v[62:65], v[134:137], v[174:177], v[62:65]
	v_mfma_f32_16x16x32_bf16 v[58:61], v[142:145], v[174:177], v[58:61]
	v_mfma_f32_16x16x32_bf16 v[46:49], v[134:137], v[182:185], v[46:49]
	v_mfma_f32_16x16x32_bf16 v[42:45], v[142:145], v[182:185], v[42:45]
	v_mfma_f32_16x16x32_bf16 v[30:33], v[134:137], v[190:193], v[30:33]
	v_mfma_f32_16x16x32_bf16 v[26:29], v[142:145], v[190:193], v[26:29]
	v_mfma_f32_16x16x32_bf16 v[14:17], v[134:137], v[198:201], v[14:17]
	v_mfma_f32_16x16x32_bf16 v[10:13], v[142:145], v[198:201], v[10:13]
	s_setprio 0
	s_setprio 1
	v_mfma_f32_16x16x32_bf16 v[54:57], v[146:149], v[170:173], v[54:57]
	v_mfma_f32_16x16x32_bf16 v[50:53], v[162:165], v[170:173], v[50:53]
	v_mfma_f32_16x16x32_bf16 v[38:41], v[146:149], v[178:181], v[38:41]
	v_mfma_f32_16x16x32_bf16 v[34:37], v[162:165], v[178:181], v[34:37]
	v_mfma_f32_16x16x32_bf16 v[22:25], v[146:149], v[186:189], v[22:25]
	v_mfma_f32_16x16x32_bf16 v[18:21], v[162:165], v[186:189], v[18:21]
	v_mfma_f32_16x16x32_bf16 v[6:9], v[146:149], v[194:197], v[6:9]
	v_mfma_f32_16x16x32_bf16 v[2:5], v[162:165], v[194:197], v[2:5]
	v_mfma_f32_16x16x32_bf16 v[54:57], v[158:161], v[174:177], v[54:57]
	v_mfma_f32_16x16x32_bf16 v[50:53], v[166:169], v[174:177], v[50:53]
	v_mfma_f32_16x16x32_bf16 v[38:41], v[158:161], v[182:185], v[38:41]
	v_mfma_f32_16x16x32_bf16 v[34:37], v[166:169], v[182:185], v[34:37]
	v_mfma_f32_16x16x32_bf16 v[22:25], v[158:161], v[190:193], v[22:25]
	v_mfma_f32_16x16x32_bf16 v[18:21], v[166:169], v[190:193], v[18:21]
	v_mfma_f32_16x16x32_bf16 v[6:9], v[158:161], v[198:201], v[6:9]
	v_mfma_f32_16x16x32_bf16 v[2:5], v[166:169], v[198:201], v[2:5]
	s_setprio 0
	s_barrier
	s_add_i32 s46, s46, 2
	s_add_u32 s4, s4, 0x100
	s_addc_u32 s5, s5, 0
	s_add_u32 s37, s37, 0x100
	s_addc_u32 s43, s43, 0
	s_cmp_gt_u32 s46, 13
	s_cbranch_scc0 .LBB0_1886
	s_cmpk_lt_u32 s14, 0x100
	s_cbranch_scc0 .LBB0_1889
	s_barrier
